# GEMM K-loops: loop-carried SALU updates and exit compare moved above the loop-back barrier (back-edge rotation), 11 loops
# baseline (speedup 1.0000x reference)
.LBB0_631:
	v_add_u32_e32 v132, s80, v202
	ds_read_b128 v[128:131], v132
	ds_read_b128 v[160:163], v132 offset:1024
	ds_read_b128 v[164:167], v132 offset:2048
	ds_read_b128 v[168:171], v132 offset:3072
	v_add_u32_e32 v132, s81, v202
	ds_read_b128 v[172:175], v132
	ds_read_b128 v[176:179], v132 offset:1024
	ds_read_b128 v[180:183], v132 offset:2048
	ds_read_b128 v[184:187], v132 offset:3072
	s_add_i32 s88, s56, 2
	s_add_u32 s57, s8, 0xfff80080
	s_addc_u32 s58, s9, -1
	s_cmp_eq_u32 s78, s56
	s_cselect_b32 s56, s62, s63
	s_cselect_b32 s59, s29, s58
	s_cselect_b32 s58, s47, s57
	s_cselect_b32 s57, s61, s87
	v_lshl_add_u64 v[132:133], s[8:9], 0, v[152:153]
	s_add_i32 m0, s33, 0xc000
	ds_read_b128 v[188:191], v203
	ds_read_b128 v[192:195], v203 offset:1024
	ds_read_b128 v[196:199], v203 offset:2048
	ds_read_b128 v[206:209], v203 offset:3072
	ds_read_b128 v[210:213], v203 offset:4096
	ds_read_b128 v[214:217], v203 offset:5120
	ds_read_b128 v[218:221], v203 offset:6144
	ds_read_b128 v[222:225], v203 offset:7168
	global_load_lds_dwordx4 v[132:133], off
	v_lshl_add_u64 v[132:133], s[8:9], 0, v[154:155]
	s_add_i32 m0, s33, 0xe000
	s_nop 0
	global_load_lds_dwordx4 v[132:133], off
	s_waitcnt vmcnt(8)
	s_waitcnt lgkmcnt(0)
	s_barrier
	s_setprio 1
	s_waitcnt lgkmcnt(0)
	v_mfma_i32_16x16x64_i8 v[124:127], v[128:131], v[188:191], v[124:127]
	v_mfma_i32_16x16x64_i8 v[92:95], v[164:167], v[188:191], v[92:95]
	v_mfma_i32_16x16x64_i8 v[120:123], v[128:131], v[196:199], v[120:123]
	v_mfma_i32_16x16x64_i8 v[88:91], v[164:167], v[196:199], v[88:91]
	v_mfma_i32_16x16x64_i8 v[116:119], v[128:131], v[210:213], v[116:119]
	v_mfma_i32_16x16x64_i8 v[84:87], v[164:167], v[210:213], v[84:87]
	v_mfma_i32_16x16x64_i8 v[112:115], v[128:131], v[218:221], v[112:115]
	v_mfma_i32_16x16x64_i8 v[80:83], v[164:167], v[218:221], v[80:83]
	v_mfma_i32_16x16x64_i8 v[124:127], v[160:163], v[192:195], v[124:127]
	v_mfma_i32_16x16x64_i8 v[92:95], v[168:171], v[192:195], v[92:95]
	v_mfma_i32_16x16x64_i8 v[120:123], v[160:163], v[206:209], v[120:123]
	v_mfma_i32_16x16x64_i8 v[88:91], v[168:171], v[206:209], v[88:91]
	v_mfma_i32_16x16x64_i8 v[116:119], v[160:163], v[214:217], v[116:119]
	v_mfma_i32_16x16x64_i8 v[84:87], v[168:171], v[214:217], v[84:87]
	v_mfma_i32_16x16x64_i8 v[112:115], v[160:163], v[222:225], v[112:115]
	v_mfma_i32_16x16x64_i8 v[80:83], v[168:171], v[222:225], v[80:83]
	s_setprio 0
	s_setprio 1
	v_mfma_i32_16x16x64_i8 v[60:63], v[172:175], v[188:191], v[60:63]
	v_mfma_i32_16x16x64_i8 v[28:31], v[180:183], v[188:191], v[28:31]
	v_mfma_i32_16x16x64_i8 v[56:59], v[172:175], v[196:199], v[56:59]
	v_mfma_i32_16x16x64_i8 v[24:27], v[180:183], v[196:199], v[24:27]
	v_mfma_i32_16x16x64_i8 v[52:55], v[172:175], v[210:213], v[52:55]
	v_mfma_i32_16x16x64_i8 v[20:23], v[180:183], v[210:213], v[20:23]
	v_mfma_i32_16x16x64_i8 v[48:51], v[172:175], v[218:221], v[48:51]
	v_mfma_i32_16x16x64_i8 v[16:19], v[180:183], v[218:221], v[16:19]
	v_mfma_i32_16x16x64_i8 v[60:63], v[176:179], v[192:195], v[60:63]
	v_mfma_i32_16x16x64_i8 v[28:31], v[184:187], v[192:195], v[28:31]
	v_mfma_i32_16x16x64_i8 v[56:59], v[176:179], v[206:209], v[56:59]
	v_mfma_i32_16x16x64_i8 v[24:27], v[184:187], v[206:209], v[24:27]
	v_mfma_i32_16x16x64_i8 v[52:55], v[176:179], v[214:217], v[52:55]
	v_mfma_i32_16x16x64_i8 v[20:23], v[184:187], v[214:217], v[20:23]
	v_mfma_i32_16x16x64_i8 v[48:51], v[176:179], v[222:225], v[48:51]
	v_mfma_i32_16x16x64_i8 v[16:19], v[184:187], v[222:225], v[16:19]
	s_setprio 0
	s_barrier
	s_add_i32 s89, s80, s31
	v_lshl_add_u64 v[132:133], s[56:57], 0, v[136:137]
	s_mov_b32 m0, s89
	ds_read_b128 v[188:191], v203 offset:16384
	ds_read_b128 v[192:195], v203 offset:17408
	ds_read_b128 v[196:199], v203 offset:18432
	ds_read_b128 v[206:209], v203 offset:19456
	ds_read_b128 v[210:213], v203 offset:20480
	ds_read_b128 v[214:217], v203 offset:21504
	ds_read_b128 v[218:221], v203 offset:22528
	ds_read_b128 v[222:225], v203 offset:23552
	global_load_lds_dwordx4 v[132:133], off
	s_add_i32 m0, s89, 0x2000
	s_add_u32 s90, s56, 0x80000
	v_lshl_add_u64 v[226:227], s[56:57], 0, v[140:141]
	s_addc_u32 s91, s57, 0
	s_add_i32 s89, s81, s31
	global_load_lds_dwordx4 v[226:227], off
	v_lshl_add_u64 v[228:229], s[90:91], 0, v[136:137]
	s_mov_b32 m0, s89
	v_lshl_add_u64 v[230:231], s[58:59], 0, v[138:139]
	global_load_lds_dwordx4 v[228:229], off
	v_lshl_add_u64 v[228:229], s[90:91], 0, v[140:141]
	s_add_i32 m0, s89, 0x2000
	s_nop 0
	global_load_lds_dwordx4 v[228:229], off
	v_lshl_add_u64 v[228:229], s[58:59], 0, v[134:135]
	s_mov_b32 m0, s33
	s_nop 0
	global_load_lds_dwordx4 v[228:229], off
	s_mov_b32 m0, s34
	s_nop 0
	global_load_lds_dwordx4 v[230:231], off
	s_waitcnt vmcnt(8)
	s_waitcnt lgkmcnt(0)
	s_barrier
	s_setprio 1
	s_waitcnt lgkmcnt(0)
	v_mfma_i32_16x16x64_i8 v[108:111], v[128:131], v[188:191], v[108:111]
	v_mfma_i32_16x16x64_i8 v[76:79], v[164:167], v[188:191], v[76:79]
	v_mfma_i32_16x16x64_i8 v[104:107], v[128:131], v[196:199], v[104:107]
	v_mfma_i32_16x16x64_i8 v[72:75], v[164:167], v[196:199], v[72:75]
	v_mfma_i32_16x16x64_i8 v[100:103], v[128:131], v[210:213], v[100:103]
	v_mfma_i32_16x16x64_i8 v[68:71], v[164:167], v[210:213], v[68:71]
	v_mfma_i32_16x16x64_i8 v[96:99], v[128:131], v[218:221], v[96:99]
	v_mfma_i32_16x16x64_i8 v[64:67], v[164:167], v[218:221], v[64:67]
	v_mfma_i32_16x16x64_i8 v[108:111], v[160:163], v[192:195], v[108:111]
	v_mfma_i32_16x16x64_i8 v[76:79], v[168:171], v[192:195], v[76:79]
	v_mfma_i32_16x16x64_i8 v[104:107], v[160:163], v[206:209], v[104:107]
	v_mfma_i32_16x16x64_i8 v[72:75], v[168:171], v[206:209], v[72:75]
	v_mfma_i32_16x16x64_i8 v[100:103], v[160:163], v[214:217], v[100:103]
	v_mfma_i32_16x16x64_i8 v[68:71], v[168:171], v[214:217], v[68:71]
	v_mfma_i32_16x16x64_i8 v[96:99], v[160:163], v[222:225], v[96:99]
	v_mfma_i32_16x16x64_i8 v[64:67], v[168:171], v[222:225], v[64:67]
	s_setprio 0
	s_setprio 1
	v_mfma_i32_16x16x64_i8 v[44:47], v[172:175], v[188:191], v[44:47]
	v_mfma_i32_16x16x64_i8 v[12:15], v[180:183], v[188:191], v[12:15]
	v_mfma_i32_16x16x64_i8 v[40:43], v[172:175], v[196:199], v[40:43]
	v_mfma_i32_16x16x64_i8 v[8:11], v[180:183], v[196:199], v[8:11]
	v_mfma_i32_16x16x64_i8 v[36:39], v[172:175], v[210:213], v[36:39]
	v_mfma_i32_16x16x64_i8 v[4:7], v[180:183], v[210:213], v[4:7]
	v_mfma_i32_16x16x64_i8 v[32:35], v[172:175], v[218:221], v[32:35]
	v_mfma_i32_16x16x64_i8 v[0:3], v[180:183], v[218:221], v[0:3]
	v_mfma_i32_16x16x64_i8 v[44:47], v[176:179], v[192:195], v[44:47]
	v_mfma_i32_16x16x64_i8 v[12:15], v[184:187], v[192:195], v[12:15]
	v_mfma_i32_16x16x64_i8 v[40:43], v[176:179], v[206:209], v[40:43]
	v_mfma_i32_16x16x64_i8 v[8:11], v[184:187], v[206:209], v[8:11]
	v_mfma_i32_16x16x64_i8 v[36:39], v[176:179], v[214:217], v[36:39]
	v_mfma_i32_16x16x64_i8 v[4:7], v[184:187], v[214:217], v[4:7]
	v_mfma_i32_16x16x64_i8 v[32:35], v[176:179], v[222:225], v[32:35]
	v_mfma_i32_16x16x64_i8 v[0:3], v[184:187], v[222:225], v[0:3]
	s_setprio 0
	s_barrier
	s_add_i32 s89, 0, 0x18000
	v_add_u32_e32 v142, s89, v202
	s_add_i32 s90, 0, 0x1c000
	ds_read_b128 v[128:131], v142
	ds_read_b128 v[160:163], v142 offset:1024
	ds_read_b128 v[164:167], v142 offset:2048
	ds_read_b128 v[168:171], v142 offset:3072
	v_add_u32_e32 v142, s90, v202
	ds_read_b128 v[172:175], v142
	ds_read_b128 v[176:179], v142 offset:1024
	ds_read_b128 v[180:183], v142 offset:2048
	ds_read_b128 v[184:187], v142 offset:3072
	s_add_u32 s58, s58, 0x80000
	s_addc_u32 s59, s59, 0
	s_mov_b32 m0, s35
	v_lshl_add_u64 v[232:233], s[58:59], 0, v[134:135]
	ds_read_b128 v[188:191], v203 offset:32768
	ds_read_b128 v[192:195], v203 offset:33792
	ds_read_b128 v[196:199], v203 offset:34816
	ds_read_b128 v[206:209], v203 offset:35840
	ds_read_b128 v[210:213], v203 offset:36864
	ds_read_b128 v[214:217], v203 offset:37888
	ds_read_b128 v[218:221], v203 offset:38912
	ds_read_b128 v[222:225], v203 offset:39936
	global_load_lds_dwordx4 v[232:233], off
	v_lshl_add_u64 v[232:233], s[58:59], 0, v[138:139]
	s_mov_b32 m0, s64
	s_nop 0
	global_load_lds_dwordx4 v[232:233], off
	s_waitcnt vmcnt(8)
	s_waitcnt lgkmcnt(0)
	s_barrier
	s_setprio 1
	s_waitcnt lgkmcnt(0)
	v_mfma_i32_16x16x64_i8 v[124:127], v[128:131], v[188:191], v[124:127]
	v_mfma_i32_16x16x64_i8 v[92:95], v[164:167], v[188:191], v[92:95]
	v_mfma_i32_16x16x64_i8 v[120:123], v[128:131], v[196:199], v[120:123]
	v_mfma_i32_16x16x64_i8 v[88:91], v[164:167], v[196:199], v[88:91]
	v_mfma_i32_16x16x64_i8 v[116:119], v[128:131], v[210:213], v[116:119]
	v_mfma_i32_16x16x64_i8 v[84:87], v[164:167], v[210:213], v[84:87]
	v_mfma_i32_16x16x64_i8 v[112:115], v[128:131], v[218:221], v[112:115]
	v_mfma_i32_16x16x64_i8 v[80:83], v[164:167], v[218:221], v[80:83]
	v_mfma_i32_16x16x64_i8 v[124:127], v[160:163], v[192:195], v[124:127]
	v_mfma_i32_16x16x64_i8 v[92:95], v[168:171], v[192:195], v[92:95]
	v_mfma_i32_16x16x64_i8 v[120:123], v[160:163], v[206:209], v[120:123]
	v_mfma_i32_16x16x64_i8 v[88:91], v[168:171], v[206:209], v[88:91]
	v_mfma_i32_16x16x64_i8 v[116:119], v[160:163], v[214:217], v[116:119]
	v_mfma_i32_16x16x64_i8 v[84:87], v[168:171], v[214:217], v[84:87]
	v_mfma_i32_16x16x64_i8 v[112:115], v[160:163], v[222:225], v[112:115]
	v_mfma_i32_16x16x64_i8 v[80:83], v[168:171], v[222:225], v[80:83]
	s_setprio 0
	s_setprio 1
	v_mfma_i32_16x16x64_i8 v[60:63], v[172:175], v[188:191], v[60:63]
	v_mfma_i32_16x16x64_i8 v[28:31], v[180:183], v[188:191], v[28:31]
	v_mfma_i32_16x16x64_i8 v[56:59], v[172:175], v[196:199], v[56:59]
	v_mfma_i32_16x16x64_i8 v[24:27], v[180:183], v[196:199], v[24:27]
	v_mfma_i32_16x16x64_i8 v[52:55], v[172:175], v[210:213], v[52:55]
	v_mfma_i32_16x16x64_i8 v[20:23], v[180:183], v[210:213], v[20:23]
	v_mfma_i32_16x16x64_i8 v[48:51], v[172:175], v[218:221], v[48:51]
	v_mfma_i32_16x16x64_i8 v[16:19], v[180:183], v[218:221], v[16:19]
	v_mfma_i32_16x16x64_i8 v[60:63], v[176:179], v[192:195], v[60:63]
	v_mfma_i32_16x16x64_i8 v[28:31], v[184:187], v[192:195], v[28:31]
	v_mfma_i32_16x16x64_i8 v[56:59], v[176:179], v[206:209], v[56:59]
	v_mfma_i32_16x16x64_i8 v[24:27], v[184:187], v[206:209], v[24:27]
	v_mfma_i32_16x16x64_i8 v[52:55], v[176:179], v[214:217], v[52:55]
	v_mfma_i32_16x16x64_i8 v[20:23], v[184:187], v[214:217], v[20:23]
	v_mfma_i32_16x16x64_i8 v[48:51], v[176:179], v[222:225], v[48:51]
	v_mfma_i32_16x16x64_i8 v[16:19], v[184:187], v[222:225], v[16:19]
	s_setprio 0
	s_barrier
	s_add_i32 s58, s89, s31
	v_lshl_add_u64 v[132:133], v[132:133], 0, s[12:13]
	s_mov_b32 m0, s58
	ds_read_b128 v[188:191], v203 offset:49152
	ds_read_b128 v[192:195], v203 offset:50176
	ds_read_b128 v[196:199], v203 offset:51200
	ds_read_b128 v[206:209], v203 offset:52224
	ds_read_b128 v[210:213], v203 offset:53248
	ds_read_b128 v[214:217], v203 offset:54272
	ds_read_b128 v[218:221], v203 offset:55296
	ds_read_b128 v[222:225], v203 offset:56320
	global_load_lds_dwordx4 v[132:133], off
	s_add_i32 m0, s58, 0x2000
	s_add_u32 s56, s56, 0x80080
	v_lshl_add_u64 v[132:133], v[226:227], 0, s[12:13]
	s_addc_u32 s57, s57, 0
	s_add_i32 s58, s90, s31
	global_load_lds_dwordx4 v[132:133], off
	v_lshl_add_u64 v[132:133], s[56:57], 0, v[136:137]
	s_mov_b32 m0, s58
	s_nop 0
	global_load_lds_dwordx4 v[132:133], off
	v_lshl_add_u64 v[132:133], s[56:57], 0, v[140:141]
	s_add_i32 m0, s58, 0x2000
	s_nop 0
	global_load_lds_dwordx4 v[132:133], off
	v_lshl_add_u64 v[132:133], v[228:229], 0, s[12:13]
	s_mov_b32 m0, s76
	s_nop 0
	global_load_lds_dwordx4 v[132:133], off
	v_lshl_add_u64 v[132:133], v[230:231], 0, s[12:13]
	s_mov_b32 m0, s77
	s_nop 0
	global_load_lds_dwordx4 v[132:133], off
	s_waitcnt vmcnt(8)
	s_waitcnt lgkmcnt(0)
	s_barrier
	s_setprio 1
	s_waitcnt lgkmcnt(0)
	v_mfma_i32_16x16x64_i8 v[108:111], v[128:131], v[188:191], v[108:111]
	v_mfma_i32_16x16x64_i8 v[76:79], v[164:167], v[188:191], v[76:79]
	v_mfma_i32_16x16x64_i8 v[104:107], v[128:131], v[196:199], v[104:107]
	v_mfma_i32_16x16x64_i8 v[72:75], v[164:167], v[196:199], v[72:75]
	v_mfma_i32_16x16x64_i8 v[100:103], v[128:131], v[210:213], v[100:103]
	v_mfma_i32_16x16x64_i8 v[68:71], v[164:167], v[210:213], v[68:71]
	v_mfma_i32_16x16x64_i8 v[96:99], v[128:131], v[218:221], v[96:99]
	v_mfma_i32_16x16x64_i8 v[64:67], v[164:167], v[218:221], v[64:67]
	v_mfma_i32_16x16x64_i8 v[108:111], v[160:163], v[192:195], v[108:111]
	v_mfma_i32_16x16x64_i8 v[76:79], v[168:171], v[192:195], v[76:79]
	v_mfma_i32_16x16x64_i8 v[104:107], v[160:163], v[206:209], v[104:107]
	v_mfma_i32_16x16x64_i8 v[72:75], v[168:171], v[206:209], v[72:75]
	v_mfma_i32_16x16x64_i8 v[100:103], v[160:163], v[214:217], v[100:103]
	v_mfma_i32_16x16x64_i8 v[68:71], v[168:171], v[214:217], v[68:71]
	v_mfma_i32_16x16x64_i8 v[96:99], v[160:163], v[222:225], v[96:99]
	v_mfma_i32_16x16x64_i8 v[64:67], v[168:171], v[222:225], v[64:67]
	s_setprio 0
	s_setprio 1
	v_mfma_i32_16x16x64_i8 v[44:47], v[172:175], v[188:191], v[44:47]
	v_mfma_i32_16x16x64_i8 v[12:15], v[180:183], v[188:191], v[12:15]
	v_mfma_i32_16x16x64_i8 v[40:43], v[172:175], v[196:199], v[40:43]
	v_mfma_i32_16x16x64_i8 v[8:11], v[180:183], v[196:199], v[8:11]
	v_mfma_i32_16x16x64_i8 v[36:39], v[172:175], v[210:213], v[36:39]
	v_mfma_i32_16x16x64_i8 v[4:7], v[180:183], v[210:213], v[4:7]
	v_mfma_i32_16x16x64_i8 v[32:35], v[172:175], v[218:221], v[32:35]
	v_mfma_i32_16x16x64_i8 v[0:3], v[180:183], v[218:221], v[0:3]
	v_mfma_i32_16x16x64_i8 v[44:47], v[176:179], v[192:195], v[44:47]
	v_mfma_i32_16x16x64_i8 v[12:15], v[184:187], v[192:195], v[12:15]
	v_mfma_i32_16x16x64_i8 v[40:43], v[176:179], v[206:209], v[40:43]
	v_mfma_i32_16x16x64_i8 v[8:11], v[184:187], v[206:209], v[8:11]
	v_mfma_i32_16x16x64_i8 v[36:39], v[176:179], v[214:217], v[36:39]
	v_mfma_i32_16x16x64_i8 v[4:7], v[184:187], v[214:217], v[4:7]
	v_mfma_i32_16x16x64_i8 v[32:35], v[176:179], v[222:225], v[32:35]
	v_mfma_i32_16x16x64_i8 v[0:3], v[184:187], v[222:225], v[0:3]
	s_setprio 0
	s_add_u32 s8, s8, 0x100
	s_addc_u32 s9, s9, 0
	s_add_u32 s63, s63, 0x100
	s_addc_u32 s87, s87, 0
	s_cmp_ge_i32 s88, s18
	s_mov_b32 s56, s88
	s_barrier
	s_cbranch_scc0 .LBB0_631
	s_and_b64 vcc, exec, s[16:17]
	s_cbranch_vccz .LBB0_634

.LBB0_840:
	ds_read_b128 v[48:51], v168
	ds_read_b128 v[52:55], v168 offset:1024
	ds_read_b128 v[64:67], v168 offset:2048
	ds_read_b128 v[68:71], v168 offset:3072
	ds_read_b128 v[160:163], v169
	ds_read_b128 v[172:175], v169 offset:1024
	ds_read_b128 v[176:179], v169 offset:2048
	ds_read_b128 v[180:183], v169 offset:3072
	s_add_i32 s89, s8, 2
	s_add_u32 s9, s6, 0xfff80080
	s_addc_u32 s10, s7, -1
	s_cmp_eq_u32 s79, s8
	s_cselect_b32 s8, s86, s87
	s_cselect_b32 s11, s57, s10
	s_cselect_b32 s10, s59, s9
	s_cselect_b32 s9, s83, s88
	v_lshl_add_u64 v[164:165], s[6:7], 0, v[156:157]
	s_add_i32 m0, s33, 0xc000
	ds_read_b128 v[184:187], v170
	ds_read_b128 v[188:191], v170 offset:1024
	ds_read_b128 v[192:195], v170 offset:2048
	ds_read_b128 v[196:199], v170 offset:3072
	ds_read_b128 v[202:205], v170 offset:4096
	ds_read_b128 v[206:209], v170 offset:5120
	ds_read_b128 v[210:213], v170 offset:6144
	ds_read_b128 v[214:217], v170 offset:7168
	global_load_lds_dwordx4 v[164:165], off
	v_lshl_add_u64 v[164:165], s[6:7], 0, v[158:159]
	s_add_i32 m0, s33, 0xe000
	s_nop 0
	global_load_lds_dwordx4 v[164:165], off
	s_waitcnt vmcnt(8)
	s_waitcnt lgkmcnt(0)
	s_barrier
	s_setprio 1
	s_waitcnt lgkmcnt(0)
	v_mfma_f32_16x16x32_bf16 v[140:143], v[48:51], v[184:187], v[140:143]
	v_mfma_f32_16x16x32_bf16 v[136:139], v[64:67], v[184:187], v[136:139]
	v_mfma_f32_16x16x32_bf16 v[124:127], v[48:51], v[192:195], v[124:127]
	v_mfma_f32_16x16x32_bf16 v[120:123], v[64:67], v[192:195], v[120:123]
	v_mfma_f32_16x16x32_bf16 v[108:111], v[48:51], v[202:205], v[108:111]
	v_mfma_f32_16x16x32_bf16 v[104:107], v[64:67], v[202:205], v[104:107]
	v_mfma_f32_16x16x32_bf16 v[92:95], v[48:51], v[210:213], v[92:95]
	v_mfma_f32_16x16x32_bf16 v[88:91], v[64:67], v[210:213], v[88:91]
	v_mfma_f32_16x16x32_bf16 v[140:143], v[52:55], v[188:191], v[140:143]
	v_mfma_f32_16x16x32_bf16 v[136:139], v[68:71], v[188:191], v[136:139]
	v_mfma_f32_16x16x32_bf16 v[124:127], v[52:55], v[196:199], v[124:127]
	v_mfma_f32_16x16x32_bf16 v[120:123], v[68:71], v[196:199], v[120:123]
	v_mfma_f32_16x16x32_bf16 v[108:111], v[52:55], v[206:209], v[108:111]
	v_mfma_f32_16x16x32_bf16 v[104:107], v[68:71], v[206:209], v[104:107]
	v_mfma_f32_16x16x32_bf16 v[92:95], v[52:55], v[214:217], v[92:95]
	v_mfma_f32_16x16x32_bf16 v[88:91], v[68:71], v[214:217], v[88:91]
	s_setprio 0
	s_setprio 1
	v_mfma_f32_16x16x32_bf16 v[132:135], v[160:163], v[184:187], v[132:135]
	v_mfma_f32_16x16x32_bf16 v[128:131], v[176:179], v[184:187], v[128:131]
	v_mfma_f32_16x16x32_bf16 v[116:119], v[160:163], v[192:195], v[116:119]
	v_mfma_f32_16x16x32_bf16 v[112:115], v[176:179], v[192:195], v[112:115]
	v_mfma_f32_16x16x32_bf16 v[100:103], v[160:163], v[202:205], v[100:103]
	v_mfma_f32_16x16x32_bf16 v[96:99], v[176:179], v[202:205], v[96:99]
	v_mfma_f32_16x16x32_bf16 v[84:87], v[160:163], v[210:213], v[84:87]
	v_mfma_f32_16x16x32_bf16 v[80:83], v[176:179], v[210:213], v[80:83]
	v_mfma_f32_16x16x32_bf16 v[132:135], v[172:175], v[188:191], v[132:135]
	v_mfma_f32_16x16x32_bf16 v[128:131], v[180:183], v[188:191], v[128:131]
	v_mfma_f32_16x16x32_bf16 v[116:119], v[172:175], v[196:199], v[116:119]
	v_mfma_f32_16x16x32_bf16 v[112:115], v[180:183], v[196:199], v[112:115]
	v_mfma_f32_16x16x32_bf16 v[100:103], v[172:175], v[206:209], v[100:103]
	v_mfma_f32_16x16x32_bf16 v[96:99], v[180:183], v[206:209], v[96:99]
	v_mfma_f32_16x16x32_bf16 v[84:87], v[172:175], v[214:217], v[84:87]
	v_mfma_f32_16x16x32_bf16 v[80:83], v[180:183], v[214:217], v[80:83]
	s_setprio 0
	s_barrier
	s_add_i32 s90, s80, s31
	v_lshl_add_u64 v[164:165], s[8:9], 0, v[146:147]
	s_mov_b32 m0, s90
	ds_read_b128 v[184:187], v170 offset:16384
	ds_read_b128 v[188:191], v170 offset:17408
	ds_read_b128 v[192:195], v170 offset:18432
	ds_read_b128 v[196:199], v170 offset:19456
	ds_read_b128 v[202:205], v170 offset:20480
	ds_read_b128 v[206:209], v170 offset:21504
	ds_read_b128 v[210:213], v170 offset:22528
	ds_read_b128 v[214:217], v170 offset:23552
	global_load_lds_dwordx4 v[164:165], off
	s_add_i32 m0, s90, 0x2000
	s_add_u32 s90, s8, 0x100000
	v_lshl_add_u64 v[218:219], s[8:9], 0, v[150:151]
	s_addc_u32 s91, s9, 0
	s_add_i32 s92, s81, s31
	global_load_lds_dwordx4 v[218:219], off
	v_lshl_add_u64 v[220:221], s[90:91], 0, v[146:147]
	s_mov_b32 m0, s92
	v_lshl_add_u64 v[222:223], s[10:11], 0, v[148:149]
	global_load_lds_dwordx4 v[220:221], off
	v_lshl_add_u64 v[220:221], s[90:91], 0, v[150:151]
	s_add_i32 m0, s92, 0x2000
	s_nop 0
	global_load_lds_dwordx4 v[220:221], off
	v_lshl_add_u64 v[220:221], s[10:11], 0, v[144:145]
	s_mov_b32 m0, s33
	s_nop 0
	global_load_lds_dwordx4 v[220:221], off
	s_mov_b32 m0, s34
	s_nop 0
	global_load_lds_dwordx4 v[222:223], off
	s_waitcnt vmcnt(8)
	s_waitcnt lgkmcnt(0)
	s_barrier
	s_setprio 1
	s_waitcnt lgkmcnt(0)
	v_mfma_f32_16x16x32_bf16 v[76:79], v[48:51], v[184:187], v[76:79]
	v_mfma_f32_16x16x32_bf16 v[72:75], v[64:67], v[184:187], v[72:75]
	v_mfma_f32_16x16x32_bf16 v[44:47], v[48:51], v[192:195], v[44:47]
	v_mfma_f32_16x16x32_bf16 v[40:43], v[64:67], v[192:195], v[40:43]
	v_mfma_f32_16x16x32_bf16 v[28:31], v[48:51], v[202:205], v[28:31]
	v_mfma_f32_16x16x32_bf16 v[24:27], v[64:67], v[202:205], v[24:27]
	v_mfma_f32_16x16x32_bf16 v[12:15], v[48:51], v[210:213], v[12:15]
	v_mfma_f32_16x16x32_bf16 v[8:11], v[64:67], v[210:213], v[8:11]
	v_mfma_f32_16x16x32_bf16 v[76:79], v[52:55], v[188:191], v[76:79]
	v_mfma_f32_16x16x32_bf16 v[72:75], v[68:71], v[188:191], v[72:75]
	v_mfma_f32_16x16x32_bf16 v[44:47], v[52:55], v[196:199], v[44:47]
	v_mfma_f32_16x16x32_bf16 v[40:43], v[68:71], v[196:199], v[40:43]
	v_mfma_f32_16x16x32_bf16 v[28:31], v[52:55], v[206:209], v[28:31]
	v_mfma_f32_16x16x32_bf16 v[24:27], v[68:71], v[206:209], v[24:27]
	v_mfma_f32_16x16x32_bf16 v[12:15], v[52:55], v[214:217], v[12:15]
	v_mfma_f32_16x16x32_bf16 v[8:11], v[68:71], v[214:217], v[8:11]
	s_setprio 0
	s_setprio 1
	v_mfma_f32_16x16x32_bf16 v[36:39], v[160:163], v[192:195], v[36:39]
	v_mfma_f32_16x16x32_bf16 v[32:35], v[176:179], v[192:195], v[32:35]
	v_mfma_f32_16x16x32_bf16 v[20:23], v[160:163], v[202:205], v[20:23]
	v_mfma_f32_16x16x32_bf16 v[16:19], v[176:179], v[202:205], v[16:19]
	v_mfma_f32_16x16x32_bf16 v[4:7], v[160:163], v[210:213], v[4:7]
	v_mfma_f32_16x16x32_bf16 v[0:3], v[176:179], v[210:213], v[0:3]
	v_mfma_f32_16x16x32_bf16 v[48:51], v[160:163], v[184:187], v[60:63]
	v_mfma_f32_16x16x32_bf16 v[52:55], v[176:179], v[184:187], v[56:59]
	v_mfma_f32_16x16x32_bf16 v[36:39], v[172:175], v[196:199], v[36:39]
	v_mfma_f32_16x16x32_bf16 v[32:35], v[180:183], v[196:199], v[32:35]
	v_mfma_f32_16x16x32_bf16 v[20:23], v[172:175], v[206:209], v[20:23]
	v_mfma_f32_16x16x32_bf16 v[16:19], v[180:183], v[206:209], v[16:19]
	v_mfma_f32_16x16x32_bf16 v[4:7], v[172:175], v[214:217], v[4:7]
	v_mfma_f32_16x16x32_bf16 v[0:3], v[180:183], v[214:217], v[0:3]
	v_mfma_f32_16x16x32_bf16 v[48:51], v[172:175], v[188:191], v[48:51]
	v_mfma_f32_16x16x32_bf16 v[52:55], v[180:183], v[188:191], v[52:55]
	s_setprio 0
	s_barrier
	s_add_i32 s90, 0, 0x18000
	s_add_i32 s91, 0, 0x1c000
	v_add_u32_e32 v68, s90, v167
	v_add_u32_e32 v171, s91, v167
	ds_read_b128 v[56:59], v68
	ds_read_b128 v[60:63], v68 offset:1024
	ds_read_b128 v[64:67], v68 offset:2048
	ds_read_b128 v[68:71], v68 offset:3072
	ds_read_b128 v[160:163], v171
	ds_read_b128 v[172:175], v171 offset:1024
	ds_read_b128 v[176:179], v171 offset:2048
	ds_read_b128 v[180:183], v171 offset:3072
	s_add_u32 s10, s10, 0x80000
	s_addc_u32 s11, s11, 0
	s_mov_b32 m0, s35
	v_lshl_add_u64 v[224:225], s[10:11], 0, v[144:145]
	ds_read_b128 v[184:187], v170 offset:32768
	ds_read_b128 v[188:191], v170 offset:33792
	ds_read_b128 v[192:195], v170 offset:34816
	ds_read_b128 v[196:199], v170 offset:35840
	ds_read_b128 v[202:205], v170 offset:36864
	ds_read_b128 v[206:209], v170 offset:37888
	ds_read_b128 v[210:213], v170 offset:38912
	ds_read_b128 v[214:217], v170 offset:39936
	global_load_lds_dwordx4 v[224:225], off
	v_lshl_add_u64 v[224:225], s[10:11], 0, v[148:149]
	s_mov_b32 m0, s64
	s_nop 0
	global_load_lds_dwordx4 v[224:225], off
	s_waitcnt vmcnt(8)
	s_waitcnt lgkmcnt(0)
	s_barrier
	s_setprio 1
	s_waitcnt lgkmcnt(0)
	v_mfma_f32_16x16x32_bf16 v[140:143], v[56:59], v[184:187], v[140:143]
	v_mfma_f32_16x16x32_bf16 v[136:139], v[64:67], v[184:187], v[136:139]
	v_mfma_f32_16x16x32_bf16 v[124:127], v[56:59], v[192:195], v[124:127]
	v_mfma_f32_16x16x32_bf16 v[120:123], v[64:67], v[192:195], v[120:123]
	v_mfma_f32_16x16x32_bf16 v[108:111], v[56:59], v[202:205], v[108:111]
	v_mfma_f32_16x16x32_bf16 v[104:107], v[64:67], v[202:205], v[104:107]
	v_mfma_f32_16x16x32_bf16 v[92:95], v[56:59], v[210:213], v[92:95]
	v_mfma_f32_16x16x32_bf16 v[88:91], v[64:67], v[210:213], v[88:91]
	v_mfma_f32_16x16x32_bf16 v[140:143], v[60:63], v[188:191], v[140:143]
	v_mfma_f32_16x16x32_bf16 v[136:139], v[68:71], v[188:191], v[136:139]
	v_mfma_f32_16x16x32_bf16 v[124:127], v[60:63], v[196:199], v[124:127]
	v_mfma_f32_16x16x32_bf16 v[120:123], v[68:71], v[196:199], v[120:123]
	v_mfma_f32_16x16x32_bf16 v[108:111], v[60:63], v[206:209], v[108:111]
	v_mfma_f32_16x16x32_bf16 v[104:107], v[68:71], v[206:209], v[104:107]
	v_mfma_f32_16x16x32_bf16 v[92:95], v[60:63], v[214:217], v[92:95]
	v_mfma_f32_16x16x32_bf16 v[88:91], v[68:71], v[214:217], v[88:91]
	s_setprio 0
	s_setprio 1
	v_mfma_f32_16x16x32_bf16 v[132:135], v[160:163], v[184:187], v[132:135]
	v_mfma_f32_16x16x32_bf16 v[128:131], v[176:179], v[184:187], v[128:131]
	v_mfma_f32_16x16x32_bf16 v[116:119], v[160:163], v[192:195], v[116:119]
	v_mfma_f32_16x16x32_bf16 v[112:115], v[176:179], v[192:195], v[112:115]
	v_mfma_f32_16x16x32_bf16 v[100:103], v[160:163], v[202:205], v[100:103]
	v_mfma_f32_16x16x32_bf16 v[96:99], v[176:179], v[202:205], v[96:99]
	v_mfma_f32_16x16x32_bf16 v[84:87], v[160:163], v[210:213], v[84:87]
	v_mfma_f32_16x16x32_bf16 v[80:83], v[176:179], v[210:213], v[80:83]
	v_mfma_f32_16x16x32_bf16 v[132:135], v[172:175], v[188:191], v[132:135]
	v_mfma_f32_16x16x32_bf16 v[128:131], v[180:183], v[188:191], v[128:131]
	v_mfma_f32_16x16x32_bf16 v[116:119], v[172:175], v[196:199], v[116:119]
	v_mfma_f32_16x16x32_bf16 v[112:115], v[180:183], v[196:199], v[112:115]
	v_mfma_f32_16x16x32_bf16 v[100:103], v[172:175], v[206:209], v[100:103]
	v_mfma_f32_16x16x32_bf16 v[96:99], v[180:183], v[206:209], v[96:99]
	v_mfma_f32_16x16x32_bf16 v[84:87], v[172:175], v[214:217], v[84:87]
	v_mfma_f32_16x16x32_bf16 v[80:83], v[180:183], v[214:217], v[80:83]
	s_setprio 0
	s_barrier
	s_add_i32 s10, s90, s31
	v_lshl_add_u64 v[164:165], v[164:165], 0, s[22:23]
	s_mov_b32 m0, s10
	ds_read_b128 v[184:187], v170 offset:49152
	ds_read_b128 v[188:191], v170 offset:50176
	ds_read_b128 v[192:195], v170 offset:51200
	ds_read_b128 v[196:199], v170 offset:52224
	ds_read_b128 v[202:205], v170 offset:53248
	ds_read_b128 v[206:209], v170 offset:54272
	ds_read_b128 v[210:213], v170 offset:55296
	ds_read_b128 v[214:217], v170 offset:56320
	global_load_lds_dwordx4 v[164:165], off
	s_add_i32 m0, s10, 0x2000
	s_add_u32 s8, s8, 0x100080
	v_lshl_add_u64 v[164:165], v[218:219], 0, s[22:23]
	s_addc_u32 s9, s9, 0
	s_add_i32 s10, s91, s31
	global_load_lds_dwordx4 v[164:165], off
	v_lshl_add_u64 v[164:165], s[8:9], 0, v[146:147]
	s_mov_b32 m0, s10
	s_nop 0
	global_load_lds_dwordx4 v[164:165], off
	v_lshl_add_u64 v[164:165], s[8:9], 0, v[150:151]
	s_add_i32 m0, s10, 0x2000
	s_nop 0
	global_load_lds_dwordx4 v[164:165], off
	v_lshl_add_u64 v[164:165], v[220:221], 0, s[22:23]
	s_mov_b32 m0, s77
	s_nop 0
	global_load_lds_dwordx4 v[164:165], off
	v_lshl_add_u64 v[164:165], v[222:223], 0, s[22:23]
	s_mov_b32 m0, s78
	s_nop 0
	global_load_lds_dwordx4 v[164:165], off
	s_waitcnt vmcnt(8)
	s_waitcnt lgkmcnt(0)
	s_barrier
	s_setprio 1
	s_waitcnt lgkmcnt(0)
	v_mfma_f32_16x16x32_bf16 v[76:79], v[56:59], v[184:187], v[76:79]
	v_mfma_f32_16x16x32_bf16 v[72:75], v[64:67], v[184:187], v[72:75]
	v_mfma_f32_16x16x32_bf16 v[44:47], v[56:59], v[192:195], v[44:47]
	v_mfma_f32_16x16x32_bf16 v[40:43], v[64:67], v[192:195], v[40:43]
	v_mfma_f32_16x16x32_bf16 v[28:31], v[56:59], v[202:205], v[28:31]
	v_mfma_f32_16x16x32_bf16 v[24:27], v[64:67], v[202:205], v[24:27]
	v_mfma_f32_16x16x32_bf16 v[12:15], v[56:59], v[210:213], v[12:15]
	v_mfma_f32_16x16x32_bf16 v[8:11], v[64:67], v[210:213], v[8:11]
	v_mfma_f32_16x16x32_bf16 v[76:79], v[60:63], v[188:191], v[76:79]
	v_mfma_f32_16x16x32_bf16 v[72:75], v[68:71], v[188:191], v[72:75]
	v_mfma_f32_16x16x32_bf16 v[44:47], v[60:63], v[196:199], v[44:47]
	v_mfma_f32_16x16x32_bf16 v[40:43], v[68:71], v[196:199], v[40:43]
	v_mfma_f32_16x16x32_bf16 v[28:31], v[60:63], v[206:209], v[28:31]
	v_mfma_f32_16x16x32_bf16 v[24:27], v[68:71], v[206:209], v[24:27]
	v_mfma_f32_16x16x32_bf16 v[12:15], v[60:63], v[214:217], v[12:15]
	v_mfma_f32_16x16x32_bf16 v[8:11], v[68:71], v[214:217], v[8:11]
	s_setprio 0
	s_setprio 1
	v_mfma_f32_16x16x32_bf16 v[48:51], v[160:163], v[184:187], v[48:51]
	v_mfma_f32_16x16x32_bf16 v[60:63], v[172:175], v[188:191], v[48:51]
	v_mfma_f32_16x16x32_bf16 v[48:51], v[176:179], v[184:187], v[52:55]
	v_mfma_f32_16x16x32_bf16 v[36:39], v[160:163], v[192:195], v[36:39]
	v_mfma_f32_16x16x32_bf16 v[32:35], v[176:179], v[192:195], v[32:35]
	v_mfma_f32_16x16x32_bf16 v[20:23], v[160:163], v[202:205], v[20:23]
	v_mfma_f32_16x16x32_bf16 v[16:19], v[176:179], v[202:205], v[16:19]
	v_mfma_f32_16x16x32_bf16 v[4:7], v[160:163], v[210:213], v[4:7]
	v_mfma_f32_16x16x32_bf16 v[0:3], v[176:179], v[210:213], v[0:3]
	v_mfma_f32_16x16x32_bf16 v[56:59], v[180:183], v[188:191], v[48:51]
	v_mfma_f32_16x16x32_bf16 v[36:39], v[172:175], v[196:199], v[36:39]
	v_mfma_f32_16x16x32_bf16 v[32:35], v[180:183], v[196:199], v[32:35]
	v_mfma_f32_16x16x32_bf16 v[20:23], v[172:175], v[206:209], v[20:23]
	v_mfma_f32_16x16x32_bf16 v[16:19], v[180:183], v[206:209], v[16:19]
	v_mfma_f32_16x16x32_bf16 v[4:7], v[172:175], v[214:217], v[4:7]
	v_mfma_f32_16x16x32_bf16 v[0:3], v[180:183], v[214:217], v[0:3]
	s_setprio 0
	s_add_u32 s6, s6, 0x100
	s_addc_u32 s7, s7, 0
	s_add_u32 s87, s87, 0x100
	s_addc_u32 s88, s88, 0
	s_cmp_ge_i32 s89, s19
	s_mov_b32 s8, s89
	s_barrier
	s_cbranch_scc0 .LBB0_840
	s_and_b64 vcc, exec, s[24:25]
	s_cbranch_vccz .LBB0_843

.LBB0_866:
	ds_read_b128 v[24:27], v170
	ds_read_b128 v[28:31], v170 offset:1024
	ds_read_b128 v[40:43], v170 offset:2048
	ds_read_b128 v[44:47], v170 offset:3072
	ds_read_b128 v[160:163], v171
	ds_read_b128 v[164:167], v171 offset:1024
	ds_read_b128 v[174:177], v171 offset:2048
	ds_read_b128 v[178:181], v171 offset:3072
	s_add_i32 s89, s8, 2
	s_add_u32 s9, s6, 0xfff80080
	s_addc_u32 s10, s7, -1
	s_cmp_eq_u32 s79, s8
	s_cselect_b32 s8, s86, s87
	s_cselect_b32 s11, s55, s10
	s_cselect_b32 s10, s57, s9
	s_cselect_b32 s9, s83, s88
	v_lshl_add_u64 v[198:199], s[6:7], 0, v[156:157]
	s_add_i32 m0, s65, 0xc000
	ds_read_b128 v[182:185], v172
	ds_read_b128 v[186:189], v172 offset:1024
	ds_read_b128 v[190:193], v172 offset:2048
	ds_read_b128 v[194:197], v172 offset:3072
	ds_read_b128 v[202:205], v172 offset:4096
	ds_read_b128 v[206:209], v172 offset:5120
	ds_read_b128 v[210:213], v172 offset:6144
	ds_read_b128 v[214:217], v172 offset:7168
	global_load_lds_dwordx4 v[198:199], off
	v_lshl_add_u64 v[198:199], s[6:7], 0, v[158:159]
	s_add_i32 m0, s65, 0xe000
	s_nop 0
	global_load_lds_dwordx4 v[198:199], off
	s_waitcnt vmcnt(8)
	s_waitcnt lgkmcnt(0)
	s_barrier
	s_setprio 1
	s_waitcnt lgkmcnt(0)
	v_mfma_f32_16x16x32_bf16 v[140:143], v[24:27], v[182:185], v[140:143]
	v_mfma_f32_16x16x32_bf16 v[136:139], v[40:43], v[182:185], v[136:139]
	v_mfma_f32_16x16x32_bf16 v[124:127], v[24:27], v[190:193], v[124:127]
	v_mfma_f32_16x16x32_bf16 v[120:123], v[40:43], v[190:193], v[120:123]
	v_mfma_f32_16x16x32_bf16 v[108:111], v[24:27], v[202:205], v[108:111]
	v_mfma_f32_16x16x32_bf16 v[104:107], v[40:43], v[202:205], v[104:107]
	v_mfma_f32_16x16x32_bf16 v[92:95], v[24:27], v[210:213], v[92:95]
	v_mfma_f32_16x16x32_bf16 v[88:91], v[40:43], v[210:213], v[88:91]
	v_mfma_f32_16x16x32_bf16 v[140:143], v[28:31], v[186:189], v[140:143]
	v_mfma_f32_16x16x32_bf16 v[136:139], v[44:47], v[186:189], v[136:139]
	v_mfma_f32_16x16x32_bf16 v[124:127], v[28:31], v[194:197], v[124:127]
	v_mfma_f32_16x16x32_bf16 v[120:123], v[44:47], v[194:197], v[120:123]
	v_mfma_f32_16x16x32_bf16 v[108:111], v[28:31], v[206:209], v[108:111]
	v_mfma_f32_16x16x32_bf16 v[104:107], v[44:47], v[206:209], v[104:107]
	v_mfma_f32_16x16x32_bf16 v[92:95], v[28:31], v[214:217], v[92:95]
	v_mfma_f32_16x16x32_bf16 v[88:91], v[44:47], v[214:217], v[88:91]
	s_setprio 0
	s_setprio 1
	v_mfma_f32_16x16x32_bf16 v[132:135], v[160:163], v[182:185], v[132:135]
	v_mfma_f32_16x16x32_bf16 v[128:131], v[174:177], v[182:185], v[128:131]
	v_mfma_f32_16x16x32_bf16 v[116:119], v[160:163], v[190:193], v[116:119]
	v_mfma_f32_16x16x32_bf16 v[112:115], v[174:177], v[190:193], v[112:115]
	v_mfma_f32_16x16x32_bf16 v[100:103], v[160:163], v[202:205], v[100:103]
	v_mfma_f32_16x16x32_bf16 v[96:99], v[174:177], v[202:205], v[96:99]
	v_mfma_f32_16x16x32_bf16 v[84:87], v[160:163], v[210:213], v[84:87]
	v_mfma_f32_16x16x32_bf16 v[80:83], v[174:177], v[210:213], v[80:83]
	v_mfma_f32_16x16x32_bf16 v[132:135], v[164:167], v[186:189], v[132:135]
	v_mfma_f32_16x16x32_bf16 v[128:131], v[178:181], v[186:189], v[128:131]
	v_mfma_f32_16x16x32_bf16 v[116:119], v[164:167], v[194:197], v[116:119]
	v_mfma_f32_16x16x32_bf16 v[112:115], v[178:181], v[194:197], v[112:115]
	v_mfma_f32_16x16x32_bf16 v[100:103], v[164:167], v[206:209], v[100:103]
	v_mfma_f32_16x16x32_bf16 v[96:99], v[178:181], v[206:209], v[96:99]
	v_mfma_f32_16x16x32_bf16 v[84:87], v[164:167], v[214:217], v[84:87]
	v_mfma_f32_16x16x32_bf16 v[80:83], v[178:181], v[214:217], v[80:83]
	s_setprio 0
	s_barrier
	s_add_i32 s90, s80, s64
	v_lshl_add_u64 v[198:199], s[8:9], 0, v[146:147]
	s_mov_b32 m0, s90
	ds_read_b128 v[182:185], v172 offset:16384
	ds_read_b128 v[186:189], v172 offset:17408
	ds_read_b128 v[190:193], v172 offset:18432
	ds_read_b128 v[194:197], v172 offset:19456
	ds_read_b128 v[202:205], v172 offset:20480
	ds_read_b128 v[206:209], v172 offset:21504
	ds_read_b128 v[210:213], v172 offset:22528
	ds_read_b128 v[214:217], v172 offset:23552
	global_load_lds_dwordx4 v[198:199], off
	s_add_i32 m0, s90, 0x2000
	s_add_u32 s90, s8, 0x100000
	v_lshl_add_u64 v[218:219], s[8:9], 0, v[150:151]
	s_addc_u32 s91, s9, 0
	s_add_i32 s92, s81, s64
	global_load_lds_dwordx4 v[218:219], off
	v_lshl_add_u64 v[220:221], s[90:91], 0, v[146:147]
	s_mov_b32 m0, s92
	v_lshl_add_u64 v[222:223], s[10:11], 0, v[148:149]
	global_load_lds_dwordx4 v[220:221], off
	v_lshl_add_u64 v[220:221], s[90:91], 0, v[150:151]
	s_add_i32 m0, s92, 0x2000
	s_nop 0
	global_load_lds_dwordx4 v[220:221], off
	v_lshl_add_u64 v[220:221], s[10:11], 0, v[144:145]
	s_mov_b32 m0, s65
	s_nop 0
	global_load_lds_dwordx4 v[220:221], off
	s_mov_b32 m0, s66
	s_nop 0
	global_load_lds_dwordx4 v[222:223], off
	s_waitcnt vmcnt(8)
	s_waitcnt lgkmcnt(0)
	s_barrier
	s_setprio 1
	s_waitcnt lgkmcnt(0)
	v_mfma_f32_16x16x32_bf16 v[76:79], v[24:27], v[182:185], v[76:79]
	v_mfma_f32_16x16x32_bf16 v[72:75], v[40:43], v[182:185], v[72:75]
	v_mfma_f32_16x16x32_bf16 v[60:63], v[24:27], v[190:193], v[60:63]
	v_mfma_f32_16x16x32_bf16 v[56:59], v[40:43], v[190:193], v[56:59]
	v_mfma_f32_16x16x32_bf16 v[36:39], v[24:27], v[202:205], v[36:39]
	v_mfma_f32_16x16x32_bf16 v[32:35], v[40:43], v[202:205], v[32:35]
	v_mfma_f32_16x16x32_bf16 v[12:15], v[24:27], v[210:213], v[12:15]
	v_mfma_f32_16x16x32_bf16 v[8:11], v[40:43], v[210:213], v[8:11]
	v_mfma_f32_16x16x32_bf16 v[76:79], v[28:31], v[186:189], v[76:79]
	v_mfma_f32_16x16x32_bf16 v[72:75], v[44:47], v[186:189], v[72:75]
	v_mfma_f32_16x16x32_bf16 v[60:63], v[28:31], v[194:197], v[60:63]
	v_mfma_f32_16x16x32_bf16 v[56:59], v[44:47], v[194:197], v[56:59]
	v_mfma_f32_16x16x32_bf16 v[36:39], v[28:31], v[206:209], v[36:39]
	v_mfma_f32_16x16x32_bf16 v[32:35], v[44:47], v[206:209], v[32:35]
	v_mfma_f32_16x16x32_bf16 v[12:15], v[28:31], v[214:217], v[12:15]
	v_mfma_f32_16x16x32_bf16 v[8:11], v[44:47], v[214:217], v[8:11]
	s_setprio 0
	s_setprio 1
	v_mfma_f32_16x16x32_bf16 v[20:23], v[160:163], v[202:205], v[20:23]
	v_mfma_f32_16x16x32_bf16 v[16:19], v[174:177], v[202:205], v[16:19]
	v_mfma_f32_16x16x32_bf16 v[4:7], v[160:163], v[210:213], v[4:7]
	v_mfma_f32_16x16x32_bf16 v[0:3], v[174:177], v[210:213], v[0:3]
	v_mfma_f32_16x16x32_bf16 v[24:27], v[160:163], v[182:185], v[68:71]
	v_mfma_f32_16x16x32_bf16 v[28:31], v[174:177], v[182:185], v[64:67]
	v_mfma_f32_16x16x32_bf16 v[40:43], v[160:163], v[190:193], v[52:55]
	v_mfma_f32_16x16x32_bf16 v[44:47], v[174:177], v[190:193], v[48:51]
	v_mfma_f32_16x16x32_bf16 v[20:23], v[164:167], v[206:209], v[20:23]
	v_mfma_f32_16x16x32_bf16 v[16:19], v[178:181], v[206:209], v[16:19]
	v_mfma_f32_16x16x32_bf16 v[4:7], v[164:167], v[214:217], v[4:7]
	v_mfma_f32_16x16x32_bf16 v[0:3], v[178:181], v[214:217], v[0:3]
	v_mfma_f32_16x16x32_bf16 v[24:27], v[164:167], v[186:189], v[24:27]
	v_mfma_f32_16x16x32_bf16 v[28:31], v[178:181], v[186:189], v[28:31]
	v_mfma_f32_16x16x32_bf16 v[40:43], v[164:167], v[194:197], v[40:43]
	v_mfma_f32_16x16x32_bf16 v[44:47], v[178:181], v[194:197], v[44:47]
	s_setprio 0
	s_barrier
	s_add_i32 s90, 0, 0x18000
	s_add_i32 s91, 0, 0x1c000
	v_add_u32_e32 v68, s90, v169
	v_add_u32_e32 v173, s91, v169
	ds_read_b128 v[48:51], v68
	ds_read_b128 v[52:55], v68 offset:1024
	ds_read_b128 v[64:67], v68 offset:2048
	ds_read_b128 v[68:71], v68 offset:3072
	ds_read_b128 v[160:163], v173
	ds_read_b128 v[164:167], v173 offset:1024
	ds_read_b128 v[174:177], v173 offset:2048
	ds_read_b128 v[178:181], v173 offset:3072
	s_add_u32 s10, s10, 0x80000
	s_addc_u32 s11, s11, 0
	s_mov_b32 m0, s67
	v_lshl_add_u64 v[224:225], s[10:11], 0, v[144:145]
	ds_read_b128 v[182:185], v172 offset:32768
	ds_read_b128 v[186:189], v172 offset:33792
	ds_read_b128 v[190:193], v172 offset:34816
	ds_read_b128 v[194:197], v172 offset:35840
	ds_read_b128 v[202:205], v172 offset:36864
	ds_read_b128 v[206:209], v172 offset:37888
	ds_read_b128 v[210:213], v172 offset:38912
	ds_read_b128 v[214:217], v172 offset:39936
	global_load_lds_dwordx4 v[224:225], off
	v_lshl_add_u64 v[224:225], s[10:11], 0, v[148:149]
	s_mov_b32 m0, s76
	s_nop 0
	global_load_lds_dwordx4 v[224:225], off
	s_waitcnt vmcnt(8)
	s_waitcnt lgkmcnt(0)
	s_barrier
	s_setprio 1
	s_waitcnt lgkmcnt(0)
	v_mfma_f32_16x16x32_bf16 v[140:143], v[48:51], v[182:185], v[140:143]
	v_mfma_f32_16x16x32_bf16 v[136:139], v[64:67], v[182:185], v[136:139]
	v_mfma_f32_16x16x32_bf16 v[124:127], v[48:51], v[190:193], v[124:127]
	v_mfma_f32_16x16x32_bf16 v[120:123], v[64:67], v[190:193], v[120:123]
	v_mfma_f32_16x16x32_bf16 v[108:111], v[48:51], v[202:205], v[108:111]
	v_mfma_f32_16x16x32_bf16 v[104:107], v[64:67], v[202:205], v[104:107]
	v_mfma_f32_16x16x32_bf16 v[92:95], v[48:51], v[210:213], v[92:95]
	v_mfma_f32_16x16x32_bf16 v[88:91], v[64:67], v[210:213], v[88:91]
	v_mfma_f32_16x16x32_bf16 v[140:143], v[52:55], v[186:189], v[140:143]
	v_mfma_f32_16x16x32_bf16 v[136:139], v[68:71], v[186:189], v[136:139]
	v_mfma_f32_16x16x32_bf16 v[124:127], v[52:55], v[194:197], v[124:127]
	v_mfma_f32_16x16x32_bf16 v[120:123], v[68:71], v[194:197], v[120:123]
	v_mfma_f32_16x16x32_bf16 v[108:111], v[52:55], v[206:209], v[108:111]
	v_mfma_f32_16x16x32_bf16 v[104:107], v[68:71], v[206:209], v[104:107]
	v_mfma_f32_16x16x32_bf16 v[92:95], v[52:55], v[214:217], v[92:95]
	v_mfma_f32_16x16x32_bf16 v[88:91], v[68:71], v[214:217], v[88:91]
	s_setprio 0
	s_setprio 1
	v_mfma_f32_16x16x32_bf16 v[132:135], v[160:163], v[182:185], v[132:135]
	v_mfma_f32_16x16x32_bf16 v[128:131], v[174:177], v[182:185], v[128:131]
	v_mfma_f32_16x16x32_bf16 v[116:119], v[160:163], v[190:193], v[116:119]
	v_mfma_f32_16x16x32_bf16 v[112:115], v[174:177], v[190:193], v[112:115]
	v_mfma_f32_16x16x32_bf16 v[100:103], v[160:163], v[202:205], v[100:103]
	v_mfma_f32_16x16x32_bf16 v[96:99], v[174:177], v[202:205], v[96:99]
	v_mfma_f32_16x16x32_bf16 v[84:87], v[160:163], v[210:213], v[84:87]
	v_mfma_f32_16x16x32_bf16 v[80:83], v[174:177], v[210:213], v[80:83]
	v_mfma_f32_16x16x32_bf16 v[132:135], v[164:167], v[186:189], v[132:135]
	v_mfma_f32_16x16x32_bf16 v[128:131], v[178:181], v[186:189], v[128:131]
	v_mfma_f32_16x16x32_bf16 v[116:119], v[164:167], v[194:197], v[116:119]
	v_mfma_f32_16x16x32_bf16 v[112:115], v[178:181], v[194:197], v[112:115]
	v_mfma_f32_16x16x32_bf16 v[100:103], v[164:167], v[206:209], v[100:103]
	v_mfma_f32_16x16x32_bf16 v[96:99], v[178:181], v[206:209], v[96:99]
	v_mfma_f32_16x16x32_bf16 v[84:87], v[164:167], v[214:217], v[84:87]
	v_mfma_f32_16x16x32_bf16 v[80:83], v[178:181], v[214:217], v[80:83]
	s_setprio 0
	s_barrier
	s_add_i32 s10, s90, s64
	v_lshl_add_u64 v[198:199], v[198:199], 0, s[26:27]
	s_mov_b32 m0, s10
	ds_read_b128 v[182:185], v172 offset:49152
	ds_read_b128 v[186:189], v172 offset:50176
	ds_read_b128 v[190:193], v172 offset:51200
	ds_read_b128 v[194:197], v172 offset:52224
	ds_read_b128 v[202:205], v172 offset:53248
	ds_read_b128 v[206:209], v172 offset:54272
	ds_read_b128 v[210:213], v172 offset:55296
	ds_read_b128 v[214:217], v172 offset:56320
	global_load_lds_dwordx4 v[198:199], off
	s_add_i32 m0, s10, 0x2000
	s_add_u32 s8, s8, 0x100080
	v_lshl_add_u64 v[198:199], v[218:219], 0, s[26:27]
	s_addc_u32 s9, s9, 0
	s_add_i32 s10, s91, s64
	global_load_lds_dwordx4 v[198:199], off
	v_lshl_add_u64 v[198:199], s[8:9], 0, v[146:147]
	s_mov_b32 m0, s10
	s_nop 0
	global_load_lds_dwordx4 v[198:199], off
	v_lshl_add_u64 v[198:199], s[8:9], 0, v[150:151]
	s_add_i32 m0, s10, 0x2000
	s_nop 0
	global_load_lds_dwordx4 v[198:199], off
	v_lshl_add_u64 v[198:199], v[220:221], 0, s[26:27]
	s_mov_b32 m0, s77
	s_nop 0
	global_load_lds_dwordx4 v[198:199], off
	v_lshl_add_u64 v[198:199], v[222:223], 0, s[26:27]
	s_mov_b32 m0, s78
	s_nop 0
	global_load_lds_dwordx4 v[198:199], off
	s_waitcnt vmcnt(8)
	s_waitcnt lgkmcnt(0)
	s_barrier
	s_setprio 1
	s_waitcnt lgkmcnt(0)
	v_mfma_f32_16x16x32_bf16 v[76:79], v[48:51], v[182:185], v[76:79]
	v_mfma_f32_16x16x32_bf16 v[72:75], v[64:67], v[182:185], v[72:75]
	v_mfma_f32_16x16x32_bf16 v[60:63], v[48:51], v[190:193], v[60:63]
	v_mfma_f32_16x16x32_bf16 v[56:59], v[64:67], v[190:193], v[56:59]
	v_mfma_f32_16x16x32_bf16 v[36:39], v[48:51], v[202:205], v[36:39]
	v_mfma_f32_16x16x32_bf16 v[32:35], v[64:67], v[202:205], v[32:35]
	v_mfma_f32_16x16x32_bf16 v[12:15], v[48:51], v[210:213], v[12:15]
	v_mfma_f32_16x16x32_bf16 v[8:11], v[64:67], v[210:213], v[8:11]
	v_mfma_f32_16x16x32_bf16 v[76:79], v[52:55], v[186:189], v[76:79]
	v_mfma_f32_16x16x32_bf16 v[72:75], v[68:71], v[186:189], v[72:75]
	v_mfma_f32_16x16x32_bf16 v[60:63], v[52:55], v[194:197], v[60:63]
	v_mfma_f32_16x16x32_bf16 v[56:59], v[68:71], v[194:197], v[56:59]
	v_mfma_f32_16x16x32_bf16 v[36:39], v[52:55], v[206:209], v[36:39]
	v_mfma_f32_16x16x32_bf16 v[32:35], v[68:71], v[206:209], v[32:35]
	v_mfma_f32_16x16x32_bf16 v[12:15], v[52:55], v[214:217], v[12:15]
	v_mfma_f32_16x16x32_bf16 v[8:11], v[68:71], v[214:217], v[8:11]
	s_setprio 0
	s_setprio 1
	v_mfma_f32_16x16x32_bf16 v[24:27], v[160:163], v[182:185], v[24:27]
	v_mfma_f32_16x16x32_bf16 v[68:71], v[164:167], v[186:189], v[24:27]
	v_mfma_f32_16x16x32_bf16 v[24:27], v[174:177], v[182:185], v[28:31]
	v_mfma_f32_16x16x32_bf16 v[64:67], v[178:181], v[186:189], v[24:27]
	v_mfma_f32_16x16x32_bf16 v[24:27], v[160:163], v[190:193], v[40:43]
	v_mfma_f32_16x16x32_bf16 v[52:55], v[164:167], v[194:197], v[24:27]
	v_mfma_f32_16x16x32_bf16 v[24:27], v[174:177], v[190:193], v[44:47]
	v_mfma_f32_16x16x32_bf16 v[20:23], v[160:163], v[202:205], v[20:23]
	v_mfma_f32_16x16x32_bf16 v[16:19], v[174:177], v[202:205], v[16:19]
	v_mfma_f32_16x16x32_bf16 v[4:7], v[160:163], v[210:213], v[4:7]
	v_mfma_f32_16x16x32_bf16 v[0:3], v[174:177], v[210:213], v[0:3]
	v_mfma_f32_16x16x32_bf16 v[48:51], v[178:181], v[194:197], v[24:27]
	v_mfma_f32_16x16x32_bf16 v[20:23], v[164:167], v[206:209], v[20:23]
	v_mfma_f32_16x16x32_bf16 v[16:19], v[178:181], v[206:209], v[16:19]
	v_mfma_f32_16x16x32_bf16 v[4:7], v[164:167], v[214:217], v[4:7]
	v_mfma_f32_16x16x32_bf16 v[0:3], v[178:181], v[214:217], v[0:3]
	s_setprio 0
	s_add_u32 s6, s6, 0x100
	s_addc_u32 s7, s7, 0
	s_add_u32 s87, s87, 0x100
	s_addc_u32 s88, s88, 0
	s_cmp_ge_i32 s89, s18
	s_mov_b32 s8, s89
	s_barrier
	s_cbranch_scc0 .LBB0_866
	s_and_b64 vcc, exec, s[28:29]
	s_cbranch_vccz .LBB0_869

.LBB0_918:
	ds_read_b128 v[152:155], v148
	ds_read_b128 v[156:159], v148 offset:1024
	ds_read_b128 v[160:163], v148 offset:2048
	ds_read_b128 v[164:167], v148 offset:3072
	ds_read_b128 v[168:171], v149
	ds_read_b128 v[172:175], v149 offset:1024
	ds_read_b128 v[176:179], v149 offset:2048
	ds_read_b128 v[180:183], v149 offset:3072
	s_add_i32 s92, s56, 2
	s_add_u32 s57, s52, 0xffff0080
	s_addc_u32 s58, s53, -1
	s_cmp_eq_u32 s79, s56
	s_cselect_b32 s56, s89, s90
	s_cselect_b32 s59, s25, s58
	s_cselect_b32 s58, s27, s57
	s_cselect_b32 s57, s88, s91
	v_lshl_add_u64 v[218:219], s[52:53], 0, v[138:139]
	s_add_i32 m0, s64, 0xc000
	ds_read_b128 v[184:187], v150
	ds_read_b128 v[188:191], v150 offset:1024
	ds_read_b128 v[192:195], v150 offset:2048
	ds_read_b128 v[196:199], v150 offset:3072
	ds_read_b128 v[202:205], v150 offset:4096
	ds_read_b128 v[206:209], v150 offset:5120
	ds_read_b128 v[210:213], v150 offset:6144
	ds_read_b128 v[214:217], v150 offset:7168
	global_load_lds_dwordx4 v[218:219], off
	v_lshl_add_u64 v[218:219], s[52:53], 0, v[140:141]
	s_add_i32 m0, s64, 0xe000
	s_nop 0
	global_load_lds_dwordx4 v[218:219], off
	s_waitcnt vmcnt(8)
	s_waitcnt lgkmcnt(0)
	s_barrier
	s_setprio 1
	s_waitcnt lgkmcnt(0)
	v_mfma_f32_16x16x32_bf16 v[124:127], v[152:155], v[184:187], v[124:127]
	v_mfma_f32_16x16x32_bf16 v[120:123], v[160:163], v[184:187], v[120:123]
	v_mfma_f32_16x16x32_bf16 v[108:111], v[152:155], v[192:195], v[108:111]
	v_mfma_f32_16x16x32_bf16 v[104:107], v[160:163], v[192:195], v[104:107]
	v_mfma_f32_16x16x32_bf16 v[92:95], v[152:155], v[202:205], v[92:95]
	v_mfma_f32_16x16x32_bf16 v[88:91], v[160:163], v[202:205], v[88:91]
	v_mfma_f32_16x16x32_bf16 v[76:79], v[152:155], v[210:213], v[76:79]
	v_mfma_f32_16x16x32_bf16 v[72:75], v[160:163], v[210:213], v[72:75]
	v_mfma_f32_16x16x32_bf16 v[124:127], v[156:159], v[188:191], v[124:127]
	v_mfma_f32_16x16x32_bf16 v[120:123], v[164:167], v[188:191], v[120:123]
	v_mfma_f32_16x16x32_bf16 v[108:111], v[156:159], v[196:199], v[108:111]
	v_mfma_f32_16x16x32_bf16 v[104:107], v[164:167], v[196:199], v[104:107]
	v_mfma_f32_16x16x32_bf16 v[92:95], v[156:159], v[206:209], v[92:95]
	v_mfma_f32_16x16x32_bf16 v[88:91], v[164:167], v[206:209], v[88:91]
	v_mfma_f32_16x16x32_bf16 v[76:79], v[156:159], v[214:217], v[76:79]
	v_mfma_f32_16x16x32_bf16 v[72:75], v[164:167], v[214:217], v[72:75]
	s_setprio 0
	s_setprio 1
	v_mfma_f32_16x16x32_bf16 v[116:119], v[168:171], v[184:187], v[116:119]
	v_mfma_f32_16x16x32_bf16 v[112:115], v[176:179], v[184:187], v[112:115]
	v_mfma_f32_16x16x32_bf16 v[100:103], v[168:171], v[192:195], v[100:103]
	v_mfma_f32_16x16x32_bf16 v[96:99], v[176:179], v[192:195], v[96:99]
	v_mfma_f32_16x16x32_bf16 v[84:87], v[168:171], v[202:205], v[84:87]
	v_mfma_f32_16x16x32_bf16 v[80:83], v[176:179], v[202:205], v[80:83]
	v_mfma_f32_16x16x32_bf16 v[68:71], v[168:171], v[210:213], v[68:71]
	v_mfma_f32_16x16x32_bf16 v[64:67], v[176:179], v[210:213], v[64:67]
	v_mfma_f32_16x16x32_bf16 v[116:119], v[172:175], v[188:191], v[116:119]
	v_mfma_f32_16x16x32_bf16 v[112:115], v[180:183], v[188:191], v[112:115]
	v_mfma_f32_16x16x32_bf16 v[100:103], v[172:175], v[196:199], v[100:103]
	v_mfma_f32_16x16x32_bf16 v[96:99], v[180:183], v[196:199], v[96:99]
	v_mfma_f32_16x16x32_bf16 v[84:87], v[172:175], v[206:209], v[84:87]
	v_mfma_f32_16x16x32_bf16 v[80:83], v[180:183], v[206:209], v[80:83]
	v_mfma_f32_16x16x32_bf16 v[68:71], v[172:175], v[214:217], v[68:71]
	v_mfma_f32_16x16x32_bf16 v[64:67], v[180:183], v[214:217], v[64:67]
	s_setprio 0
	s_barrier
	s_add_i32 s93, s81, s61
	v_lshl_add_u64 v[218:219], s[56:57], 0, v[132:133]
	s_mov_b32 m0, s93
	ds_read_b128 v[184:187], v150 offset:16384
	ds_read_b128 v[188:191], v150 offset:17408
	ds_read_b128 v[192:195], v150 offset:18432
	ds_read_b128 v[196:199], v150 offset:19456
	ds_read_b128 v[202:205], v150 offset:20480
	ds_read_b128 v[206:209], v150 offset:21504
	ds_read_b128 v[210:213], v150 offset:22528
	ds_read_b128 v[214:217], v150 offset:23552
	global_load_lds_dwordx4 v[218:219], off
	s_add_i32 m0, s93, 0x2000
	s_add_u32 s94, s56, 0x10000
	v_lshl_add_u64 v[220:221], s[56:57], 0, v[128:129]
	s_addc_u32 s95, s57, 0
	s_add_i32 s93, s82, s61
	global_load_lds_dwordx4 v[220:221], off
	v_lshl_add_u64 v[222:223], s[94:95], 0, v[132:133]
	s_mov_b32 m0, s93
	v_lshl_add_u64 v[224:225], s[58:59], 0, v[130:131]
	global_load_lds_dwordx4 v[222:223], off
	v_lshl_add_u64 v[222:223], s[94:95], 0, v[128:129]
	s_add_i32 m0, s93, 0x2000
	s_nop 0
	global_load_lds_dwordx4 v[222:223], off
	v_lshl_add_u64 v[222:223], s[58:59], 0, v[134:135]
	s_mov_b32 m0, s64
	s_nop 0
	global_load_lds_dwordx4 v[222:223], off
	s_mov_b32 m0, s65
	s_nop 0
	global_load_lds_dwordx4 v[224:225], off
	s_waitcnt vmcnt(8)
	s_waitcnt lgkmcnt(0)
	s_barrier
	s_setprio 1
	s_waitcnt lgkmcnt(0)
	v_mfma_f32_16x16x32_bf16 v[60:63], v[152:155], v[184:187], v[60:63]
	v_mfma_f32_16x16x32_bf16 v[56:59], v[160:163], v[184:187], v[56:59]
	v_mfma_f32_16x16x32_bf16 v[44:47], v[152:155], v[192:195], v[44:47]
	v_mfma_f32_16x16x32_bf16 v[40:43], v[160:163], v[192:195], v[40:43]
	v_mfma_f32_16x16x32_bf16 v[28:31], v[152:155], v[202:205], v[28:31]
	v_mfma_f32_16x16x32_bf16 v[24:27], v[160:163], v[202:205], v[24:27]
	v_mfma_f32_16x16x32_bf16 v[12:15], v[152:155], v[210:213], v[12:15]
	v_mfma_f32_16x16x32_bf16 v[8:11], v[160:163], v[210:213], v[8:11]
	v_mfma_f32_16x16x32_bf16 v[60:63], v[156:159], v[188:191], v[60:63]
	v_mfma_f32_16x16x32_bf16 v[56:59], v[164:167], v[188:191], v[56:59]
	v_mfma_f32_16x16x32_bf16 v[44:47], v[156:159], v[196:199], v[44:47]
	v_mfma_f32_16x16x32_bf16 v[40:43], v[164:167], v[196:199], v[40:43]
	v_mfma_f32_16x16x32_bf16 v[28:31], v[156:159], v[206:209], v[28:31]
	v_mfma_f32_16x16x32_bf16 v[24:27], v[164:167], v[206:209], v[24:27]
	v_mfma_f32_16x16x32_bf16 v[12:15], v[156:159], v[214:217], v[12:15]
	v_mfma_f32_16x16x32_bf16 v[8:11], v[164:167], v[214:217], v[8:11]
	s_setprio 0
	s_setprio 1
	v_mfma_f32_16x16x32_bf16 v[52:55], v[168:171], v[184:187], v[52:55]
	v_mfma_f32_16x16x32_bf16 v[48:51], v[176:179], v[184:187], v[48:51]
	v_mfma_f32_16x16x32_bf16 v[36:39], v[168:171], v[192:195], v[36:39]
	v_mfma_f32_16x16x32_bf16 v[32:35], v[176:179], v[192:195], v[32:35]
	v_mfma_f32_16x16x32_bf16 v[20:23], v[168:171], v[202:205], v[20:23]
	v_mfma_f32_16x16x32_bf16 v[16:19], v[176:179], v[202:205], v[16:19]
	v_mfma_f32_16x16x32_bf16 v[4:7], v[168:171], v[210:213], v[4:7]
	v_mfma_f32_16x16x32_bf16 v[0:3], v[176:179], v[210:213], v[0:3]
	v_mfma_f32_16x16x32_bf16 v[52:55], v[172:175], v[188:191], v[52:55]
	v_mfma_f32_16x16x32_bf16 v[48:51], v[180:183], v[188:191], v[48:51]
	v_mfma_f32_16x16x32_bf16 v[36:39], v[172:175], v[196:199], v[36:39]
	v_mfma_f32_16x16x32_bf16 v[32:35], v[180:183], v[196:199], v[32:35]
	v_mfma_f32_16x16x32_bf16 v[20:23], v[172:175], v[206:209], v[20:23]
	v_mfma_f32_16x16x32_bf16 v[16:19], v[180:183], v[206:209], v[16:19]
	v_mfma_f32_16x16x32_bf16 v[4:7], v[172:175], v[214:217], v[4:7]
	v_mfma_f32_16x16x32_bf16 v[0:3], v[180:183], v[214:217], v[0:3]
	s_setprio 0
	s_barrier
	s_add_i32 s93, 0, 0x18000
	v_add_u32_e32 v151, s93, v147
	s_add_i32 s94, 0, 0x1c000
	ds_read_b128 v[152:155], v151
	ds_read_b128 v[156:159], v151 offset:1024
	ds_read_b128 v[160:163], v151 offset:2048
	ds_read_b128 v[164:167], v151 offset:3072
	v_add_u32_e32 v151, s94, v147
	ds_read_b128 v[168:171], v151
	ds_read_b128 v[172:175], v151 offset:1024
	ds_read_b128 v[176:179], v151 offset:2048
	ds_read_b128 v[180:183], v151 offset:3072
	s_add_u32 s58, s58, 0x10000
	s_addc_u32 s59, s59, 0
	s_mov_b32 m0, s66
	v_lshl_add_u64 v[226:227], s[58:59], 0, v[134:135]
	ds_read_b128 v[184:187], v150 offset:32768
	ds_read_b128 v[188:191], v150 offset:33792
	ds_read_b128 v[192:195], v150 offset:34816
	ds_read_b128 v[196:199], v150 offset:35840
	ds_read_b128 v[202:205], v150 offset:36864
	ds_read_b128 v[206:209], v150 offset:37888
	ds_read_b128 v[210:213], v150 offset:38912
	ds_read_b128 v[214:217], v150 offset:39936
	global_load_lds_dwordx4 v[226:227], off
	v_lshl_add_u64 v[226:227], s[58:59], 0, v[130:131]
	s_mov_b32 m0, s67
	s_nop 0
	global_load_lds_dwordx4 v[226:227], off
	s_waitcnt vmcnt(8)
	s_waitcnt lgkmcnt(0)
	s_barrier
	s_setprio 1
	s_waitcnt lgkmcnt(0)
	v_mfma_f32_16x16x32_bf16 v[124:127], v[152:155], v[184:187], v[124:127]
	v_mfma_f32_16x16x32_bf16 v[120:123], v[160:163], v[184:187], v[120:123]
	v_mfma_f32_16x16x32_bf16 v[108:111], v[152:155], v[192:195], v[108:111]
	v_mfma_f32_16x16x32_bf16 v[104:107], v[160:163], v[192:195], v[104:107]
	v_mfma_f32_16x16x32_bf16 v[92:95], v[152:155], v[202:205], v[92:95]
	v_mfma_f32_16x16x32_bf16 v[88:91], v[160:163], v[202:205], v[88:91]
	v_mfma_f32_16x16x32_bf16 v[76:79], v[152:155], v[210:213], v[76:79]
	v_mfma_f32_16x16x32_bf16 v[72:75], v[160:163], v[210:213], v[72:75]
	v_mfma_f32_16x16x32_bf16 v[124:127], v[156:159], v[188:191], v[124:127]
	v_mfma_f32_16x16x32_bf16 v[120:123], v[164:167], v[188:191], v[120:123]
	v_mfma_f32_16x16x32_bf16 v[108:111], v[156:159], v[196:199], v[108:111]
	v_mfma_f32_16x16x32_bf16 v[104:107], v[164:167], v[196:199], v[104:107]
	v_mfma_f32_16x16x32_bf16 v[92:95], v[156:159], v[206:209], v[92:95]
	v_mfma_f32_16x16x32_bf16 v[88:91], v[164:167], v[206:209], v[88:91]
	v_mfma_f32_16x16x32_bf16 v[76:79], v[156:159], v[214:217], v[76:79]
	v_mfma_f32_16x16x32_bf16 v[72:75], v[164:167], v[214:217], v[72:75]
	s_setprio 0
	s_setprio 1
	v_mfma_f32_16x16x32_bf16 v[116:119], v[168:171], v[184:187], v[116:119]
	v_mfma_f32_16x16x32_bf16 v[112:115], v[176:179], v[184:187], v[112:115]
	v_mfma_f32_16x16x32_bf16 v[100:103], v[168:171], v[192:195], v[100:103]
	v_mfma_f32_16x16x32_bf16 v[96:99], v[176:179], v[192:195], v[96:99]
	v_mfma_f32_16x16x32_bf16 v[84:87], v[168:171], v[202:205], v[84:87]
	v_mfma_f32_16x16x32_bf16 v[80:83], v[176:179], v[202:205], v[80:83]
	v_mfma_f32_16x16x32_bf16 v[68:71], v[168:171], v[210:213], v[68:71]
	v_mfma_f32_16x16x32_bf16 v[64:67], v[176:179], v[210:213], v[64:67]
	v_mfma_f32_16x16x32_bf16 v[116:119], v[172:175], v[188:191], v[116:119]
	v_mfma_f32_16x16x32_bf16 v[112:115], v[180:183], v[188:191], v[112:115]
	v_mfma_f32_16x16x32_bf16 v[100:103], v[172:175], v[196:199], v[100:103]
	v_mfma_f32_16x16x32_bf16 v[96:99], v[180:183], v[196:199], v[96:99]
	v_mfma_f32_16x16x32_bf16 v[84:87], v[172:175], v[206:209], v[84:87]
	v_mfma_f32_16x16x32_bf16 v[80:83], v[180:183], v[206:209], v[80:83]
	v_mfma_f32_16x16x32_bf16 v[68:71], v[172:175], v[214:217], v[68:71]
	v_mfma_f32_16x16x32_bf16 v[64:67], v[180:183], v[214:217], v[64:67]
	s_setprio 0
	s_barrier
	s_add_i32 s58, s93, s61
	v_lshl_add_u64 v[218:219], v[218:219], 0, s[8:9]
	s_mov_b32 m0, s58
	ds_read_b128 v[184:187], v150 offset:49152
	ds_read_b128 v[188:191], v150 offset:50176
	ds_read_b128 v[192:195], v150 offset:51200
	ds_read_b128 v[196:199], v150 offset:52224
	ds_read_b128 v[202:205], v150 offset:53248
	ds_read_b128 v[206:209], v150 offset:54272
	ds_read_b128 v[210:213], v150 offset:55296
	ds_read_b128 v[214:217], v150 offset:56320
	global_load_lds_dwordx4 v[218:219], off
	s_add_i32 m0, s58, 0x2000
	s_add_u32 s56, s56, 0x10080
	v_lshl_add_u64 v[218:219], v[220:221], 0, s[8:9]
	s_addc_u32 s57, s57, 0
	s_add_i32 s58, s94, s61
	global_load_lds_dwordx4 v[218:219], off
	v_lshl_add_u64 v[218:219], s[56:57], 0, v[132:133]
	s_mov_b32 m0, s58
	s_nop 0
	global_load_lds_dwordx4 v[218:219], off
	v_lshl_add_u64 v[218:219], s[56:57], 0, v[128:129]
	s_add_i32 m0, s58, 0x2000
	s_nop 0
	global_load_lds_dwordx4 v[218:219], off
	v_lshl_add_u64 v[218:219], v[222:223], 0, s[8:9]
	s_mov_b32 m0, s77
	s_nop 0
	global_load_lds_dwordx4 v[218:219], off
	v_lshl_add_u64 v[218:219], v[224:225], 0, s[8:9]
	s_mov_b32 m0, s78
	s_nop 0
	global_load_lds_dwordx4 v[218:219], off
	s_waitcnt vmcnt(8)
	s_waitcnt lgkmcnt(0)
	s_barrier
	s_setprio 1
	s_waitcnt lgkmcnt(0)
	v_mfma_f32_16x16x32_bf16 v[60:63], v[152:155], v[184:187], v[60:63]
	v_mfma_f32_16x16x32_bf16 v[56:59], v[160:163], v[184:187], v[56:59]
	v_mfma_f32_16x16x32_bf16 v[44:47], v[152:155], v[192:195], v[44:47]
	v_mfma_f32_16x16x32_bf16 v[40:43], v[160:163], v[192:195], v[40:43]
	v_mfma_f32_16x16x32_bf16 v[28:31], v[152:155], v[202:205], v[28:31]
	v_mfma_f32_16x16x32_bf16 v[24:27], v[160:163], v[202:205], v[24:27]
	v_mfma_f32_16x16x32_bf16 v[12:15], v[152:155], v[210:213], v[12:15]
	v_mfma_f32_16x16x32_bf16 v[8:11], v[160:163], v[210:213], v[8:11]
	v_mfma_f32_16x16x32_bf16 v[60:63], v[156:159], v[188:191], v[60:63]
	v_mfma_f32_16x16x32_bf16 v[56:59], v[164:167], v[188:191], v[56:59]
	v_mfma_f32_16x16x32_bf16 v[44:47], v[156:159], v[196:199], v[44:47]
	v_mfma_f32_16x16x32_bf16 v[40:43], v[164:167], v[196:199], v[40:43]
	v_mfma_f32_16x16x32_bf16 v[28:31], v[156:159], v[206:209], v[28:31]
	v_mfma_f32_16x16x32_bf16 v[24:27], v[164:167], v[206:209], v[24:27]
	v_mfma_f32_16x16x32_bf16 v[12:15], v[156:159], v[214:217], v[12:15]
	v_mfma_f32_16x16x32_bf16 v[8:11], v[164:167], v[214:217], v[8:11]
	s_setprio 0
	s_setprio 1
	v_mfma_f32_16x16x32_bf16 v[52:55], v[168:171], v[184:187], v[52:55]
	v_mfma_f32_16x16x32_bf16 v[48:51], v[176:179], v[184:187], v[48:51]
	v_mfma_f32_16x16x32_bf16 v[36:39], v[168:171], v[192:195], v[36:39]
	v_mfma_f32_16x16x32_bf16 v[32:35], v[176:179], v[192:195], v[32:35]
	v_mfma_f32_16x16x32_bf16 v[20:23], v[168:171], v[202:205], v[20:23]
	v_mfma_f32_16x16x32_bf16 v[16:19], v[176:179], v[202:205], v[16:19]
	v_mfma_f32_16x16x32_bf16 v[4:7], v[168:171], v[210:213], v[4:7]
	v_mfma_f32_16x16x32_bf16 v[0:3], v[176:179], v[210:213], v[0:3]
	v_mfma_f32_16x16x32_bf16 v[52:55], v[172:175], v[188:191], v[52:55]
	v_mfma_f32_16x16x32_bf16 v[48:51], v[180:183], v[188:191], v[48:51]
	v_mfma_f32_16x16x32_bf16 v[36:39], v[172:175], v[196:199], v[36:39]
	v_mfma_f32_16x16x32_bf16 v[32:35], v[180:183], v[196:199], v[32:35]
	v_mfma_f32_16x16x32_bf16 v[20:23], v[172:175], v[206:209], v[20:23]
	v_mfma_f32_16x16x32_bf16 v[16:19], v[180:183], v[206:209], v[16:19]
	v_mfma_f32_16x16x32_bf16 v[4:7], v[172:175], v[214:217], v[4:7]
	v_mfma_f32_16x16x32_bf16 v[0:3], v[180:183], v[214:217], v[0:3]
	s_setprio 0
	s_add_u32 s52, s52, 0x100
	s_addc_u32 s53, s53, 0
	s_add_u32 s90, s90, 0x100
	s_addc_u32 s91, s91, 0
	s_cmp_ge_i32 s92, s34
	s_mov_b32 s56, s92
	s_barrier
	s_cbranch_scc0 .LBB0_918
	s_and_b64 vcc, exec, s[22:23]
	s_cbranch_vccz .LBB0_921

.LBB0_940:
	ds_read_b128 v[152:155], v148
	ds_read_b128 v[156:159], v148 offset:1024
	ds_read_b128 v[160:163], v148 offset:2048
	ds_read_b128 v[164:167], v148 offset:3072
	ds_read_b128 v[168:171], v149
	ds_read_b128 v[172:175], v149 offset:1024
	ds_read_b128 v[176:179], v149 offset:2048
	ds_read_b128 v[180:183], v149 offset:3072
	s_add_i32 s91, s56, 2
	s_add_u32 s57, s52, 0xffff0080
	s_addc_u32 s58, s53, -1
	s_cmp_eq_u32 s78, s56
	s_cselect_b32 s56, s88, s89
	s_cselect_b32 s59, s23, s58
	s_cselect_b32 s58, s25, s57
	s_cselect_b32 s57, s87, s90
	v_lshl_add_u64 v[218:219], s[52:53], 0, v[138:139]
	s_add_i32 m0, s63, 0xc000
	ds_read_b128 v[184:187], v150
	ds_read_b128 v[188:191], v150 offset:1024
	ds_read_b128 v[192:195], v150 offset:2048
	ds_read_b128 v[196:199], v150 offset:3072
	ds_read_b128 v[202:205], v150 offset:4096
	ds_read_b128 v[206:209], v150 offset:5120
	ds_read_b128 v[210:213], v150 offset:6144
	ds_read_b128 v[214:217], v150 offset:7168
	global_load_lds_dwordx4 v[218:219], off
	v_lshl_add_u64 v[218:219], s[52:53], 0, v[140:141]
	s_add_i32 m0, s63, 0xe000
	s_nop 0
	global_load_lds_dwordx4 v[218:219], off
	s_waitcnt vmcnt(8)
	s_waitcnt lgkmcnt(0)
	s_barrier
	s_setprio 1
	s_waitcnt lgkmcnt(0)
	v_mfma_f32_16x16x32_bf16 v[124:127], v[152:155], v[184:187], v[124:127]
	v_mfma_f32_16x16x32_bf16 v[120:123], v[160:163], v[184:187], v[120:123]
	v_mfma_f32_16x16x32_bf16 v[108:111], v[152:155], v[192:195], v[108:111]
	v_mfma_f32_16x16x32_bf16 v[104:107], v[160:163], v[192:195], v[104:107]
	v_mfma_f32_16x16x32_bf16 v[92:95], v[152:155], v[202:205], v[92:95]
	v_mfma_f32_16x16x32_bf16 v[88:91], v[160:163], v[202:205], v[88:91]
	v_mfma_f32_16x16x32_bf16 v[76:79], v[152:155], v[210:213], v[76:79]
	v_mfma_f32_16x16x32_bf16 v[72:75], v[160:163], v[210:213], v[72:75]
	v_mfma_f32_16x16x32_bf16 v[124:127], v[156:159], v[188:191], v[124:127]
	v_mfma_f32_16x16x32_bf16 v[120:123], v[164:167], v[188:191], v[120:123]
	v_mfma_f32_16x16x32_bf16 v[108:111], v[156:159], v[196:199], v[108:111]
	v_mfma_f32_16x16x32_bf16 v[104:107], v[164:167], v[196:199], v[104:107]
	v_mfma_f32_16x16x32_bf16 v[92:95], v[156:159], v[206:209], v[92:95]
	v_mfma_f32_16x16x32_bf16 v[88:91], v[164:167], v[206:209], v[88:91]
	v_mfma_f32_16x16x32_bf16 v[76:79], v[156:159], v[214:217], v[76:79]
	v_mfma_f32_16x16x32_bf16 v[72:75], v[164:167], v[214:217], v[72:75]
	s_setprio 0
	s_setprio 1
	v_mfma_f32_16x16x32_bf16 v[116:119], v[168:171], v[184:187], v[116:119]
	v_mfma_f32_16x16x32_bf16 v[112:115], v[176:179], v[184:187], v[112:115]
	v_mfma_f32_16x16x32_bf16 v[100:103], v[168:171], v[192:195], v[100:103]
	v_mfma_f32_16x16x32_bf16 v[96:99], v[176:179], v[192:195], v[96:99]
	v_mfma_f32_16x16x32_bf16 v[84:87], v[168:171], v[202:205], v[84:87]
	v_mfma_f32_16x16x32_bf16 v[80:83], v[176:179], v[202:205], v[80:83]
	v_mfma_f32_16x16x32_bf16 v[68:71], v[168:171], v[210:213], v[68:71]
	v_mfma_f32_16x16x32_bf16 v[64:67], v[176:179], v[210:213], v[64:67]
	v_mfma_f32_16x16x32_bf16 v[116:119], v[172:175], v[188:191], v[116:119]
	v_mfma_f32_16x16x32_bf16 v[112:115], v[180:183], v[188:191], v[112:115]
	v_mfma_f32_16x16x32_bf16 v[100:103], v[172:175], v[196:199], v[100:103]
	v_mfma_f32_16x16x32_bf16 v[96:99], v[180:183], v[196:199], v[96:99]
	v_mfma_f32_16x16x32_bf16 v[84:87], v[172:175], v[206:209], v[84:87]
	v_mfma_f32_16x16x32_bf16 v[80:83], v[180:183], v[206:209], v[80:83]
	v_mfma_f32_16x16x32_bf16 v[68:71], v[172:175], v[214:217], v[68:71]
	v_mfma_f32_16x16x32_bf16 v[64:67], v[180:183], v[214:217], v[64:67]
	s_setprio 0
	s_barrier
	s_add_i32 s92, s80, s62
	v_lshl_add_u64 v[218:219], s[56:57], 0, v[132:133]
	s_mov_b32 m0, s92
	ds_read_b128 v[184:187], v150 offset:16384
	ds_read_b128 v[188:191], v150 offset:17408
	ds_read_b128 v[192:195], v150 offset:18432
	ds_read_b128 v[196:199], v150 offset:19456
	ds_read_b128 v[202:205], v150 offset:20480
	ds_read_b128 v[206:209], v150 offset:21504
	ds_read_b128 v[210:213], v150 offset:22528
	ds_read_b128 v[214:217], v150 offset:23552
	global_load_lds_dwordx4 v[218:219], off
	s_add_i32 m0, s92, 0x2000
	s_add_u32 s92, s56, 0x10000
	v_lshl_add_u64 v[220:221], s[56:57], 0, v[128:129]
	s_addc_u32 s93, s57, 0
	s_add_i32 s94, s81, s62
	global_load_lds_dwordx4 v[220:221], off
	v_lshl_add_u64 v[222:223], s[92:93], 0, v[132:133]
	s_mov_b32 m0, s94
	v_lshl_add_u64 v[224:225], s[58:59], 0, v[130:131]
	global_load_lds_dwordx4 v[222:223], off
	v_lshl_add_u64 v[222:223], s[92:93], 0, v[128:129]
	s_add_i32 m0, s94, 0x2000
	s_nop 0
	global_load_lds_dwordx4 v[222:223], off
	v_lshl_add_u64 v[222:223], s[58:59], 0, v[134:135]
	s_mov_b32 m0, s63
	s_nop 0
	global_load_lds_dwordx4 v[222:223], off
	s_mov_b32 m0, s64
	s_nop 0
	global_load_lds_dwordx4 v[224:225], off
	s_waitcnt vmcnt(8)
	s_waitcnt lgkmcnt(0)
	s_barrier
	s_setprio 1
	s_waitcnt lgkmcnt(0)
	v_mfma_f32_16x16x32_bf16 v[60:63], v[152:155], v[184:187], v[60:63]
	v_mfma_f32_16x16x32_bf16 v[56:59], v[160:163], v[184:187], v[56:59]
	v_mfma_f32_16x16x32_bf16 v[44:47], v[152:155], v[192:195], v[44:47]
	v_mfma_f32_16x16x32_bf16 v[40:43], v[160:163], v[192:195], v[40:43]
	v_mfma_f32_16x16x32_bf16 v[28:31], v[152:155], v[202:205], v[28:31]
	v_mfma_f32_16x16x32_bf16 v[24:27], v[160:163], v[202:205], v[24:27]
	v_mfma_f32_16x16x32_bf16 v[12:15], v[152:155], v[210:213], v[12:15]
	v_mfma_f32_16x16x32_bf16 v[8:11], v[160:163], v[210:213], v[8:11]
	v_mfma_f32_16x16x32_bf16 v[60:63], v[156:159], v[188:191], v[60:63]
	v_mfma_f32_16x16x32_bf16 v[56:59], v[164:167], v[188:191], v[56:59]
	v_mfma_f32_16x16x32_bf16 v[44:47], v[156:159], v[196:199], v[44:47]
	v_mfma_f32_16x16x32_bf16 v[40:43], v[164:167], v[196:199], v[40:43]
	v_mfma_f32_16x16x32_bf16 v[28:31], v[156:159], v[206:209], v[28:31]
	v_mfma_f32_16x16x32_bf16 v[24:27], v[164:167], v[206:209], v[24:27]
	v_mfma_f32_16x16x32_bf16 v[12:15], v[156:159], v[214:217], v[12:15]
	v_mfma_f32_16x16x32_bf16 v[8:11], v[164:167], v[214:217], v[8:11]
	s_setprio 0
	s_setprio 1
	v_mfma_f32_16x16x32_bf16 v[52:55], v[168:171], v[184:187], v[52:55]
	v_mfma_f32_16x16x32_bf16 v[48:51], v[176:179], v[184:187], v[48:51]
	v_mfma_f32_16x16x32_bf16 v[36:39], v[168:171], v[192:195], v[36:39]
	v_mfma_f32_16x16x32_bf16 v[32:35], v[176:179], v[192:195], v[32:35]
	v_mfma_f32_16x16x32_bf16 v[20:23], v[168:171], v[202:205], v[20:23]
	v_mfma_f32_16x16x32_bf16 v[16:19], v[176:179], v[202:205], v[16:19]
	v_mfma_f32_16x16x32_bf16 v[4:7], v[168:171], v[210:213], v[4:7]
	v_mfma_f32_16x16x32_bf16 v[0:3], v[176:179], v[210:213], v[0:3]
	v_mfma_f32_16x16x32_bf16 v[52:55], v[172:175], v[188:191], v[52:55]
	v_mfma_f32_16x16x32_bf16 v[48:51], v[180:183], v[188:191], v[48:51]
	v_mfma_f32_16x16x32_bf16 v[36:39], v[172:175], v[196:199], v[36:39]
	v_mfma_f32_16x16x32_bf16 v[32:35], v[180:183], v[196:199], v[32:35]
	v_mfma_f32_16x16x32_bf16 v[20:23], v[172:175], v[206:209], v[20:23]
	v_mfma_f32_16x16x32_bf16 v[16:19], v[180:183], v[206:209], v[16:19]
	v_mfma_f32_16x16x32_bf16 v[4:7], v[172:175], v[214:217], v[4:7]
	v_mfma_f32_16x16x32_bf16 v[0:3], v[180:183], v[214:217], v[0:3]
	s_setprio 0
	s_barrier
	s_add_i32 s92, 0, 0x18000
	v_add_u32_e32 v151, s92, v147
	s_add_i32 s93, 0, 0x1c000
	ds_read_b128 v[152:155], v151
	ds_read_b128 v[156:159], v151 offset:1024
	ds_read_b128 v[160:163], v151 offset:2048
	ds_read_b128 v[164:167], v151 offset:3072
	v_add_u32_e32 v151, s93, v147
	ds_read_b128 v[168:171], v151
	ds_read_b128 v[172:175], v151 offset:1024
	ds_read_b128 v[176:179], v151 offset:2048
	ds_read_b128 v[180:183], v151 offset:3072
	s_add_u32 s58, s58, 0x10000
	s_addc_u32 s59, s59, 0
	s_mov_b32 m0, s65
	v_lshl_add_u64 v[226:227], s[58:59], 0, v[134:135]
	ds_read_b128 v[184:187], v150 offset:32768
	ds_read_b128 v[188:191], v150 offset:33792
	ds_read_b128 v[192:195], v150 offset:34816
	ds_read_b128 v[196:199], v150 offset:35840
	ds_read_b128 v[202:205], v150 offset:36864
	ds_read_b128 v[206:209], v150 offset:37888
	ds_read_b128 v[210:213], v150 offset:38912
	ds_read_b128 v[214:217], v150 offset:39936
	global_load_lds_dwordx4 v[226:227], off
	v_lshl_add_u64 v[226:227], s[58:59], 0, v[130:131]
	s_mov_b32 m0, s66
	s_nop 0
	global_load_lds_dwordx4 v[226:227], off
	s_waitcnt vmcnt(8)
	s_waitcnt lgkmcnt(0)
	s_barrier
	s_setprio 1
	s_waitcnt lgkmcnt(0)
	v_mfma_f32_16x16x32_bf16 v[124:127], v[152:155], v[184:187], v[124:127]
	v_mfma_f32_16x16x32_bf16 v[120:123], v[160:163], v[184:187], v[120:123]
	v_mfma_f32_16x16x32_bf16 v[108:111], v[152:155], v[192:195], v[108:111]
	v_mfma_f32_16x16x32_bf16 v[104:107], v[160:163], v[192:195], v[104:107]
	v_mfma_f32_16x16x32_bf16 v[92:95], v[152:155], v[202:205], v[92:95]
	v_mfma_f32_16x16x32_bf16 v[88:91], v[160:163], v[202:205], v[88:91]
	v_mfma_f32_16x16x32_bf16 v[76:79], v[152:155], v[210:213], v[76:79]
	v_mfma_f32_16x16x32_bf16 v[72:75], v[160:163], v[210:213], v[72:75]
	v_mfma_f32_16x16x32_bf16 v[124:127], v[156:159], v[188:191], v[124:127]
	v_mfma_f32_16x16x32_bf16 v[120:123], v[164:167], v[188:191], v[120:123]
	v_mfma_f32_16x16x32_bf16 v[108:111], v[156:159], v[196:199], v[108:111]
	v_mfma_f32_16x16x32_bf16 v[104:107], v[164:167], v[196:199], v[104:107]
	v_mfma_f32_16x16x32_bf16 v[92:95], v[156:159], v[206:209], v[92:95]
	v_mfma_f32_16x16x32_bf16 v[88:91], v[164:167], v[206:209], v[88:91]
	v_mfma_f32_16x16x32_bf16 v[76:79], v[156:159], v[214:217], v[76:79]
	v_mfma_f32_16x16x32_bf16 v[72:75], v[164:167], v[214:217], v[72:75]
	s_setprio 0
	s_setprio 1
	v_mfma_f32_16x16x32_bf16 v[116:119], v[168:171], v[184:187], v[116:119]
	v_mfma_f32_16x16x32_bf16 v[112:115], v[176:179], v[184:187], v[112:115]
	v_mfma_f32_16x16x32_bf16 v[100:103], v[168:171], v[192:195], v[100:103]
	v_mfma_f32_16x16x32_bf16 v[96:99], v[176:179], v[192:195], v[96:99]
	v_mfma_f32_16x16x32_bf16 v[84:87], v[168:171], v[202:205], v[84:87]
	v_mfma_f32_16x16x32_bf16 v[80:83], v[176:179], v[202:205], v[80:83]
	v_mfma_f32_16x16x32_bf16 v[68:71], v[168:171], v[210:213], v[68:71]
	v_mfma_f32_16x16x32_bf16 v[64:67], v[176:179], v[210:213], v[64:67]
	v_mfma_f32_16x16x32_bf16 v[116:119], v[172:175], v[188:191], v[116:119]
	v_mfma_f32_16x16x32_bf16 v[112:115], v[180:183], v[188:191], v[112:115]
	v_mfma_f32_16x16x32_bf16 v[100:103], v[172:175], v[196:199], v[100:103]
	v_mfma_f32_16x16x32_bf16 v[96:99], v[180:183], v[196:199], v[96:99]
	v_mfma_f32_16x16x32_bf16 v[84:87], v[172:175], v[206:209], v[84:87]
	v_mfma_f32_16x16x32_bf16 v[80:83], v[180:183], v[206:209], v[80:83]
	v_mfma_f32_16x16x32_bf16 v[68:71], v[172:175], v[214:217], v[68:71]
	v_mfma_f32_16x16x32_bf16 v[64:67], v[180:183], v[214:217], v[64:67]
	s_setprio 0
	s_barrier
	s_add_i32 s58, s92, s62
	v_lshl_add_u64 v[218:219], v[218:219], 0, s[6:7]
	s_mov_b32 m0, s58
	ds_read_b128 v[184:187], v150 offset:49152
	ds_read_b128 v[188:191], v150 offset:50176
	ds_read_b128 v[192:195], v150 offset:51200
	ds_read_b128 v[196:199], v150 offset:52224
	ds_read_b128 v[202:205], v150 offset:53248
	ds_read_b128 v[206:209], v150 offset:54272
	ds_read_b128 v[210:213], v150 offset:55296
	ds_read_b128 v[214:217], v150 offset:56320
	global_load_lds_dwordx4 v[218:219], off
	s_add_i32 m0, s58, 0x2000
	s_add_u32 s56, s56, 0x10080
	v_lshl_add_u64 v[218:219], v[220:221], 0, s[6:7]
	s_addc_u32 s57, s57, 0
	s_add_i32 s58, s93, s62
	global_load_lds_dwordx4 v[218:219], off
	v_lshl_add_u64 v[218:219], s[56:57], 0, v[132:133]
	s_mov_b32 m0, s58
	s_nop 0
	global_load_lds_dwordx4 v[218:219], off
	v_lshl_add_u64 v[218:219], s[56:57], 0, v[128:129]
	s_add_i32 m0, s58, 0x2000
	s_nop 0
	global_load_lds_dwordx4 v[218:219], off
	v_lshl_add_u64 v[218:219], v[222:223], 0, s[6:7]
	s_mov_b32 m0, s76
	s_nop 0
	global_load_lds_dwordx4 v[218:219], off
	v_lshl_add_u64 v[218:219], v[224:225], 0, s[6:7]
	s_mov_b32 m0, s77
	s_nop 0
	global_load_lds_dwordx4 v[218:219], off
	s_waitcnt vmcnt(8)
	s_waitcnt lgkmcnt(0)
	s_barrier
	s_setprio 1
	s_waitcnt lgkmcnt(0)
	v_mfma_f32_16x16x32_bf16 v[60:63], v[152:155], v[184:187], v[60:63]
	v_mfma_f32_16x16x32_bf16 v[56:59], v[160:163], v[184:187], v[56:59]
	v_mfma_f32_16x16x32_bf16 v[44:47], v[152:155], v[192:195], v[44:47]
	v_mfma_f32_16x16x32_bf16 v[40:43], v[160:163], v[192:195], v[40:43]
	v_mfma_f32_16x16x32_bf16 v[28:31], v[152:155], v[202:205], v[28:31]
	v_mfma_f32_16x16x32_bf16 v[24:27], v[160:163], v[202:205], v[24:27]
	v_mfma_f32_16x16x32_bf16 v[12:15], v[152:155], v[210:213], v[12:15]
	v_mfma_f32_16x16x32_bf16 v[8:11], v[160:163], v[210:213], v[8:11]
	v_mfma_f32_16x16x32_bf16 v[60:63], v[156:159], v[188:191], v[60:63]
	v_mfma_f32_16x16x32_bf16 v[56:59], v[164:167], v[188:191], v[56:59]
	v_mfma_f32_16x16x32_bf16 v[44:47], v[156:159], v[196:199], v[44:47]
	v_mfma_f32_16x16x32_bf16 v[40:43], v[164:167], v[196:199], v[40:43]
	v_mfma_f32_16x16x32_bf16 v[28:31], v[156:159], v[206:209], v[28:31]
	v_mfma_f32_16x16x32_bf16 v[24:27], v[164:167], v[206:209], v[24:27]
	v_mfma_f32_16x16x32_bf16 v[12:15], v[156:159], v[214:217], v[12:15]
	v_mfma_f32_16x16x32_bf16 v[8:11], v[164:167], v[214:217], v[8:11]
	s_setprio 0
	s_setprio 1
	v_mfma_f32_16x16x32_bf16 v[52:55], v[168:171], v[184:187], v[52:55]
	v_mfma_f32_16x16x32_bf16 v[48:51], v[176:179], v[184:187], v[48:51]
	v_mfma_f32_16x16x32_bf16 v[36:39], v[168:171], v[192:195], v[36:39]
	v_mfma_f32_16x16x32_bf16 v[32:35], v[176:179], v[192:195], v[32:35]
	v_mfma_f32_16x16x32_bf16 v[20:23], v[168:171], v[202:205], v[20:23]
	v_mfma_f32_16x16x32_bf16 v[16:19], v[176:179], v[202:205], v[16:19]
	v_mfma_f32_16x16x32_bf16 v[4:7], v[168:171], v[210:213], v[4:7]
	v_mfma_f32_16x16x32_bf16 v[0:3], v[176:179], v[210:213], v[0:3]
	v_mfma_f32_16x16x32_bf16 v[52:55], v[172:175], v[188:191], v[52:55]
	v_mfma_f32_16x16x32_bf16 v[48:51], v[180:183], v[188:191], v[48:51]
	v_mfma_f32_16x16x32_bf16 v[36:39], v[172:175], v[196:199], v[36:39]
	v_mfma_f32_16x16x32_bf16 v[32:35], v[180:183], v[196:199], v[32:35]
	v_mfma_f32_16x16x32_bf16 v[20:23], v[172:175], v[206:209], v[20:23]
	v_mfma_f32_16x16x32_bf16 v[16:19], v[180:183], v[206:209], v[16:19]
	v_mfma_f32_16x16x32_bf16 v[4:7], v[172:175], v[214:217], v[4:7]
	v_mfma_f32_16x16x32_bf16 v[0:3], v[180:183], v[214:217], v[0:3]
	s_setprio 0
	s_add_u32 s52, s52, 0x100
	s_addc_u32 s53, s53, 0
	s_add_u32 s89, s89, 0x100
	s_addc_u32 s90, s90, 0
	s_cmp_ge_i32 s91, s33
	s_mov_b32 s56, s91
	s_barrier
	s_cbranch_scc0 .LBB0_940
	s_and_b64 vcc, exec, s[10:11]
	s_cbranch_vccz .LBB0_943

.LBB0_1373:
	v_add_u32_e32 v132, s64, v147
	ds_read_b128 v[142:145], v132
	ds_read_b128 v[150:153], v132 offset:1024
	ds_read_b128 v[154:157], v132 offset:2048
	ds_read_b128 v[158:161], v132 offset:3072
	v_add_u32_e32 v132, s65, v147
	ds_read_b128 v[162:165], v132
	ds_read_b128 v[166:169], v132 offset:1024
	ds_read_b128 v[170:173], v132 offset:2048
	ds_read_b128 v[174:177], v132 offset:3072
	s_add_i32 s79, s58, 2
	s_add_u32 s59, s56, 0xfff80080
	s_addc_u32 s60, s57, -1
	s_cmp_eq_u32 s63, s58
	s_cselect_b32 s58, s76, s77
	s_cselect_b32 s61, s25, s60
	s_cselect_b32 s60, s27, s59
	s_cselect_b32 s59, s67, s78
	v_lshl_add_u64 v[198:199], s[56:57], 0, v[134:135]
	s_add_i32 m0, s33, 0xc000
	ds_read_b128 v[178:181], v149
	ds_read_b128 v[182:185], v149 offset:1024
	ds_read_b128 v[186:189], v149 offset:2048
	ds_read_b128 v[190:193], v149 offset:3072
	ds_read_b128 v[194:197], v149 offset:4096
	ds_read_b128 v[202:205], v149 offset:5120
	ds_read_b128 v[206:209], v149 offset:6144
	ds_read_b128 v[210:213], v149 offset:7168
	global_load_lds_dwordx4 v[198:199], off
	v_lshl_add_u64 v[198:199], s[56:57], 0, v[136:137]
	s_add_i32 m0, s33, 0xe000
	s_nop 0
	global_load_lds_dwordx4 v[198:199], off
	s_waitcnt vmcnt(8)
	s_waitcnt lgkmcnt(0)
	s_barrier
	s_setprio 1
	s_waitcnt lgkmcnt(0)
	v_mfma_i32_16x16x64_i8 v[124:127], v[142:145], v[178:181], v[124:127]
	v_mfma_i32_16x16x64_i8 v[120:123], v[154:157], v[178:181], v[120:123]
	v_mfma_i32_16x16x64_i8 v[108:111], v[142:145], v[186:189], v[108:111]
	v_mfma_i32_16x16x64_i8 v[104:107], v[154:157], v[186:189], v[104:107]
	v_mfma_i32_16x16x64_i8 v[92:95], v[142:145], v[194:197], v[92:95]
	v_mfma_i32_16x16x64_i8 v[88:91], v[154:157], v[194:197], v[88:91]
	v_mfma_i32_16x16x64_i8 v[76:79], v[142:145], v[206:209], v[76:79]
	v_mfma_i32_16x16x64_i8 v[72:75], v[154:157], v[206:209], v[72:75]
	v_mfma_i32_16x16x64_i8 v[124:127], v[150:153], v[182:185], v[124:127]
	v_mfma_i32_16x16x64_i8 v[120:123], v[158:161], v[182:185], v[120:123]
	v_mfma_i32_16x16x64_i8 v[108:111], v[150:153], v[190:193], v[108:111]
	v_mfma_i32_16x16x64_i8 v[104:107], v[158:161], v[190:193], v[104:107]
	v_mfma_i32_16x16x64_i8 v[92:95], v[150:153], v[202:205], v[92:95]
	v_mfma_i32_16x16x64_i8 v[88:91], v[158:161], v[202:205], v[88:91]
	v_mfma_i32_16x16x64_i8 v[76:79], v[150:153], v[210:213], v[76:79]
	v_mfma_i32_16x16x64_i8 v[72:75], v[158:161], v[210:213], v[72:75]
	s_setprio 0
	s_setprio 1
	v_mfma_i32_16x16x64_i8 v[116:119], v[162:165], v[178:181], v[116:119]
	v_mfma_i32_16x16x64_i8 v[112:115], v[170:173], v[178:181], v[112:115]
	v_mfma_i32_16x16x64_i8 v[100:103], v[162:165], v[186:189], v[100:103]
	v_mfma_i32_16x16x64_i8 v[96:99], v[170:173], v[186:189], v[96:99]
	v_mfma_i32_16x16x64_i8 v[84:87], v[162:165], v[194:197], v[84:87]
	v_mfma_i32_16x16x64_i8 v[80:83], v[170:173], v[194:197], v[80:83]
	v_mfma_i32_16x16x64_i8 v[68:71], v[162:165], v[206:209], v[68:71]
	v_mfma_i32_16x16x64_i8 v[64:67], v[170:173], v[206:209], v[64:67]
	v_mfma_i32_16x16x64_i8 v[116:119], v[166:169], v[182:185], v[116:119]
	v_mfma_i32_16x16x64_i8 v[112:115], v[174:177], v[182:185], v[112:115]
	v_mfma_i32_16x16x64_i8 v[100:103], v[166:169], v[190:193], v[100:103]
	v_mfma_i32_16x16x64_i8 v[96:99], v[174:177], v[190:193], v[96:99]
	v_mfma_i32_16x16x64_i8 v[84:87], v[166:169], v[202:205], v[84:87]
	v_mfma_i32_16x16x64_i8 v[80:83], v[174:177], v[202:205], v[80:83]
	v_mfma_i32_16x16x64_i8 v[68:71], v[166:169], v[210:213], v[68:71]
	v_mfma_i32_16x16x64_i8 v[64:67], v[174:177], v[210:213], v[64:67]
	s_setprio 0
	s_barrier
	s_add_i32 s80, s64, s31
	v_lshl_add_u64 v[198:199], s[58:59], 0, v[128:129]
	s_mov_b32 m0, s80
	ds_read_b128 v[178:181], v149 offset:16384
	ds_read_b128 v[182:185], v149 offset:17408
	ds_read_b128 v[186:189], v149 offset:18432
	ds_read_b128 v[190:193], v149 offset:19456
	ds_read_b128 v[194:197], v149 offset:20480
	ds_read_b128 v[202:205], v149 offset:21504
	ds_read_b128 v[206:209], v149 offset:22528
	ds_read_b128 v[210:213], v149 offset:23552
	global_load_lds_dwordx4 v[198:199], off
	s_add_i32 m0, s80, 0x2000
	s_add_u32 s80, s58, 0x80000
	v_lshl_add_u64 v[214:215], s[58:59], 0, v[130:131]
	s_addc_u32 s81, s59, 0
	s_add_i32 s82, s65, s31
	global_load_lds_dwordx4 v[214:215], off
	v_lshl_add_u64 v[216:217], s[80:81], 0, v[128:129]
	s_mov_b32 m0, s82
	v_lshl_add_u64 v[218:219], s[60:61], 0, v[130:131]
	global_load_lds_dwordx4 v[216:217], off
	v_lshl_add_u64 v[216:217], s[80:81], 0, v[130:131]
	s_add_i32 m0, s82, 0x2000
	s_nop 0
	global_load_lds_dwordx4 v[216:217], off
	v_lshl_add_u64 v[216:217], s[60:61], 0, v[128:129]
	s_mov_b32 m0, s33
	s_nop 0
	global_load_lds_dwordx4 v[216:217], off
	s_mov_b32 m0, s34
	s_nop 0
	global_load_lds_dwordx4 v[218:219], off
	s_waitcnt vmcnt(8)
	s_waitcnt lgkmcnt(0)
	s_barrier
	s_setprio 1
	s_waitcnt lgkmcnt(0)
	v_mfma_i32_16x16x64_i8 v[60:63], v[142:145], v[178:181], v[60:63]
	v_mfma_i32_16x16x64_i8 v[56:59], v[154:157], v[178:181], v[56:59]
	v_mfma_i32_16x16x64_i8 v[44:47], v[142:145], v[186:189], v[44:47]
	v_mfma_i32_16x16x64_i8 v[40:43], v[154:157], v[186:189], v[40:43]
	v_mfma_i32_16x16x64_i8 v[28:31], v[142:145], v[194:197], v[28:31]
	v_mfma_i32_16x16x64_i8 v[24:27], v[154:157], v[194:197], v[24:27]
	v_mfma_i32_16x16x64_i8 v[12:15], v[142:145], v[206:209], v[12:15]
	v_mfma_i32_16x16x64_i8 v[8:11], v[154:157], v[206:209], v[8:11]
	v_mfma_i32_16x16x64_i8 v[60:63], v[150:153], v[182:185], v[60:63]
	v_mfma_i32_16x16x64_i8 v[56:59], v[158:161], v[182:185], v[56:59]
	v_mfma_i32_16x16x64_i8 v[44:47], v[150:153], v[190:193], v[44:47]
	v_mfma_i32_16x16x64_i8 v[40:43], v[158:161], v[190:193], v[40:43]
	v_mfma_i32_16x16x64_i8 v[28:31], v[150:153], v[202:205], v[28:31]
	v_mfma_i32_16x16x64_i8 v[24:27], v[158:161], v[202:205], v[24:27]
	v_mfma_i32_16x16x64_i8 v[12:15], v[150:153], v[210:213], v[12:15]
	v_mfma_i32_16x16x64_i8 v[8:11], v[158:161], v[210:213], v[8:11]
	s_setprio 0
	s_setprio 1
	v_mfma_i32_16x16x64_i8 v[52:55], v[162:165], v[178:181], v[52:55]
	v_mfma_i32_16x16x64_i8 v[48:51], v[170:173], v[178:181], v[48:51]
	v_mfma_i32_16x16x64_i8 v[36:39], v[162:165], v[186:189], v[36:39]
	v_mfma_i32_16x16x64_i8 v[32:35], v[170:173], v[186:189], v[32:35]
	v_mfma_i32_16x16x64_i8 v[20:23], v[162:165], v[194:197], v[20:23]
	v_mfma_i32_16x16x64_i8 v[16:19], v[170:173], v[194:197], v[16:19]
	v_mfma_i32_16x16x64_i8 v[4:7], v[162:165], v[206:209], v[4:7]
	v_mfma_i32_16x16x64_i8 v[0:3], v[170:173], v[206:209], v[0:3]
	v_mfma_i32_16x16x64_i8 v[52:55], v[166:169], v[182:185], v[52:55]
	v_mfma_i32_16x16x64_i8 v[48:51], v[174:177], v[182:185], v[48:51]
	v_mfma_i32_16x16x64_i8 v[36:39], v[166:169], v[190:193], v[36:39]
	v_mfma_i32_16x16x64_i8 v[32:35], v[174:177], v[190:193], v[32:35]
	v_mfma_i32_16x16x64_i8 v[20:23], v[166:169], v[202:205], v[20:23]
	v_mfma_i32_16x16x64_i8 v[16:19], v[174:177], v[202:205], v[16:19]
	v_mfma_i32_16x16x64_i8 v[4:7], v[166:169], v[210:213], v[4:7]
	v_mfma_i32_16x16x64_i8 v[0:3], v[174:177], v[210:213], v[0:3]
	s_setprio 0
	s_barrier
	s_add_i32 s80, 0, 0x18000
	v_add_u32_e32 v132, s80, v147
	s_add_i32 s81, 0, 0x1c000
	ds_read_b128 v[142:145], v132
	ds_read_b128 v[150:153], v132 offset:1024
	ds_read_b128 v[154:157], v132 offset:2048
	ds_read_b128 v[158:161], v132 offset:3072
	v_add_u32_e32 v132, s81, v147
	ds_read_b128 v[162:165], v132
	ds_read_b128 v[166:169], v132 offset:1024
	ds_read_b128 v[170:173], v132 offset:2048
	ds_read_b128 v[174:177], v132 offset:3072
	s_add_u32 s60, s60, 0x80000
	s_addc_u32 s61, s61, 0
	s_mov_b32 m0, s35
	v_lshl_add_u64 v[220:221], s[60:61], 0, v[128:129]
	ds_read_b128 v[178:181], v149 offset:32768
	ds_read_b128 v[182:185], v149 offset:33792
	ds_read_b128 v[186:189], v149 offset:34816
	ds_read_b128 v[190:193], v149 offset:35840
	ds_read_b128 v[194:197], v149 offset:36864
	ds_read_b128 v[202:205], v149 offset:37888
	ds_read_b128 v[206:209], v149 offset:38912
	ds_read_b128 v[210:213], v149 offset:39936
	global_load_lds_dwordx4 v[220:221], off
	v_lshl_add_u64 v[220:221], s[60:61], 0, v[130:131]
	s_mov_b32 m0, s51
	s_nop 0
	global_load_lds_dwordx4 v[220:221], off
	s_waitcnt vmcnt(8)
	s_waitcnt lgkmcnt(0)
	s_barrier
	s_setprio 1
	s_waitcnt lgkmcnt(0)
	v_mfma_i32_16x16x64_i8 v[124:127], v[142:145], v[178:181], v[124:127]
	v_mfma_i32_16x16x64_i8 v[120:123], v[154:157], v[178:181], v[120:123]
	v_mfma_i32_16x16x64_i8 v[108:111], v[142:145], v[186:189], v[108:111]
	v_mfma_i32_16x16x64_i8 v[104:107], v[154:157], v[186:189], v[104:107]
	v_mfma_i32_16x16x64_i8 v[92:95], v[142:145], v[194:197], v[92:95]
	v_mfma_i32_16x16x64_i8 v[88:91], v[154:157], v[194:197], v[88:91]
	v_mfma_i32_16x16x64_i8 v[76:79], v[142:145], v[206:209], v[76:79]
	v_mfma_i32_16x16x64_i8 v[72:75], v[154:157], v[206:209], v[72:75]
	v_mfma_i32_16x16x64_i8 v[124:127], v[150:153], v[182:185], v[124:127]
	v_mfma_i32_16x16x64_i8 v[120:123], v[158:161], v[182:185], v[120:123]
	v_mfma_i32_16x16x64_i8 v[108:111], v[150:153], v[190:193], v[108:111]
	v_mfma_i32_16x16x64_i8 v[104:107], v[158:161], v[190:193], v[104:107]
	v_mfma_i32_16x16x64_i8 v[92:95], v[150:153], v[202:205], v[92:95]
	v_mfma_i32_16x16x64_i8 v[88:91], v[158:161], v[202:205], v[88:91]
	v_mfma_i32_16x16x64_i8 v[76:79], v[150:153], v[210:213], v[76:79]
	v_mfma_i32_16x16x64_i8 v[72:75], v[158:161], v[210:213], v[72:75]
	s_setprio 0
	s_setprio 1
	v_mfma_i32_16x16x64_i8 v[116:119], v[162:165], v[178:181], v[116:119]
	v_mfma_i32_16x16x64_i8 v[112:115], v[170:173], v[178:181], v[112:115]
	v_mfma_i32_16x16x64_i8 v[100:103], v[162:165], v[186:189], v[100:103]
	v_mfma_i32_16x16x64_i8 v[96:99], v[170:173], v[186:189], v[96:99]
	v_mfma_i32_16x16x64_i8 v[84:87], v[162:165], v[194:197], v[84:87]
	v_mfma_i32_16x16x64_i8 v[80:83], v[170:173], v[194:197], v[80:83]
	v_mfma_i32_16x16x64_i8 v[68:71], v[162:165], v[206:209], v[68:71]
	v_mfma_i32_16x16x64_i8 v[64:67], v[170:173], v[206:209], v[64:67]
	v_mfma_i32_16x16x64_i8 v[116:119], v[166:169], v[182:185], v[116:119]
	v_mfma_i32_16x16x64_i8 v[112:115], v[174:177], v[182:185], v[112:115]
	v_mfma_i32_16x16x64_i8 v[100:103], v[166:169], v[190:193], v[100:103]
	v_mfma_i32_16x16x64_i8 v[96:99], v[174:177], v[190:193], v[96:99]
	v_mfma_i32_16x16x64_i8 v[84:87], v[166:169], v[202:205], v[84:87]
	v_mfma_i32_16x16x64_i8 v[80:83], v[174:177], v[202:205], v[80:83]
	v_mfma_i32_16x16x64_i8 v[68:71], v[166:169], v[210:213], v[68:71]
	v_mfma_i32_16x16x64_i8 v[64:67], v[174:177], v[210:213], v[64:67]
	s_setprio 0
	s_barrier
	s_add_i32 s60, s80, s31
	v_lshl_add_u64 v[198:199], v[198:199], 0, s[12:13]
	s_mov_b32 m0, s60
	ds_read_b128 v[178:181], v149 offset:49152
	ds_read_b128 v[182:185], v149 offset:50176
	ds_read_b128 v[186:189], v149 offset:51200
	ds_read_b128 v[190:193], v149 offset:52224
	ds_read_b128 v[194:197], v149 offset:53248
	ds_read_b128 v[202:205], v149 offset:54272
	ds_read_b128 v[206:209], v149 offset:55296
	ds_read_b128 v[210:213], v149 offset:56320
	global_load_lds_dwordx4 v[198:199], off
	s_add_i32 m0, s60, 0x2000
	s_add_u32 s58, s58, 0x80080
	v_lshl_add_u64 v[198:199], v[214:215], 0, s[12:13]
	s_addc_u32 s59, s59, 0
	s_add_i32 s60, s81, s31
	global_load_lds_dwordx4 v[198:199], off
	v_lshl_add_u64 v[198:199], s[58:59], 0, v[128:129]
	s_mov_b32 m0, s60
	s_nop 0
	global_load_lds_dwordx4 v[198:199], off
	v_lshl_add_u64 v[198:199], s[58:59], 0, v[130:131]
	s_add_i32 m0, s60, 0x2000
	s_nop 0
	global_load_lds_dwordx4 v[198:199], off
	v_lshl_add_u64 v[198:199], v[216:217], 0, s[12:13]
	s_mov_b32 m0, s53
	s_nop 0
	global_load_lds_dwordx4 v[198:199], off
	v_lshl_add_u64 v[198:199], v[218:219], 0, s[12:13]
	s_mov_b32 m0, s62
	s_nop 0
	global_load_lds_dwordx4 v[198:199], off
	s_waitcnt vmcnt(8)
	s_waitcnt lgkmcnt(0)
	s_barrier
	s_setprio 1
	s_waitcnt lgkmcnt(0)
	v_mfma_i32_16x16x64_i8 v[60:63], v[142:145], v[178:181], v[60:63]
	v_mfma_i32_16x16x64_i8 v[56:59], v[154:157], v[178:181], v[56:59]
	v_mfma_i32_16x16x64_i8 v[44:47], v[142:145], v[186:189], v[44:47]
	v_mfma_i32_16x16x64_i8 v[40:43], v[154:157], v[186:189], v[40:43]
	v_mfma_i32_16x16x64_i8 v[28:31], v[142:145], v[194:197], v[28:31]
	v_mfma_i32_16x16x64_i8 v[24:27], v[154:157], v[194:197], v[24:27]
	v_mfma_i32_16x16x64_i8 v[12:15], v[142:145], v[206:209], v[12:15]
	v_mfma_i32_16x16x64_i8 v[8:11], v[154:157], v[206:209], v[8:11]
	v_mfma_i32_16x16x64_i8 v[60:63], v[150:153], v[182:185], v[60:63]
	v_mfma_i32_16x16x64_i8 v[56:59], v[158:161], v[182:185], v[56:59]
	v_mfma_i32_16x16x64_i8 v[44:47], v[150:153], v[190:193], v[44:47]
	v_mfma_i32_16x16x64_i8 v[40:43], v[158:161], v[190:193], v[40:43]
	v_mfma_i32_16x16x64_i8 v[28:31], v[150:153], v[202:205], v[28:31]
	v_mfma_i32_16x16x64_i8 v[24:27], v[158:161], v[202:205], v[24:27]
	v_mfma_i32_16x16x64_i8 v[12:15], v[150:153], v[210:213], v[12:15]
	v_mfma_i32_16x16x64_i8 v[8:11], v[158:161], v[210:213], v[8:11]
	s_setprio 0
	s_setprio 1
	v_mfma_i32_16x16x64_i8 v[52:55], v[162:165], v[178:181], v[52:55]
	v_mfma_i32_16x16x64_i8 v[48:51], v[170:173], v[178:181], v[48:51]
	v_mfma_i32_16x16x64_i8 v[36:39], v[162:165], v[186:189], v[36:39]
	v_mfma_i32_16x16x64_i8 v[32:35], v[170:173], v[186:189], v[32:35]
	v_mfma_i32_16x16x64_i8 v[20:23], v[162:165], v[194:197], v[20:23]
	v_mfma_i32_16x16x64_i8 v[16:19], v[170:173], v[194:197], v[16:19]
	v_mfma_i32_16x16x64_i8 v[4:7], v[162:165], v[206:209], v[4:7]
	v_mfma_i32_16x16x64_i8 v[0:3], v[170:173], v[206:209], v[0:3]
	v_mfma_i32_16x16x64_i8 v[52:55], v[166:169], v[182:185], v[52:55]
	v_mfma_i32_16x16x64_i8 v[48:51], v[174:177], v[182:185], v[48:51]
	v_mfma_i32_16x16x64_i8 v[36:39], v[166:169], v[190:193], v[36:39]
	v_mfma_i32_16x16x64_i8 v[32:35], v[174:177], v[190:193], v[32:35]
	v_mfma_i32_16x16x64_i8 v[20:23], v[166:169], v[202:205], v[20:23]
	v_mfma_i32_16x16x64_i8 v[16:19], v[174:177], v[202:205], v[16:19]
	v_mfma_i32_16x16x64_i8 v[4:7], v[166:169], v[210:213], v[4:7]
	v_mfma_i32_16x16x64_i8 v[0:3], v[174:177], v[210:213], v[0:3]
	s_setprio 0
	s_add_u32 s56, s56, 0x100
	s_addc_u32 s57, s57, 0
	s_add_u32 s77, s77, 0x100
	s_addc_u32 s78, s78, 0
	s_cmp_ge_i32 s79, s18
	s_mov_b32 s58, s79
	s_barrier
	s_cbranch_scc0 .LBB0_1373
	s_and_b64 vcc, exec, s[16:17]
	s_cbranch_vccz .LBB0_1376

.LBB0_1510:
	v_add_u32_e32 v140, s61, v158
	ds_read_b128 v[128:131], v140
	ds_read_b128 v[132:135], v140 offset:1024
	ds_read_b128 v[150:153], v140 offset:2048
	ds_read_b128 v[162:165], v140 offset:3072
	v_add_u32_e32 v140, s62, v158
	ds_read_b128 v[166:169], v140
	ds_read_b128 v[170:173], v140 offset:1024
	ds_read_b128 v[174:177], v140 offset:2048
	ds_read_b128 v[178:181], v140 offset:3072
	s_add_i32 s67, s12, 2
	s_add_u32 s13, s10, 0xfff80080
	s_addc_u32 s56, s11, -1
	s_cmp_eq_u32 s60, s12
	s_cselect_b32 s12, s64, s65
	s_cselect_b32 s57, s29, s56
	s_cselect_b32 s56, s37, s13
	s_cselect_b32 s13, s63, s66
	v_lshl_add_u64 v[154:155], s[10:11], 0, v[142:143]
	s_add_i32 m0, s33, 0xc000
	ds_read_b128 v[182:185], v160
	ds_read_b128 v[186:189], v160 offset:1024
	ds_read_b128 v[190:193], v160 offset:2048
	ds_read_b128 v[194:197], v160 offset:3072
	ds_read_b128 v[202:205], v160 offset:4096
	ds_read_b128 v[206:209], v160 offset:5120
	ds_read_b128 v[210:213], v160 offset:6144
	ds_read_b128 v[214:217], v160 offset:7168
	global_load_lds_dwordx4 v[154:155], off
	v_lshl_add_u64 v[154:155], s[10:11], 0, v[144:145]
	s_add_i32 m0, s33, 0xe000
	s_nop 0
	global_load_lds_dwordx4 v[154:155], off
	s_waitcnt vmcnt(8)
	s_waitcnt lgkmcnt(0)
	s_barrier
	s_setprio 1
	s_waitcnt lgkmcnt(0)
	v_mfma_i32_16x16x64_i8 v[124:127], v[128:131], v[182:185], v[124:127]
	v_mfma_i32_16x16x64_i8 v[120:123], v[150:153], v[182:185], v[120:123]
	v_mfma_i32_16x16x64_i8 v[108:111], v[128:131], v[190:193], v[108:111]
	v_mfma_i32_16x16x64_i8 v[104:107], v[150:153], v[190:193], v[104:107]
	v_mfma_i32_16x16x64_i8 v[92:95], v[128:131], v[202:205], v[92:95]
	v_mfma_i32_16x16x64_i8 v[88:91], v[150:153], v[202:205], v[88:91]
	v_mfma_i32_16x16x64_i8 v[76:79], v[128:131], v[210:213], v[76:79]
	v_mfma_i32_16x16x64_i8 v[72:75], v[150:153], v[210:213], v[72:75]
	v_mfma_i32_16x16x64_i8 v[124:127], v[132:135], v[186:189], v[124:127]
	v_mfma_i32_16x16x64_i8 v[120:123], v[162:165], v[186:189], v[120:123]
	v_mfma_i32_16x16x64_i8 v[108:111], v[132:135], v[194:197], v[108:111]
	v_mfma_i32_16x16x64_i8 v[104:107], v[162:165], v[194:197], v[104:107]
	v_mfma_i32_16x16x64_i8 v[92:95], v[132:135], v[206:209], v[92:95]
	v_mfma_i32_16x16x64_i8 v[88:91], v[162:165], v[206:209], v[88:91]
	v_mfma_i32_16x16x64_i8 v[76:79], v[132:135], v[214:217], v[76:79]
	v_mfma_i32_16x16x64_i8 v[72:75], v[162:165], v[214:217], v[72:75]
	s_setprio 0
	s_setprio 1
	v_mfma_i32_16x16x64_i8 v[116:119], v[166:169], v[182:185], v[116:119]
	v_mfma_i32_16x16x64_i8 v[112:115], v[174:177], v[182:185], v[112:115]
	v_mfma_i32_16x16x64_i8 v[100:103], v[166:169], v[190:193], v[100:103]
	v_mfma_i32_16x16x64_i8 v[96:99], v[174:177], v[190:193], v[96:99]
	v_mfma_i32_16x16x64_i8 v[84:87], v[166:169], v[202:205], v[84:87]
	v_mfma_i32_16x16x64_i8 v[80:83], v[174:177], v[202:205], v[80:83]
	v_mfma_i32_16x16x64_i8 v[68:71], v[166:169], v[210:213], v[68:71]
	v_mfma_i32_16x16x64_i8 v[64:67], v[174:177], v[210:213], v[64:67]
	v_mfma_i32_16x16x64_i8 v[116:119], v[170:173], v[186:189], v[116:119]
	v_mfma_i32_16x16x64_i8 v[112:115], v[178:181], v[186:189], v[112:115]
	v_mfma_i32_16x16x64_i8 v[100:103], v[170:173], v[194:197], v[100:103]
	v_mfma_i32_16x16x64_i8 v[96:99], v[178:181], v[194:197], v[96:99]
	v_mfma_i32_16x16x64_i8 v[84:87], v[170:173], v[206:209], v[84:87]
	v_mfma_i32_16x16x64_i8 v[80:83], v[178:181], v[206:209], v[80:83]
	v_mfma_i32_16x16x64_i8 v[68:71], v[170:173], v[214:217], v[68:71]
	v_mfma_i32_16x16x64_i8 v[64:67], v[178:181], v[214:217], v[64:67]
	s_setprio 0
	s_barrier
	s_add_i32 s76, s61, s31
	v_lshl_add_u64 v[154:155], s[12:13], 0, v[136:137]
	s_mov_b32 m0, s76
	ds_read_b128 v[182:185], v160 offset:16384
	ds_read_b128 v[186:189], v160 offset:17408
	ds_read_b128 v[190:193], v160 offset:18432
	ds_read_b128 v[194:197], v160 offset:19456
	ds_read_b128 v[202:205], v160 offset:20480
	ds_read_b128 v[206:209], v160 offset:21504
	ds_read_b128 v[210:213], v160 offset:22528
	ds_read_b128 v[214:217], v160 offset:23552
	global_load_lds_dwordx4 v[154:155], off
	s_add_i32 m0, s76, 0x2000
	s_add_u32 s76, s12, 0x80000
	v_lshl_add_u64 v[198:199], s[12:13], 0, v[138:139]
	s_addc_u32 s77, s13, 0
	s_add_i32 s78, s62, s31
	global_load_lds_dwordx4 v[198:199], off
	v_lshl_add_u64 v[218:219], s[76:77], 0, v[136:137]
	s_mov_b32 m0, s78
	v_lshl_add_u64 v[220:221], s[56:57], 0, v[138:139]
	global_load_lds_dwordx4 v[218:219], off
	v_lshl_add_u64 v[218:219], s[76:77], 0, v[138:139]
	s_add_i32 m0, s78, 0x2000
	s_nop 0
	global_load_lds_dwordx4 v[218:219], off
	v_lshl_add_u64 v[218:219], s[56:57], 0, v[136:137]
	s_mov_b32 m0, s33
	s_nop 0
	global_load_lds_dwordx4 v[218:219], off
	s_mov_b32 m0, s34
	s_nop 0
	global_load_lds_dwordx4 v[220:221], off
	s_waitcnt vmcnt(8)
	s_waitcnt lgkmcnt(0)
	s_barrier
	s_setprio 1
	s_waitcnt lgkmcnt(0)
	v_mfma_i32_16x16x64_i8 v[60:63], v[128:131], v[182:185], v[60:63]
	v_mfma_i32_16x16x64_i8 v[56:59], v[150:153], v[182:185], v[56:59]
	v_mfma_i32_16x16x64_i8 v[44:47], v[128:131], v[190:193], v[44:47]
	v_mfma_i32_16x16x64_i8 v[40:43], v[150:153], v[190:193], v[40:43]
	v_mfma_i32_16x16x64_i8 v[28:31], v[128:131], v[202:205], v[28:31]
	v_mfma_i32_16x16x64_i8 v[24:27], v[150:153], v[202:205], v[24:27]
	v_mfma_i32_16x16x64_i8 v[12:15], v[128:131], v[210:213], v[12:15]
	v_mfma_i32_16x16x64_i8 v[8:11], v[150:153], v[210:213], v[8:11]
	v_mfma_i32_16x16x64_i8 v[60:63], v[132:135], v[186:189], v[60:63]
	v_mfma_i32_16x16x64_i8 v[56:59], v[162:165], v[186:189], v[56:59]
	v_mfma_i32_16x16x64_i8 v[44:47], v[132:135], v[194:197], v[44:47]
	v_mfma_i32_16x16x64_i8 v[40:43], v[162:165], v[194:197], v[40:43]
	v_mfma_i32_16x16x64_i8 v[28:31], v[132:135], v[206:209], v[28:31]
	v_mfma_i32_16x16x64_i8 v[24:27], v[162:165], v[206:209], v[24:27]
	v_mfma_i32_16x16x64_i8 v[12:15], v[132:135], v[214:217], v[12:15]
	v_mfma_i32_16x16x64_i8 v[8:11], v[162:165], v[214:217], v[8:11]
	s_setprio 0
	s_setprio 1
	v_mfma_i32_16x16x64_i8 v[52:55], v[166:169], v[182:185], v[52:55]
	v_mfma_i32_16x16x64_i8 v[48:51], v[174:177], v[182:185], v[48:51]
	v_mfma_i32_16x16x64_i8 v[36:39], v[166:169], v[190:193], v[36:39]
	v_mfma_i32_16x16x64_i8 v[32:35], v[174:177], v[190:193], v[32:35]
	v_mfma_i32_16x16x64_i8 v[20:23], v[166:169], v[202:205], v[20:23]
	v_mfma_i32_16x16x64_i8 v[16:19], v[174:177], v[202:205], v[16:19]
	v_mfma_i32_16x16x64_i8 v[4:7], v[166:169], v[210:213], v[4:7]
	v_mfma_i32_16x16x64_i8 v[0:3], v[174:177], v[210:213], v[0:3]
	v_mfma_i32_16x16x64_i8 v[52:55], v[170:173], v[186:189], v[52:55]
	v_mfma_i32_16x16x64_i8 v[48:51], v[178:181], v[186:189], v[48:51]
	v_mfma_i32_16x16x64_i8 v[36:39], v[170:173], v[194:197], v[36:39]
	v_mfma_i32_16x16x64_i8 v[32:35], v[178:181], v[194:197], v[32:35]
	v_mfma_i32_16x16x64_i8 v[20:23], v[170:173], v[206:209], v[20:23]
	v_mfma_i32_16x16x64_i8 v[16:19], v[178:181], v[206:209], v[16:19]
	v_mfma_i32_16x16x64_i8 v[4:7], v[170:173], v[214:217], v[4:7]
	v_mfma_i32_16x16x64_i8 v[0:3], v[178:181], v[214:217], v[0:3]
	s_setprio 0
	s_barrier
	s_add_i32 s76, 0, 0x18000
	v_add_u32_e32 v140, s76, v158
	s_add_i32 s77, 0, 0x1c000
	ds_read_b128 v[128:131], v140
	ds_read_b128 v[132:135], v140 offset:1024
	ds_read_b128 v[150:153], v140 offset:2048
	ds_read_b128 v[162:165], v140 offset:3072
	v_add_u32_e32 v140, s77, v158
	ds_read_b128 v[166:169], v140
	ds_read_b128 v[170:173], v140 offset:1024
	ds_read_b128 v[174:177], v140 offset:2048
	ds_read_b128 v[178:181], v140 offset:3072
	s_add_u32 s56, s56, 0x80000
	s_addc_u32 s57, s57, 0
	s_mov_b32 m0, s35
	v_lshl_add_u64 v[222:223], s[56:57], 0, v[136:137]
	ds_read_b128 v[182:185], v160 offset:32768
	ds_read_b128 v[186:189], v160 offset:33792
	ds_read_b128 v[190:193], v160 offset:34816
	ds_read_b128 v[194:197], v160 offset:35840
	ds_read_b128 v[202:205], v160 offset:36864
	ds_read_b128 v[206:209], v160 offset:37888
	ds_read_b128 v[210:213], v160 offset:38912
	ds_read_b128 v[214:217], v160 offset:39936
	global_load_lds_dwordx4 v[222:223], off
	v_lshl_add_u64 v[222:223], s[56:57], 0, v[138:139]
	s_mov_b32 m0, s52
	s_nop 0
	global_load_lds_dwordx4 v[222:223], off
	s_waitcnt vmcnt(8)
	s_waitcnt lgkmcnt(0)
	s_barrier
	s_setprio 1
	s_waitcnt lgkmcnt(0)
	v_mfma_i32_16x16x64_i8 v[124:127], v[128:131], v[182:185], v[124:127]
	v_mfma_i32_16x16x64_i8 v[120:123], v[150:153], v[182:185], v[120:123]
	v_mfma_i32_16x16x64_i8 v[108:111], v[128:131], v[190:193], v[108:111]
	v_mfma_i32_16x16x64_i8 v[104:107], v[150:153], v[190:193], v[104:107]
	v_mfma_i32_16x16x64_i8 v[92:95], v[128:131], v[202:205], v[92:95]
	v_mfma_i32_16x16x64_i8 v[88:91], v[150:153], v[202:205], v[88:91]
	v_mfma_i32_16x16x64_i8 v[76:79], v[128:131], v[210:213], v[76:79]
	v_mfma_i32_16x16x64_i8 v[72:75], v[150:153], v[210:213], v[72:75]
	v_mfma_i32_16x16x64_i8 v[124:127], v[132:135], v[186:189], v[124:127]
	v_mfma_i32_16x16x64_i8 v[120:123], v[162:165], v[186:189], v[120:123]
	v_mfma_i32_16x16x64_i8 v[108:111], v[132:135], v[194:197], v[108:111]
	v_mfma_i32_16x16x64_i8 v[104:107], v[162:165], v[194:197], v[104:107]
	v_mfma_i32_16x16x64_i8 v[92:95], v[132:135], v[206:209], v[92:95]
	v_mfma_i32_16x16x64_i8 v[88:91], v[162:165], v[206:209], v[88:91]
	v_mfma_i32_16x16x64_i8 v[76:79], v[132:135], v[214:217], v[76:79]
	v_mfma_i32_16x16x64_i8 v[72:75], v[162:165], v[214:217], v[72:75]
	s_setprio 0
	s_setprio 1
	v_mfma_i32_16x16x64_i8 v[116:119], v[166:169], v[182:185], v[116:119]
	v_mfma_i32_16x16x64_i8 v[112:115], v[174:177], v[182:185], v[112:115]
	v_mfma_i32_16x16x64_i8 v[100:103], v[166:169], v[190:193], v[100:103]
	v_mfma_i32_16x16x64_i8 v[96:99], v[174:177], v[190:193], v[96:99]
	v_mfma_i32_16x16x64_i8 v[84:87], v[166:169], v[202:205], v[84:87]
	v_mfma_i32_16x16x64_i8 v[80:83], v[174:177], v[202:205], v[80:83]
	v_mfma_i32_16x16x64_i8 v[68:71], v[166:169], v[210:213], v[68:71]
	v_mfma_i32_16x16x64_i8 v[64:67], v[174:177], v[210:213], v[64:67]
	v_mfma_i32_16x16x64_i8 v[116:119], v[170:173], v[186:189], v[116:119]
	v_mfma_i32_16x16x64_i8 v[112:115], v[178:181], v[186:189], v[112:115]
	v_mfma_i32_16x16x64_i8 v[100:103], v[170:173], v[194:197], v[100:103]
	v_mfma_i32_16x16x64_i8 v[96:99], v[178:181], v[194:197], v[96:99]
	v_mfma_i32_16x16x64_i8 v[84:87], v[170:173], v[206:209], v[84:87]
	v_mfma_i32_16x16x64_i8 v[80:83], v[178:181], v[206:209], v[80:83]
	v_mfma_i32_16x16x64_i8 v[68:71], v[170:173], v[214:217], v[68:71]
	v_mfma_i32_16x16x64_i8 v[64:67], v[178:181], v[214:217], v[64:67]
	s_setprio 0
	s_barrier
	s_add_i32 s56, s76, s31
	v_lshl_add_u64 v[154:155], v[154:155], 0, s[22:23]
	s_mov_b32 m0, s56
	ds_read_b128 v[182:185], v160 offset:49152
	ds_read_b128 v[186:189], v160 offset:50176
	ds_read_b128 v[190:193], v160 offset:51200
	ds_read_b128 v[194:197], v160 offset:52224
	ds_read_b128 v[202:205], v160 offset:53248
	ds_read_b128 v[206:209], v160 offset:54272
	ds_read_b128 v[210:213], v160 offset:55296
	ds_read_b128 v[214:217], v160 offset:56320
	global_load_lds_dwordx4 v[154:155], off
	s_add_i32 m0, s56, 0x2000
	s_add_u32 s12, s12, 0x80080
	v_lshl_add_u64 v[154:155], v[198:199], 0, s[22:23]
	s_addc_u32 s13, s13, 0
	s_add_i32 s56, s77, s31
	global_load_lds_dwordx4 v[154:155], off
	v_lshl_add_u64 v[154:155], s[12:13], 0, v[136:137]
	s_mov_b32 m0, s56
	s_nop 0
	global_load_lds_dwordx4 v[154:155], off
	v_lshl_add_u64 v[154:155], s[12:13], 0, v[138:139]
	s_add_i32 m0, s56, 0x2000
	s_nop 0
	global_load_lds_dwordx4 v[154:155], off
	v_lshl_add_u64 v[154:155], v[218:219], 0, s[22:23]
	s_mov_b32 m0, s58
	s_nop 0
	global_load_lds_dwordx4 v[154:155], off
	v_lshl_add_u64 v[154:155], v[220:221], 0, s[22:23]
	s_mov_b32 m0, s59
	s_nop 0
	global_load_lds_dwordx4 v[154:155], off
	s_waitcnt vmcnt(8)
	s_waitcnt lgkmcnt(0)
	s_barrier
	s_setprio 1
	s_waitcnt lgkmcnt(0)
	v_mfma_i32_16x16x64_i8 v[60:63], v[128:131], v[182:185], v[60:63]
	v_mfma_i32_16x16x64_i8 v[56:59], v[150:153], v[182:185], v[56:59]
	v_mfma_i32_16x16x64_i8 v[44:47], v[128:131], v[190:193], v[44:47]
	v_mfma_i32_16x16x64_i8 v[40:43], v[150:153], v[190:193], v[40:43]
	v_mfma_i32_16x16x64_i8 v[28:31], v[128:131], v[202:205], v[28:31]
	v_mfma_i32_16x16x64_i8 v[24:27], v[150:153], v[202:205], v[24:27]
	v_mfma_i32_16x16x64_i8 v[12:15], v[128:131], v[210:213], v[12:15]
	v_mfma_i32_16x16x64_i8 v[8:11], v[150:153], v[210:213], v[8:11]
	v_mfma_i32_16x16x64_i8 v[60:63], v[132:135], v[186:189], v[60:63]
	v_mfma_i32_16x16x64_i8 v[56:59], v[162:165], v[186:189], v[56:59]
	v_mfma_i32_16x16x64_i8 v[44:47], v[132:135], v[194:197], v[44:47]
	v_mfma_i32_16x16x64_i8 v[40:43], v[162:165], v[194:197], v[40:43]
	v_mfma_i32_16x16x64_i8 v[28:31], v[132:135], v[206:209], v[28:31]
	v_mfma_i32_16x16x64_i8 v[24:27], v[162:165], v[206:209], v[24:27]
	v_mfma_i32_16x16x64_i8 v[12:15], v[132:135], v[214:217], v[12:15]
	v_mfma_i32_16x16x64_i8 v[8:11], v[162:165], v[214:217], v[8:11]
	s_setprio 0
	s_setprio 1
	v_mfma_i32_16x16x64_i8 v[52:55], v[166:169], v[182:185], v[52:55]
	v_mfma_i32_16x16x64_i8 v[48:51], v[174:177], v[182:185], v[48:51]
	v_mfma_i32_16x16x64_i8 v[36:39], v[166:169], v[190:193], v[36:39]
	v_mfma_i32_16x16x64_i8 v[32:35], v[174:177], v[190:193], v[32:35]
	v_mfma_i32_16x16x64_i8 v[20:23], v[166:169], v[202:205], v[20:23]
	v_mfma_i32_16x16x64_i8 v[16:19], v[174:177], v[202:205], v[16:19]
	v_mfma_i32_16x16x64_i8 v[4:7], v[166:169], v[210:213], v[4:7]
	v_mfma_i32_16x16x64_i8 v[0:3], v[174:177], v[210:213], v[0:3]
	v_mfma_i32_16x16x64_i8 v[52:55], v[170:173], v[186:189], v[52:55]
	v_mfma_i32_16x16x64_i8 v[48:51], v[178:181], v[186:189], v[48:51]
	v_mfma_i32_16x16x64_i8 v[36:39], v[170:173], v[194:197], v[36:39]
	v_mfma_i32_16x16x64_i8 v[32:35], v[178:181], v[194:197], v[32:35]
	v_mfma_i32_16x16x64_i8 v[20:23], v[170:173], v[206:209], v[20:23]
	v_mfma_i32_16x16x64_i8 v[16:19], v[178:181], v[206:209], v[16:19]
	v_mfma_i32_16x16x64_i8 v[4:7], v[170:173], v[214:217], v[4:7]
	v_mfma_i32_16x16x64_i8 v[0:3], v[178:181], v[214:217], v[0:3]
	s_setprio 0
	s_add_u32 s10, s10, 0x100
	s_addc_u32 s11, s11, 0
	s_add_u32 s65, s65, 0x100
	s_addc_u32 s66, s66, 0
	s_cmp_ge_i32 s67, s18
	s_mov_b32 s12, s67
	s_barrier
	s_cbranch_scc0 .LBB0_1510
	s_and_b64 vcc, exec, s[24:25]
	s_cbranch_vccz .LBB0_1513

.LBB0_1647:
	v_add_u32_e32 v132, s93, v184
	ds_read_b128 v[128:131], v132
	ds_read_b128 v[156:159], v132 offset:1024
	ds_read_b128 v[160:163], v132 offset:2048
	ds_read_b128 v[164:167], v132 offset:3072
	v_add_u32_e32 v132, s94, v184
	ds_read_b128 v[168:171], v132
	ds_read_b128 v[172:175], v132 offset:1024
	ds_read_b128 v[176:179], v132 offset:2048
	ds_read_b128 v[188:191], v132 offset:3072
	s_add_i32 s51, s35, 2
	s_add_u32 s52, s60, 0xfff80080
	s_addc_u32 s53, s61, -1
	s_cmp_eq_u32 s91, s35
	s_cselect_b32 s65, s9, s53
	s_cselect_b32 s64, s11, s52
	s_cselect_b32 s63, s18, s34
	s_cselect_b32 s62, s19, s33
	v_lshl_add_u64 v[132:133], s[60:61], 0, v[148:149]
	s_add_i32 m0, s78, 0xc000
	ds_read_b128 v[192:195], v186
	ds_read_b128 v[196:199], v186 offset:1024
	ds_read_b128 v[202:205], v186 offset:2048
	ds_read_b128 v[206:209], v186 offset:3072
	ds_read_b128 v[210:213], v186 offset:4096
	ds_read_b128 v[214:217], v186 offset:5120
	ds_read_b128 v[218:221], v186 offset:6144
	ds_read_b128 v[222:225], v186 offset:7168
	global_load_lds_dwordx4 v[132:133], off
	v_lshl_add_u64 v[132:133], s[60:61], 0, v[150:151]
	s_add_i32 m0, s78, 0xe000
	s_nop 0
	global_load_lds_dwordx4 v[132:133], off
	s_waitcnt vmcnt(8)
	s_waitcnt lgkmcnt(0)
	s_barrier
	s_setprio 1
	s_waitcnt lgkmcnt(0)
	v_mfma_i32_16x16x64_i8 v[124:127], v[128:131], v[192:195], v[124:127]
	v_mfma_i32_16x16x64_i8 v[120:123], v[160:163], v[192:195], v[120:123]
	v_mfma_i32_16x16x64_i8 v[108:111], v[128:131], v[202:205], v[108:111]
	v_mfma_i32_16x16x64_i8 v[104:107], v[160:163], v[202:205], v[104:107]
	v_mfma_i32_16x16x64_i8 v[92:95], v[128:131], v[210:213], v[92:95]
	v_mfma_i32_16x16x64_i8 v[88:91], v[160:163], v[210:213], v[88:91]
	v_mfma_i32_16x16x64_i8 v[76:79], v[128:131], v[218:221], v[76:79]
	v_mfma_i32_16x16x64_i8 v[72:75], v[160:163], v[218:221], v[72:75]
	v_mfma_i32_16x16x64_i8 v[124:127], v[156:159], v[196:199], v[124:127]
	v_mfma_i32_16x16x64_i8 v[120:123], v[164:167], v[196:199], v[120:123]
	v_mfma_i32_16x16x64_i8 v[108:111], v[156:159], v[206:209], v[108:111]
	v_mfma_i32_16x16x64_i8 v[104:107], v[164:167], v[206:209], v[104:107]
	v_mfma_i32_16x16x64_i8 v[92:95], v[156:159], v[214:217], v[92:95]
	v_mfma_i32_16x16x64_i8 v[88:91], v[164:167], v[214:217], v[88:91]
	v_mfma_i32_16x16x64_i8 v[76:79], v[156:159], v[222:225], v[76:79]
	v_mfma_i32_16x16x64_i8 v[72:75], v[164:167], v[222:225], v[72:75]
	s_setprio 0
	s_setprio 1
	v_mfma_i32_16x16x64_i8 v[116:119], v[168:171], v[192:195], v[116:119]
	v_mfma_i32_16x16x64_i8 v[112:115], v[176:179], v[192:195], v[112:115]
	v_mfma_i32_16x16x64_i8 v[100:103], v[168:171], v[202:205], v[100:103]
	v_mfma_i32_16x16x64_i8 v[96:99], v[176:179], v[202:205], v[96:99]
	v_mfma_i32_16x16x64_i8 v[84:87], v[168:171], v[210:213], v[84:87]
	v_mfma_i32_16x16x64_i8 v[80:83], v[176:179], v[210:213], v[80:83]
	v_mfma_i32_16x16x64_i8 v[68:71], v[168:171], v[218:221], v[68:71]
	v_mfma_i32_16x16x64_i8 v[64:67], v[176:179], v[218:221], v[64:67]
	v_mfma_i32_16x16x64_i8 v[116:119], v[172:175], v[196:199], v[116:119]
	v_mfma_i32_16x16x64_i8 v[112:115], v[188:191], v[196:199], v[112:115]
	v_mfma_i32_16x16x64_i8 v[100:103], v[172:175], v[206:209], v[100:103]
	v_mfma_i32_16x16x64_i8 v[96:99], v[188:191], v[206:209], v[96:99]
	v_mfma_i32_16x16x64_i8 v[84:87], v[172:175], v[214:217], v[84:87]
	v_mfma_i32_16x16x64_i8 v[80:83], v[188:191], v[214:217], v[80:83]
	v_mfma_i32_16x16x64_i8 v[68:71], v[172:175], v[222:225], v[68:71]
	v_mfma_i32_16x16x64_i8 v[64:67], v[188:191], v[222:225], v[64:67]
	s_setprio 0
	s_barrier
	s_add_i32 s35, s93, s67
	v_lshl_add_u64 v[132:133], s[62:63], 0, v[136:137]
	s_mov_b32 m0, s35
	ds_read_b128 v[192:195], v186 offset:16384
	ds_read_b128 v[196:199], v186 offset:17408
	ds_read_b128 v[202:205], v186 offset:18432
	ds_read_b128 v[206:209], v186 offset:19456
	ds_read_b128 v[210:213], v186 offset:20480
	ds_read_b128 v[214:217], v186 offset:21504
	ds_read_b128 v[218:221], v186 offset:22528
	ds_read_b128 v[222:225], v186 offset:23552
	global_load_lds_dwordx4 v[132:133], off
	s_add_i32 m0, s35, 0x2000
	s_add_u32 s52, s62, 0x80000
	v_lshl_add_u64 v[180:181], s[62:63], 0, v[140:141]
	s_addc_u32 s53, s63, 0
	s_add_i32 s35, s94, s67
	global_load_lds_dwordx4 v[180:181], off
	v_lshl_add_u64 v[226:227], s[52:53], 0, v[136:137]
	s_mov_b32 m0, s35
	v_lshl_add_u64 v[228:229], s[64:65], 0, v[138:139]
	global_load_lds_dwordx4 v[226:227], off
	v_lshl_add_u64 v[226:227], s[52:53], 0, v[140:141]
	s_add_i32 m0, s35, 0x2000
	s_nop 0
	global_load_lds_dwordx4 v[226:227], off
	v_lshl_add_u64 v[226:227], s[64:65], 0, v[134:135]
	s_mov_b32 m0, s78
	s_nop 0
	global_load_lds_dwordx4 v[226:227], off
	s_mov_b32 m0, s79
	s_nop 0
	global_load_lds_dwordx4 v[228:229], off
	s_waitcnt vmcnt(8)
	s_waitcnt lgkmcnt(0)
	s_barrier
	s_setprio 1
	s_waitcnt lgkmcnt(0)
	v_mfma_i32_16x16x64_i8 v[60:63], v[128:131], v[192:195], v[60:63]
	v_mfma_i32_16x16x64_i8 v[56:59], v[160:163], v[192:195], v[56:59]
	v_mfma_i32_16x16x64_i8 v[44:47], v[128:131], v[202:205], v[44:47]
	v_mfma_i32_16x16x64_i8 v[40:43], v[160:163], v[202:205], v[40:43]
	v_mfma_i32_16x16x64_i8 v[28:31], v[128:131], v[210:213], v[28:31]
	v_mfma_i32_16x16x64_i8 v[24:27], v[160:163], v[210:213], v[24:27]
	v_mfma_i32_16x16x64_i8 v[12:15], v[128:131], v[218:221], v[12:15]
	v_mfma_i32_16x16x64_i8 v[8:11], v[160:163], v[218:221], v[8:11]
	v_mfma_i32_16x16x64_i8 v[60:63], v[156:159], v[196:199], v[60:63]
	v_mfma_i32_16x16x64_i8 v[56:59], v[164:167], v[196:199], v[56:59]
	v_mfma_i32_16x16x64_i8 v[44:47], v[156:159], v[206:209], v[44:47]
	v_mfma_i32_16x16x64_i8 v[40:43], v[164:167], v[206:209], v[40:43]
	v_mfma_i32_16x16x64_i8 v[28:31], v[156:159], v[214:217], v[28:31]
	v_mfma_i32_16x16x64_i8 v[24:27], v[164:167], v[214:217], v[24:27]
	v_mfma_i32_16x16x64_i8 v[12:15], v[156:159], v[222:225], v[12:15]
	v_mfma_i32_16x16x64_i8 v[8:11], v[164:167], v[222:225], v[8:11]
	s_setprio 0
	s_setprio 1
	v_mfma_i32_16x16x64_i8 v[52:55], v[168:171], v[192:195], v[52:55]
	v_mfma_i32_16x16x64_i8 v[48:51], v[176:179], v[192:195], v[48:51]
	v_mfma_i32_16x16x64_i8 v[36:39], v[168:171], v[202:205], v[36:39]
	v_mfma_i32_16x16x64_i8 v[32:35], v[176:179], v[202:205], v[32:35]
	v_mfma_i32_16x16x64_i8 v[20:23], v[168:171], v[210:213], v[20:23]
	v_mfma_i32_16x16x64_i8 v[16:19], v[176:179], v[210:213], v[16:19]
	v_mfma_i32_16x16x64_i8 v[4:7], v[168:171], v[218:221], v[4:7]
	v_mfma_i32_16x16x64_i8 v[0:3], v[176:179], v[218:221], v[0:3]
	v_mfma_i32_16x16x64_i8 v[52:55], v[172:175], v[196:199], v[52:55]
	v_mfma_i32_16x16x64_i8 v[48:51], v[188:191], v[196:199], v[48:51]
	v_mfma_i32_16x16x64_i8 v[36:39], v[172:175], v[206:209], v[36:39]
	v_mfma_i32_16x16x64_i8 v[32:35], v[188:191], v[206:209], v[32:35]
	v_mfma_i32_16x16x64_i8 v[20:23], v[172:175], v[214:217], v[20:23]
	v_mfma_i32_16x16x64_i8 v[16:19], v[188:191], v[214:217], v[16:19]
	v_mfma_i32_16x16x64_i8 v[4:7], v[172:175], v[222:225], v[4:7]
	v_mfma_i32_16x16x64_i8 v[0:3], v[188:191], v[222:225], v[0:3]
	s_setprio 0
	s_barrier
	s_add_i32 s35, 0, 0x18000
	v_add_u32_e32 v142, s35, v184
	s_add_i32 s55, 0, 0x1c000
	ds_read_b128 v[128:131], v142
	ds_read_b128 v[156:159], v142 offset:1024
	ds_read_b128 v[160:163], v142 offset:2048
	ds_read_b128 v[164:167], v142 offset:3072
	v_add_u32_e32 v142, s55, v184
	ds_read_b128 v[168:171], v142
	ds_read_b128 v[172:175], v142 offset:1024
	ds_read_b128 v[176:179], v142 offset:2048
	ds_read_b128 v[188:191], v142 offset:3072
	s_add_u32 s52, s64, 0x80000
	s_addc_u32 s53, s65, 0
	s_mov_b32 m0, s80
	v_lshl_add_u64 v[230:231], s[52:53], 0, v[134:135]
	ds_read_b128 v[192:195], v186 offset:32768
	ds_read_b128 v[196:199], v186 offset:33792
	ds_read_b128 v[202:205], v186 offset:34816
	ds_read_b128 v[206:209], v186 offset:35840
	ds_read_b128 v[210:213], v186 offset:36864
	ds_read_b128 v[214:217], v186 offset:37888
	ds_read_b128 v[218:221], v186 offset:38912
	ds_read_b128 v[222:225], v186 offset:39936
	global_load_lds_dwordx4 v[230:231], off
	v_lshl_add_u64 v[230:231], s[52:53], 0, v[138:139]
	s_mov_b32 m0, s81
	s_nop 0
	global_load_lds_dwordx4 v[230:231], off
	s_waitcnt vmcnt(8)
	s_waitcnt lgkmcnt(0)
	s_barrier
	s_setprio 1
	s_waitcnt lgkmcnt(0)
	v_mfma_i32_16x16x64_i8 v[124:127], v[128:131], v[192:195], v[124:127]
	v_mfma_i32_16x16x64_i8 v[120:123], v[160:163], v[192:195], v[120:123]
	v_mfma_i32_16x16x64_i8 v[108:111], v[128:131], v[202:205], v[108:111]
	v_mfma_i32_16x16x64_i8 v[104:107], v[160:163], v[202:205], v[104:107]
	v_mfma_i32_16x16x64_i8 v[92:95], v[128:131], v[210:213], v[92:95]
	v_mfma_i32_16x16x64_i8 v[88:91], v[160:163], v[210:213], v[88:91]
	v_mfma_i32_16x16x64_i8 v[76:79], v[128:131], v[218:221], v[76:79]
	v_mfma_i32_16x16x64_i8 v[72:75], v[160:163], v[218:221], v[72:75]
	v_mfma_i32_16x16x64_i8 v[124:127], v[156:159], v[196:199], v[124:127]
	v_mfma_i32_16x16x64_i8 v[120:123], v[164:167], v[196:199], v[120:123]
	v_mfma_i32_16x16x64_i8 v[108:111], v[156:159], v[206:209], v[108:111]
	v_mfma_i32_16x16x64_i8 v[104:107], v[164:167], v[206:209], v[104:107]
	v_mfma_i32_16x16x64_i8 v[92:95], v[156:159], v[214:217], v[92:95]
	v_mfma_i32_16x16x64_i8 v[88:91], v[164:167], v[214:217], v[88:91]
	v_mfma_i32_16x16x64_i8 v[76:79], v[156:159], v[222:225], v[76:79]
	v_mfma_i32_16x16x64_i8 v[72:75], v[164:167], v[222:225], v[72:75]
	s_setprio 0
	s_setprio 1
	v_mfma_i32_16x16x64_i8 v[116:119], v[168:171], v[192:195], v[116:119]
	v_mfma_i32_16x16x64_i8 v[112:115], v[176:179], v[192:195], v[112:115]
	v_mfma_i32_16x16x64_i8 v[100:103], v[168:171], v[202:205], v[100:103]
	v_mfma_i32_16x16x64_i8 v[96:99], v[176:179], v[202:205], v[96:99]
	v_mfma_i32_16x16x64_i8 v[84:87], v[168:171], v[210:213], v[84:87]
	v_mfma_i32_16x16x64_i8 v[80:83], v[176:179], v[210:213], v[80:83]
	v_mfma_i32_16x16x64_i8 v[68:71], v[168:171], v[218:221], v[68:71]
	v_mfma_i32_16x16x64_i8 v[64:67], v[176:179], v[218:221], v[64:67]
	v_mfma_i32_16x16x64_i8 v[116:119], v[172:175], v[196:199], v[116:119]
	v_mfma_i32_16x16x64_i8 v[112:115], v[188:191], v[196:199], v[112:115]
	v_mfma_i32_16x16x64_i8 v[100:103], v[172:175], v[206:209], v[100:103]
	v_mfma_i32_16x16x64_i8 v[96:99], v[188:191], v[206:209], v[96:99]
	v_mfma_i32_16x16x64_i8 v[84:87], v[172:175], v[214:217], v[84:87]
	v_mfma_i32_16x16x64_i8 v[80:83], v[188:191], v[214:217], v[80:83]
	v_mfma_i32_16x16x64_i8 v[68:71], v[172:175], v[222:225], v[68:71]
	v_mfma_i32_16x16x64_i8 v[64:67], v[188:191], v[222:225], v[64:67]
	s_setprio 0
	s_barrier
	s_add_i32 s35, s35, s67
	v_lshl_add_u64 v[132:133], v[132:133], 0, s[22:23]
	s_mov_b32 m0, s35
	ds_read_b128 v[192:195], v186 offset:49152
	ds_read_b128 v[196:199], v186 offset:50176
	ds_read_b128 v[202:205], v186 offset:51200
	ds_read_b128 v[206:209], v186 offset:52224
	ds_read_b128 v[210:213], v186 offset:53248
	ds_read_b128 v[214:217], v186 offset:54272
	ds_read_b128 v[218:221], v186 offset:55296
	ds_read_b128 v[222:225], v186 offset:56320
	global_load_lds_dwordx4 v[132:133], off
	s_add_i32 m0, s35, 0x2000
	s_add_u32 s52, s62, 0x80080
	v_lshl_add_u64 v[132:133], v[180:181], 0, s[22:23]
	s_addc_u32 s53, s63, 0
	s_add_i32 s35, s55, s67
	global_load_lds_dwordx4 v[132:133], off
	v_lshl_add_u64 v[132:133], s[52:53], 0, v[136:137]
	s_mov_b32 m0, s35
	s_nop 0
	global_load_lds_dwordx4 v[132:133], off
	v_lshl_add_u64 v[132:133], s[52:53], 0, v[140:141]
	s_add_i32 m0, s35, 0x2000
	s_nop 0
	global_load_lds_dwordx4 v[132:133], off
	v_lshl_add_u64 v[132:133], v[226:227], 0, s[22:23]
	s_mov_b32 m0, s89
	s_nop 0
	global_load_lds_dwordx4 v[132:133], off
	v_lshl_add_u64 v[132:133], v[228:229], 0, s[22:23]
	s_mov_b32 m0, s90
	s_nop 0
	global_load_lds_dwordx4 v[132:133], off
	s_waitcnt vmcnt(8)
	s_waitcnt lgkmcnt(0)
	s_barrier
	s_setprio 1
	s_waitcnt lgkmcnt(0)
	v_mfma_i32_16x16x64_i8 v[60:63], v[128:131], v[192:195], v[60:63]
	v_mfma_i32_16x16x64_i8 v[56:59], v[160:163], v[192:195], v[56:59]
	v_mfma_i32_16x16x64_i8 v[44:47], v[128:131], v[202:205], v[44:47]
	v_mfma_i32_16x16x64_i8 v[40:43], v[160:163], v[202:205], v[40:43]
	v_mfma_i32_16x16x64_i8 v[28:31], v[128:131], v[210:213], v[28:31]
	v_mfma_i32_16x16x64_i8 v[24:27], v[160:163], v[210:213], v[24:27]
	v_mfma_i32_16x16x64_i8 v[12:15], v[128:131], v[218:221], v[12:15]
	v_mfma_i32_16x16x64_i8 v[8:11], v[160:163], v[218:221], v[8:11]
	v_mfma_i32_16x16x64_i8 v[60:63], v[156:159], v[196:199], v[60:63]
	v_mfma_i32_16x16x64_i8 v[56:59], v[164:167], v[196:199], v[56:59]
	v_mfma_i32_16x16x64_i8 v[44:47], v[156:159], v[206:209], v[44:47]
	v_mfma_i32_16x16x64_i8 v[40:43], v[164:167], v[206:209], v[40:43]
	v_mfma_i32_16x16x64_i8 v[28:31], v[156:159], v[214:217], v[28:31]
	v_mfma_i32_16x16x64_i8 v[24:27], v[164:167], v[214:217], v[24:27]
	v_mfma_i32_16x16x64_i8 v[12:15], v[156:159], v[222:225], v[12:15]
	v_mfma_i32_16x16x64_i8 v[8:11], v[164:167], v[222:225], v[8:11]
	s_setprio 0
	s_setprio 1
	v_mfma_i32_16x16x64_i8 v[52:55], v[168:171], v[192:195], v[52:55]
	v_mfma_i32_16x16x64_i8 v[48:51], v[176:179], v[192:195], v[48:51]
	v_mfma_i32_16x16x64_i8 v[36:39], v[168:171], v[202:205], v[36:39]
	v_mfma_i32_16x16x64_i8 v[32:35], v[176:179], v[202:205], v[32:35]
	v_mfma_i32_16x16x64_i8 v[20:23], v[168:171], v[210:213], v[20:23]
	v_mfma_i32_16x16x64_i8 v[16:19], v[176:179], v[210:213], v[16:19]
	v_mfma_i32_16x16x64_i8 v[4:7], v[168:171], v[218:221], v[4:7]
	v_mfma_i32_16x16x64_i8 v[0:3], v[176:179], v[218:221], v[0:3]
	v_mfma_i32_16x16x64_i8 v[52:55], v[172:175], v[196:199], v[52:55]
	v_mfma_i32_16x16x64_i8 v[48:51], v[188:191], v[196:199], v[48:51]
	v_mfma_i32_16x16x64_i8 v[36:39], v[172:175], v[206:209], v[36:39]
	v_mfma_i32_16x16x64_i8 v[32:35], v[188:191], v[206:209], v[32:35]
	v_mfma_i32_16x16x64_i8 v[20:23], v[172:175], v[214:217], v[20:23]
	v_mfma_i32_16x16x64_i8 v[16:19], v[188:191], v[214:217], v[16:19]
	v_mfma_i32_16x16x64_i8 v[4:7], v[172:175], v[222:225], v[4:7]
	v_mfma_i32_16x16x64_i8 v[0:3], v[188:191], v[222:225], v[0:3]
	s_setprio 0
	s_add_u32 s60, s60, 0x100
	s_addc_u32 s61, s61, 0
	s_add_u32 s33, s33, 0x100
	s_addc_u32 s34, s34, 0
	s_cmp_ge_i32 s51, s31
	s_mov_b32 s35, s51
	s_barrier
	s_cbranch_scc0 .LBB0_1647
	s_and_b64 vcc, exec, s[26:27]
	s_cbranch_vccz .LBB0_1650

.LBB0_2155:
	v_add_u32_e32 v148, s78, v151
	ds_read_b128 v[154:157], v148
	ds_read_b128 v[158:161], v148 offset:1024
	ds_read_b128 v[162:165], v148 offset:2048
	ds_read_b128 v[166:169], v148 offset:3072
	v_add_u32_e32 v148, s79, v151
	ds_read_b128 v[170:173], v148
	ds_read_b128 v[174:177], v148 offset:1024
	ds_read_b128 v[178:181], v148 offset:2048
	ds_read_b128 v[182:185], v148 offset:3072
	s_add_i32 s90, s62, 2
	s_add_u32 s63, s60, 0xfff80080
	s_addc_u32 s64, s61, -1
	s_cmp_eq_u32 s77, s62
	s_cselect_b32 s62, s87, s88
	s_cselect_b32 s65, s51, s64
	s_cselect_b32 s64, s53, s63
	s_cselect_b32 s63, s86, s89
	v_lshl_add_u64 v[148:149], s[60:61], 0, v[140:141]
	s_add_i32 m0, s33, 0xc000
	ds_read_b128 v[186:189], v152
	ds_read_b128 v[190:193], v152 offset:1024
	ds_read_b128 v[194:197], v152 offset:2048
	ds_read_b128 v[202:205], v152 offset:3072
	ds_read_b128 v[206:209], v152 offset:4096
	ds_read_b128 v[210:213], v152 offset:5120
	ds_read_b128 v[214:217], v152 offset:6144
	ds_read_b128 v[218:221], v152 offset:7168
	global_load_lds_dwordx4 v[148:149], off
	v_lshl_add_u64 v[148:149], s[60:61], 0, v[142:143]
	s_add_i32 m0, s33, 0xe000
	s_nop 0
	global_load_lds_dwordx4 v[148:149], off
	s_waitcnt vmcnt(8)
	s_waitcnt lgkmcnt(0)
	s_barrier
	s_setprio 1
	s_waitcnt lgkmcnt(0)
	v_mfma_i32_16x16x64_i8 v[124:127], v[154:157], v[186:189], v[124:127]
	v_mfma_i32_16x16x64_i8 v[92:95], v[162:165], v[186:189], v[92:95]
	v_mfma_i32_16x16x64_i8 v[120:123], v[154:157], v[194:197], v[120:123]
	v_mfma_i32_16x16x64_i8 v[88:91], v[162:165], v[194:197], v[88:91]
	v_mfma_i32_16x16x64_i8 v[116:119], v[154:157], v[206:209], v[116:119]
	v_mfma_i32_16x16x64_i8 v[84:87], v[162:165], v[206:209], v[84:87]
	v_mfma_i32_16x16x64_i8 v[112:115], v[154:157], v[214:217], v[112:115]
	v_mfma_i32_16x16x64_i8 v[80:83], v[162:165], v[214:217], v[80:83]
	v_mfma_i32_16x16x64_i8 v[124:127], v[158:161], v[190:193], v[124:127]
	v_mfma_i32_16x16x64_i8 v[92:95], v[166:169], v[190:193], v[92:95]
	v_mfma_i32_16x16x64_i8 v[120:123], v[158:161], v[202:205], v[120:123]
	v_mfma_i32_16x16x64_i8 v[88:91], v[166:169], v[202:205], v[88:91]
	v_mfma_i32_16x16x64_i8 v[116:119], v[158:161], v[210:213], v[116:119]
	v_mfma_i32_16x16x64_i8 v[84:87], v[166:169], v[210:213], v[84:87]
	v_mfma_i32_16x16x64_i8 v[112:115], v[158:161], v[218:221], v[112:115]
	v_mfma_i32_16x16x64_i8 v[80:83], v[166:169], v[218:221], v[80:83]
	s_setprio 0
	s_setprio 1
	v_mfma_i32_16x16x64_i8 v[60:63], v[170:173], v[186:189], v[60:63]
	v_mfma_i32_16x16x64_i8 v[28:31], v[178:181], v[186:189], v[28:31]
	v_mfma_i32_16x16x64_i8 v[56:59], v[170:173], v[194:197], v[56:59]
	v_mfma_i32_16x16x64_i8 v[24:27], v[178:181], v[194:197], v[24:27]
	v_mfma_i32_16x16x64_i8 v[52:55], v[170:173], v[206:209], v[52:55]
	v_mfma_i32_16x16x64_i8 v[20:23], v[178:181], v[206:209], v[20:23]
	v_mfma_i32_16x16x64_i8 v[48:51], v[170:173], v[214:217], v[48:51]
	v_mfma_i32_16x16x64_i8 v[16:19], v[178:181], v[214:217], v[16:19]
	v_mfma_i32_16x16x64_i8 v[60:63], v[174:177], v[190:193], v[60:63]
	v_mfma_i32_16x16x64_i8 v[28:31], v[182:185], v[190:193], v[28:31]
	v_mfma_i32_16x16x64_i8 v[56:59], v[174:177], v[202:205], v[56:59]
	v_mfma_i32_16x16x64_i8 v[24:27], v[182:185], v[202:205], v[24:27]
	v_mfma_i32_16x16x64_i8 v[52:55], v[174:177], v[210:213], v[52:55]
	v_mfma_i32_16x16x64_i8 v[20:23], v[182:185], v[210:213], v[20:23]
	v_mfma_i32_16x16x64_i8 v[48:51], v[174:177], v[218:221], v[48:51]
	v_mfma_i32_16x16x64_i8 v[16:19], v[182:185], v[218:221], v[16:19]
	s_setprio 0
	s_barrier
	s_add_i32 s91, s78, s31
	v_lshl_add_u64 v[148:149], s[62:63], 0, v[130:131]
	s_mov_b32 m0, s91
	ds_read_b128 v[186:189], v152 offset:16384
	ds_read_b128 v[190:193], v152 offset:17408
	ds_read_b128 v[194:197], v152 offset:18432
	ds_read_b128 v[202:205], v152 offset:19456
	ds_read_b128 v[206:209], v152 offset:20480
	ds_read_b128 v[210:213], v152 offset:21504
	ds_read_b128 v[214:217], v152 offset:22528
	ds_read_b128 v[218:221], v152 offset:23552
	global_load_lds_dwordx4 v[148:149], off
	s_add_i32 m0, s91, 0x2000
	s_add_u32 s92, s62, 0x80000
	v_lshl_add_u64 v[198:199], s[62:63], 0, v[134:135]
	s_addc_u32 s93, s63, 0
	s_add_i32 s91, s79, s31
	global_load_lds_dwordx4 v[198:199], off
	v_lshl_add_u64 v[222:223], s[92:93], 0, v[130:131]
	s_mov_b32 m0, s91
	v_lshl_add_u64 v[224:225], s[64:65], 0, v[132:133]
	global_load_lds_dwordx4 v[222:223], off
	v_lshl_add_u64 v[222:223], s[92:93], 0, v[134:135]
	s_add_i32 m0, s91, 0x2000
	s_nop 0
	global_load_lds_dwordx4 v[222:223], off
	v_lshl_add_u64 v[222:223], s[64:65], 0, v[128:129]
	s_mov_b32 m0, s33
	s_nop 0
	global_load_lds_dwordx4 v[222:223], off
	s_mov_b32 m0, s34
	s_nop 0
	global_load_lds_dwordx4 v[224:225], off
	s_waitcnt vmcnt(8)
	s_waitcnt lgkmcnt(0)
	s_barrier
	s_setprio 1
	s_waitcnt lgkmcnt(0)
	v_mfma_i32_16x16x64_i8 v[108:111], v[154:157], v[186:189], v[108:111]
	v_mfma_i32_16x16x64_i8 v[76:79], v[162:165], v[186:189], v[76:79]
	v_mfma_i32_16x16x64_i8 v[104:107], v[154:157], v[194:197], v[104:107]
	v_mfma_i32_16x16x64_i8 v[72:75], v[162:165], v[194:197], v[72:75]
	v_mfma_i32_16x16x64_i8 v[100:103], v[154:157], v[206:209], v[100:103]
	v_mfma_i32_16x16x64_i8 v[68:71], v[162:165], v[206:209], v[68:71]
	v_mfma_i32_16x16x64_i8 v[96:99], v[154:157], v[214:217], v[96:99]
	v_mfma_i32_16x16x64_i8 v[64:67], v[162:165], v[214:217], v[64:67]
	v_mfma_i32_16x16x64_i8 v[108:111], v[158:161], v[190:193], v[108:111]
	v_mfma_i32_16x16x64_i8 v[76:79], v[166:169], v[190:193], v[76:79]
	v_mfma_i32_16x16x64_i8 v[104:107], v[158:161], v[202:205], v[104:107]
	v_mfma_i32_16x16x64_i8 v[72:75], v[166:169], v[202:205], v[72:75]
	v_mfma_i32_16x16x64_i8 v[100:103], v[158:161], v[210:213], v[100:103]
	v_mfma_i32_16x16x64_i8 v[68:71], v[166:169], v[210:213], v[68:71]
	v_mfma_i32_16x16x64_i8 v[96:99], v[158:161], v[218:221], v[96:99]
	v_mfma_i32_16x16x64_i8 v[64:67], v[166:169], v[218:221], v[64:67]
	s_setprio 0
	s_setprio 1
	v_mfma_i32_16x16x64_i8 v[44:47], v[170:173], v[186:189], v[44:47]
	v_mfma_i32_16x16x64_i8 v[12:15], v[178:181], v[186:189], v[12:15]
	v_mfma_i32_16x16x64_i8 v[40:43], v[170:173], v[194:197], v[40:43]
	v_mfma_i32_16x16x64_i8 v[8:11], v[178:181], v[194:197], v[8:11]
	v_mfma_i32_16x16x64_i8 v[36:39], v[170:173], v[206:209], v[36:39]
	v_mfma_i32_16x16x64_i8 v[4:7], v[178:181], v[206:209], v[4:7]
	v_mfma_i32_16x16x64_i8 v[32:35], v[170:173], v[214:217], v[32:35]
	v_mfma_i32_16x16x64_i8 v[0:3], v[178:181], v[214:217], v[0:3]
	v_mfma_i32_16x16x64_i8 v[44:47], v[174:177], v[190:193], v[44:47]
	v_mfma_i32_16x16x64_i8 v[12:15], v[182:185], v[190:193], v[12:15]
	v_mfma_i32_16x16x64_i8 v[40:43], v[174:177], v[202:205], v[40:43]
	v_mfma_i32_16x16x64_i8 v[8:11], v[182:185], v[202:205], v[8:11]
	v_mfma_i32_16x16x64_i8 v[36:39], v[174:177], v[210:213], v[36:39]
	v_mfma_i32_16x16x64_i8 v[4:7], v[182:185], v[210:213], v[4:7]
	v_mfma_i32_16x16x64_i8 v[32:35], v[174:177], v[218:221], v[32:35]
	v_mfma_i32_16x16x64_i8 v[0:3], v[182:185], v[218:221], v[0:3]
	s_setprio 0
	s_barrier
	s_add_i32 s91, 0, 0x18000
	v_add_u32_e32 v153, s91, v151
	s_add_i32 s92, 0, 0x1c000
	ds_read_b128 v[154:157], v153
	ds_read_b128 v[158:161], v153 offset:1024
	ds_read_b128 v[162:165], v153 offset:2048
	ds_read_b128 v[166:169], v153 offset:3072
	v_add_u32_e32 v153, s92, v151
	ds_read_b128 v[170:173], v153
	ds_read_b128 v[174:177], v153 offset:1024
	ds_read_b128 v[178:181], v153 offset:2048
	ds_read_b128 v[182:185], v153 offset:3072
	s_add_u32 s64, s64, 0x80000
	s_addc_u32 s65, s65, 0
	s_mov_b32 m0, s35
	v_lshl_add_u64 v[226:227], s[64:65], 0, v[128:129]
	ds_read_b128 v[186:189], v152 offset:32768
	ds_read_b128 v[190:193], v152 offset:33792
	ds_read_b128 v[194:197], v152 offset:34816
	ds_read_b128 v[202:205], v152 offset:35840
	ds_read_b128 v[206:209], v152 offset:36864
	ds_read_b128 v[210:213], v152 offset:37888
	ds_read_b128 v[214:217], v152 offset:38912
	ds_read_b128 v[218:221], v152 offset:39936
	global_load_lds_dwordx4 v[226:227], off
	v_lshl_add_u64 v[226:227], s[64:65], 0, v[132:133]
	s_mov_b32 m0, s59
	s_nop 0
	global_load_lds_dwordx4 v[226:227], off
	s_waitcnt vmcnt(8)
	s_waitcnt lgkmcnt(0)
	s_barrier
	s_setprio 1
	s_waitcnt lgkmcnt(0)
	v_mfma_i32_16x16x64_i8 v[124:127], v[154:157], v[186:189], v[124:127]
	v_mfma_i32_16x16x64_i8 v[92:95], v[162:165], v[186:189], v[92:95]
	v_mfma_i32_16x16x64_i8 v[120:123], v[154:157], v[194:197], v[120:123]
	v_mfma_i32_16x16x64_i8 v[88:91], v[162:165], v[194:197], v[88:91]
	v_mfma_i32_16x16x64_i8 v[116:119], v[154:157], v[206:209], v[116:119]
	v_mfma_i32_16x16x64_i8 v[84:87], v[162:165], v[206:209], v[84:87]
	v_mfma_i32_16x16x64_i8 v[112:115], v[154:157], v[214:217], v[112:115]
	v_mfma_i32_16x16x64_i8 v[80:83], v[162:165], v[214:217], v[80:83]
	v_mfma_i32_16x16x64_i8 v[124:127], v[158:161], v[190:193], v[124:127]
	v_mfma_i32_16x16x64_i8 v[92:95], v[166:169], v[190:193], v[92:95]
	v_mfma_i32_16x16x64_i8 v[120:123], v[158:161], v[202:205], v[120:123]
	v_mfma_i32_16x16x64_i8 v[88:91], v[166:169], v[202:205], v[88:91]
	v_mfma_i32_16x16x64_i8 v[116:119], v[158:161], v[210:213], v[116:119]
	v_mfma_i32_16x16x64_i8 v[84:87], v[166:169], v[210:213], v[84:87]
	v_mfma_i32_16x16x64_i8 v[112:115], v[158:161], v[218:221], v[112:115]
	v_mfma_i32_16x16x64_i8 v[80:83], v[166:169], v[218:221], v[80:83]
	s_setprio 0
	s_setprio 1
	v_mfma_i32_16x16x64_i8 v[60:63], v[170:173], v[186:189], v[60:63]
	v_mfma_i32_16x16x64_i8 v[28:31], v[178:181], v[186:189], v[28:31]
	v_mfma_i32_16x16x64_i8 v[56:59], v[170:173], v[194:197], v[56:59]
	v_mfma_i32_16x16x64_i8 v[24:27], v[178:181], v[194:197], v[24:27]
	v_mfma_i32_16x16x64_i8 v[52:55], v[170:173], v[206:209], v[52:55]
	v_mfma_i32_16x16x64_i8 v[20:23], v[178:181], v[206:209], v[20:23]
	v_mfma_i32_16x16x64_i8 v[48:51], v[170:173], v[214:217], v[48:51]
	v_mfma_i32_16x16x64_i8 v[16:19], v[178:181], v[214:217], v[16:19]
	v_mfma_i32_16x16x64_i8 v[60:63], v[174:177], v[190:193], v[60:63]
	v_mfma_i32_16x16x64_i8 v[28:31], v[182:185], v[190:193], v[28:31]
	v_mfma_i32_16x16x64_i8 v[56:59], v[174:177], v[202:205], v[56:59]
	v_mfma_i32_16x16x64_i8 v[24:27], v[182:185], v[202:205], v[24:27]
	v_mfma_i32_16x16x64_i8 v[52:55], v[174:177], v[210:213], v[52:55]
	v_mfma_i32_16x16x64_i8 v[20:23], v[182:185], v[210:213], v[20:23]
	v_mfma_i32_16x16x64_i8 v[48:51], v[174:177], v[218:221], v[48:51]
	v_mfma_i32_16x16x64_i8 v[16:19], v[182:185], v[218:221], v[16:19]
	s_setprio 0
	s_barrier
	s_add_i32 s64, s91, s31
	v_lshl_add_u64 v[148:149], v[148:149], 0, s[22:23]
	s_mov_b32 m0, s64
	ds_read_b128 v[186:189], v152 offset:49152
	ds_read_b128 v[190:193], v152 offset:50176
	ds_read_b128 v[194:197], v152 offset:51200
	ds_read_b128 v[202:205], v152 offset:52224
	ds_read_b128 v[206:209], v152 offset:53248
	ds_read_b128 v[210:213], v152 offset:54272
	ds_read_b128 v[214:217], v152 offset:55296
	ds_read_b128 v[218:221], v152 offset:56320
	global_load_lds_dwordx4 v[148:149], off
	s_add_i32 m0, s64, 0x2000
	s_add_u32 s62, s62, 0x80080
	v_lshl_add_u64 v[148:149], v[198:199], 0, s[22:23]
	s_addc_u32 s63, s63, 0
	s_add_i32 s64, s92, s31
	global_load_lds_dwordx4 v[148:149], off
	v_lshl_add_u64 v[148:149], s[62:63], 0, v[130:131]
	s_mov_b32 m0, s64
	s_nop 0
	global_load_lds_dwordx4 v[148:149], off
	v_lshl_add_u64 v[148:149], s[62:63], 0, v[134:135]
	s_add_i32 m0, s64, 0x2000
	s_nop 0
	global_load_lds_dwordx4 v[148:149], off
	v_lshl_add_u64 v[148:149], v[222:223], 0, s[22:23]
	s_mov_b32 m0, s67
	s_nop 0
	global_load_lds_dwordx4 v[148:149], off
	v_lshl_add_u64 v[148:149], v[224:225], 0, s[22:23]
	s_mov_b32 m0, s76
	s_nop 0
	global_load_lds_dwordx4 v[148:149], off
	s_waitcnt vmcnt(8)
	s_waitcnt lgkmcnt(0)
	s_barrier
	s_setprio 1
	s_waitcnt lgkmcnt(0)
	v_mfma_i32_16x16x64_i8 v[108:111], v[154:157], v[186:189], v[108:111]
	v_mfma_i32_16x16x64_i8 v[76:79], v[162:165], v[186:189], v[76:79]
	v_mfma_i32_16x16x64_i8 v[104:107], v[154:157], v[194:197], v[104:107]
	v_mfma_i32_16x16x64_i8 v[72:75], v[162:165], v[194:197], v[72:75]
	v_mfma_i32_16x16x64_i8 v[100:103], v[154:157], v[206:209], v[100:103]
	v_mfma_i32_16x16x64_i8 v[68:71], v[162:165], v[206:209], v[68:71]
	v_mfma_i32_16x16x64_i8 v[96:99], v[154:157], v[214:217], v[96:99]
	v_mfma_i32_16x16x64_i8 v[64:67], v[162:165], v[214:217], v[64:67]
	v_mfma_i32_16x16x64_i8 v[108:111], v[158:161], v[190:193], v[108:111]
	v_mfma_i32_16x16x64_i8 v[76:79], v[166:169], v[190:193], v[76:79]
	v_mfma_i32_16x16x64_i8 v[104:107], v[158:161], v[202:205], v[104:107]
	v_mfma_i32_16x16x64_i8 v[72:75], v[166:169], v[202:205], v[72:75]
	v_mfma_i32_16x16x64_i8 v[100:103], v[158:161], v[210:213], v[100:103]
	v_mfma_i32_16x16x64_i8 v[68:71], v[166:169], v[210:213], v[68:71]
	v_mfma_i32_16x16x64_i8 v[96:99], v[158:161], v[218:221], v[96:99]
	v_mfma_i32_16x16x64_i8 v[64:67], v[166:169], v[218:221], v[64:67]
	s_setprio 0
	s_setprio 1
	v_mfma_i32_16x16x64_i8 v[44:47], v[170:173], v[186:189], v[44:47]
	v_mfma_i32_16x16x64_i8 v[12:15], v[178:181], v[186:189], v[12:15]
	v_mfma_i32_16x16x64_i8 v[40:43], v[170:173], v[194:197], v[40:43]
	v_mfma_i32_16x16x64_i8 v[8:11], v[178:181], v[194:197], v[8:11]
	v_mfma_i32_16x16x64_i8 v[36:39], v[170:173], v[206:209], v[36:39]
	v_mfma_i32_16x16x64_i8 v[4:7], v[178:181], v[206:209], v[4:7]
	v_mfma_i32_16x16x64_i8 v[32:35], v[170:173], v[214:217], v[32:35]
	v_mfma_i32_16x16x64_i8 v[0:3], v[178:181], v[214:217], v[0:3]
	v_mfma_i32_16x16x64_i8 v[44:47], v[174:177], v[190:193], v[44:47]
	v_mfma_i32_16x16x64_i8 v[12:15], v[182:185], v[190:193], v[12:15]
	v_mfma_i32_16x16x64_i8 v[40:43], v[174:177], v[202:205], v[40:43]
	v_mfma_i32_16x16x64_i8 v[8:11], v[182:185], v[202:205], v[8:11]
	v_mfma_i32_16x16x64_i8 v[36:39], v[174:177], v[210:213], v[36:39]
	v_mfma_i32_16x16x64_i8 v[4:7], v[182:185], v[210:213], v[4:7]
	v_mfma_i32_16x16x64_i8 v[32:35], v[174:177], v[218:221], v[32:35]
	v_mfma_i32_16x16x64_i8 v[0:3], v[182:185], v[218:221], v[0:3]
	s_setprio 0
	s_add_u32 s60, s60, 0x100
	s_addc_u32 s61, s61, 0
	s_add_u32 s88, s88, 0x100
	s_addc_u32 s89, s89, 0
	s_cmp_ge_i32 s90, s18
	s_mov_b32 s62, s90
	s_barrier
	s_cbranch_scc0 .LBB0_2155
	s_and_b64 vcc, exec, s[24:25]
	s_cbranch_vccz .LBB0_2158

.LBB0_2369:
	v_add_u32_e32 v132, s58, v159
	ds_read_b128 v[142:145], v132
	ds_read_b128 v[146:149], v132 offset:1024
	ds_read_b128 v[150:153], v132 offset:2048
	ds_read_b128 v[154:157], v132 offset:3072
	v_add_u32_e32 v132, s59, v159
	ds_read_b128 v[162:165], v132
	ds_read_b128 v[166:169], v132 offset:1024
	ds_read_b128 v[170:173], v132 offset:2048
	ds_read_b128 v[174:177], v132 offset:3072
	s_add_i32 s65, s50, 2
	s_add_u32 s51, s48, 0xfff80080
	s_addc_u32 s52, s49, -1
	s_cmp_eq_u32 s57, s50
	s_cselect_b32 s50, s62, s63
	s_cselect_b32 s53, s25, s52
	s_cselect_b32 s52, s27, s51
	s_cselect_b32 s51, s61, s64
	v_lshl_add_u64 v[198:199], s[48:49], 0, v[134:135]
	s_add_i32 m0, s33, 0xc000
	ds_read_b128 v[178:181], v161
	ds_read_b128 v[182:185], v161 offset:1024
	ds_read_b128 v[186:189], v161 offset:2048
	ds_read_b128 v[190:193], v161 offset:3072
	ds_read_b128 v[194:197], v161 offset:4096
	ds_read_b128 v[202:205], v161 offset:5120
	ds_read_b128 v[206:209], v161 offset:6144
	ds_read_b128 v[210:213], v161 offset:7168
	global_load_lds_dwordx4 v[198:199], off
	v_lshl_add_u64 v[198:199], s[48:49], 0, v[136:137]
	s_add_i32 m0, s33, 0xe000
	s_nop 0
	global_load_lds_dwordx4 v[198:199], off
	s_waitcnt vmcnt(8)
	s_waitcnt lgkmcnt(0)
	s_barrier
	s_setprio 1
	s_waitcnt lgkmcnt(0)
	v_mfma_i32_16x16x64_i8 v[124:127], v[142:145], v[178:181], v[124:127]
	v_mfma_i32_16x16x64_i8 v[120:123], v[150:153], v[178:181], v[120:123]
	v_mfma_i32_16x16x64_i8 v[108:111], v[142:145], v[186:189], v[108:111]
	v_mfma_i32_16x16x64_i8 v[104:107], v[150:153], v[186:189], v[104:107]
	v_mfma_i32_16x16x64_i8 v[92:95], v[142:145], v[194:197], v[92:95]
	v_mfma_i32_16x16x64_i8 v[88:91], v[150:153], v[194:197], v[88:91]
	v_mfma_i32_16x16x64_i8 v[76:79], v[142:145], v[206:209], v[76:79]
	v_mfma_i32_16x16x64_i8 v[72:75], v[150:153], v[206:209], v[72:75]
	v_mfma_i32_16x16x64_i8 v[124:127], v[146:149], v[182:185], v[124:127]
	v_mfma_i32_16x16x64_i8 v[120:123], v[154:157], v[182:185], v[120:123]
	v_mfma_i32_16x16x64_i8 v[108:111], v[146:149], v[190:193], v[108:111]
	v_mfma_i32_16x16x64_i8 v[104:107], v[154:157], v[190:193], v[104:107]
	v_mfma_i32_16x16x64_i8 v[92:95], v[146:149], v[202:205], v[92:95]
	v_mfma_i32_16x16x64_i8 v[88:91], v[154:157], v[202:205], v[88:91]
	v_mfma_i32_16x16x64_i8 v[76:79], v[146:149], v[210:213], v[76:79]
	v_mfma_i32_16x16x64_i8 v[72:75], v[154:157], v[210:213], v[72:75]
	s_setprio 0
	s_setprio 1
	v_mfma_i32_16x16x64_i8 v[116:119], v[162:165], v[178:181], v[116:119]
	v_mfma_i32_16x16x64_i8 v[112:115], v[170:173], v[178:181], v[112:115]
	v_mfma_i32_16x16x64_i8 v[100:103], v[162:165], v[186:189], v[100:103]
	v_mfma_i32_16x16x64_i8 v[96:99], v[170:173], v[186:189], v[96:99]
	v_mfma_i32_16x16x64_i8 v[84:87], v[162:165], v[194:197], v[84:87]
	v_mfma_i32_16x16x64_i8 v[80:83], v[170:173], v[194:197], v[80:83]
	v_mfma_i32_16x16x64_i8 v[68:71], v[162:165], v[206:209], v[68:71]
	v_mfma_i32_16x16x64_i8 v[64:67], v[170:173], v[206:209], v[64:67]
	v_mfma_i32_16x16x64_i8 v[116:119], v[166:169], v[182:185], v[116:119]
	v_mfma_i32_16x16x64_i8 v[112:115], v[174:177], v[182:185], v[112:115]
	v_mfma_i32_16x16x64_i8 v[100:103], v[166:169], v[190:193], v[100:103]
	v_mfma_i32_16x16x64_i8 v[96:99], v[174:177], v[190:193], v[96:99]
	v_mfma_i32_16x16x64_i8 v[84:87], v[166:169], v[202:205], v[84:87]
	v_mfma_i32_16x16x64_i8 v[80:83], v[174:177], v[202:205], v[80:83]
	v_mfma_i32_16x16x64_i8 v[68:71], v[166:169], v[210:213], v[68:71]
	v_mfma_i32_16x16x64_i8 v[64:67], v[174:177], v[210:213], v[64:67]
	s_setprio 0
	s_barrier
	s_add_i32 s66, s58, s31
	v_lshl_add_u64 v[198:199], s[50:51], 0, v[128:129]
	s_mov_b32 m0, s66
	ds_read_b128 v[178:181], v161 offset:16384
	ds_read_b128 v[182:185], v161 offset:17408
	ds_read_b128 v[186:189], v161 offset:18432
	ds_read_b128 v[190:193], v161 offset:19456
	ds_read_b128 v[194:197], v161 offset:20480
	ds_read_b128 v[202:205], v161 offset:21504
	ds_read_b128 v[206:209], v161 offset:22528
	ds_read_b128 v[210:213], v161 offset:23552
	global_load_lds_dwordx4 v[198:199], off
	s_add_i32 m0, s66, 0x2000
	s_add_u32 s66, s50, 0x80000
	v_lshl_add_u64 v[214:215], s[50:51], 0, v[130:131]
	s_addc_u32 s67, s51, 0
	s_add_i32 s76, s59, s31
	global_load_lds_dwordx4 v[214:215], off
	v_lshl_add_u64 v[216:217], s[66:67], 0, v[128:129]
	s_mov_b32 m0, s76
	v_lshl_add_u64 v[218:219], s[52:53], 0, v[130:131]
	global_load_lds_dwordx4 v[216:217], off
	v_lshl_add_u64 v[216:217], s[66:67], 0, v[130:131]
	s_add_i32 m0, s76, 0x2000
	s_nop 0
	global_load_lds_dwordx4 v[216:217], off
	v_lshl_add_u64 v[216:217], s[52:53], 0, v[128:129]
	s_mov_b32 m0, s33
	s_nop 0
	global_load_lds_dwordx4 v[216:217], off
	s_mov_b32 m0, s34
	s_nop 0
	global_load_lds_dwordx4 v[218:219], off
	s_waitcnt vmcnt(8)
	s_waitcnt lgkmcnt(0)
	s_barrier
	s_setprio 1
	s_waitcnt lgkmcnt(0)
	v_mfma_i32_16x16x64_i8 v[60:63], v[142:145], v[178:181], v[60:63]
	v_mfma_i32_16x16x64_i8 v[56:59], v[150:153], v[178:181], v[56:59]
	v_mfma_i32_16x16x64_i8 v[44:47], v[142:145], v[186:189], v[44:47]
	v_mfma_i32_16x16x64_i8 v[40:43], v[150:153], v[186:189], v[40:43]
	v_mfma_i32_16x16x64_i8 v[28:31], v[142:145], v[194:197], v[28:31]
	v_mfma_i32_16x16x64_i8 v[24:27], v[150:153], v[194:197], v[24:27]
	v_mfma_i32_16x16x64_i8 v[12:15], v[142:145], v[206:209], v[12:15]
	v_mfma_i32_16x16x64_i8 v[8:11], v[150:153], v[206:209], v[8:11]
	v_mfma_i32_16x16x64_i8 v[60:63], v[146:149], v[182:185], v[60:63]
	v_mfma_i32_16x16x64_i8 v[56:59], v[154:157], v[182:185], v[56:59]
	v_mfma_i32_16x16x64_i8 v[44:47], v[146:149], v[190:193], v[44:47]
	v_mfma_i32_16x16x64_i8 v[40:43], v[154:157], v[190:193], v[40:43]
	v_mfma_i32_16x16x64_i8 v[28:31], v[146:149], v[202:205], v[28:31]
	v_mfma_i32_16x16x64_i8 v[24:27], v[154:157], v[202:205], v[24:27]
	v_mfma_i32_16x16x64_i8 v[12:15], v[146:149], v[210:213], v[12:15]
	v_mfma_i32_16x16x64_i8 v[8:11], v[154:157], v[210:213], v[8:11]
	s_setprio 0
	s_setprio 1
	v_mfma_i32_16x16x64_i8 v[52:55], v[162:165], v[178:181], v[52:55]
	v_mfma_i32_16x16x64_i8 v[48:51], v[170:173], v[178:181], v[48:51]
	v_mfma_i32_16x16x64_i8 v[36:39], v[162:165], v[186:189], v[36:39]
	v_mfma_i32_16x16x64_i8 v[32:35], v[170:173], v[186:189], v[32:35]
	v_mfma_i32_16x16x64_i8 v[20:23], v[162:165], v[194:197], v[20:23]
	v_mfma_i32_16x16x64_i8 v[16:19], v[170:173], v[194:197], v[16:19]
	v_mfma_i32_16x16x64_i8 v[4:7], v[162:165], v[206:209], v[4:7]
	v_mfma_i32_16x16x64_i8 v[0:3], v[170:173], v[206:209], v[0:3]
	v_mfma_i32_16x16x64_i8 v[52:55], v[166:169], v[182:185], v[52:55]
	v_mfma_i32_16x16x64_i8 v[48:51], v[174:177], v[182:185], v[48:51]
	v_mfma_i32_16x16x64_i8 v[36:39], v[166:169], v[190:193], v[36:39]
	v_mfma_i32_16x16x64_i8 v[32:35], v[174:177], v[190:193], v[32:35]
	v_mfma_i32_16x16x64_i8 v[20:23], v[166:169], v[202:205], v[20:23]
	v_mfma_i32_16x16x64_i8 v[16:19], v[174:177], v[202:205], v[16:19]
	v_mfma_i32_16x16x64_i8 v[4:7], v[166:169], v[210:213], v[4:7]
	v_mfma_i32_16x16x64_i8 v[0:3], v[174:177], v[210:213], v[0:3]
	s_setprio 0
	s_barrier
	s_add_i32 s66, 0, 0x18000
	v_add_u32_e32 v132, s66, v159
	s_add_i32 s67, 0, 0x1c000
	ds_read_b128 v[142:145], v132
	ds_read_b128 v[146:149], v132 offset:1024
	ds_read_b128 v[150:153], v132 offset:2048
	ds_read_b128 v[154:157], v132 offset:3072
	v_add_u32_e32 v132, s67, v159
	ds_read_b128 v[162:165], v132
	ds_read_b128 v[166:169], v132 offset:1024
	ds_read_b128 v[170:173], v132 offset:2048
	ds_read_b128 v[174:177], v132 offset:3072
	s_add_u32 s52, s52, 0x80000
	s_addc_u32 s53, s53, 0
	s_mov_b32 m0, s35
	v_lshl_add_u64 v[220:221], s[52:53], 0, v[128:129]
	ds_read_b128 v[178:181], v161 offset:32768
	ds_read_b128 v[182:185], v161 offset:33792
	ds_read_b128 v[186:189], v161 offset:34816
	ds_read_b128 v[190:193], v161 offset:35840
	ds_read_b128 v[194:197], v161 offset:36864
	ds_read_b128 v[202:205], v161 offset:37888
	ds_read_b128 v[206:209], v161 offset:38912
	ds_read_b128 v[210:213], v161 offset:39936
	global_load_lds_dwordx4 v[220:221], off
	v_lshl_add_u64 v[220:221], s[52:53], 0, v[130:131]
	s_mov_b32 m0, s45
	s_nop 0
	global_load_lds_dwordx4 v[220:221], off
	s_waitcnt vmcnt(8)
	s_waitcnt lgkmcnt(0)
	s_barrier
	s_setprio 1
	s_waitcnt lgkmcnt(0)
	v_mfma_i32_16x16x64_i8 v[124:127], v[142:145], v[178:181], v[124:127]
	v_mfma_i32_16x16x64_i8 v[120:123], v[150:153], v[178:181], v[120:123]
	v_mfma_i32_16x16x64_i8 v[108:111], v[142:145], v[186:189], v[108:111]
	v_mfma_i32_16x16x64_i8 v[104:107], v[150:153], v[186:189], v[104:107]
	v_mfma_i32_16x16x64_i8 v[92:95], v[142:145], v[194:197], v[92:95]
	v_mfma_i32_16x16x64_i8 v[88:91], v[150:153], v[194:197], v[88:91]
	v_mfma_i32_16x16x64_i8 v[76:79], v[142:145], v[206:209], v[76:79]
	v_mfma_i32_16x16x64_i8 v[72:75], v[150:153], v[206:209], v[72:75]
	v_mfma_i32_16x16x64_i8 v[124:127], v[146:149], v[182:185], v[124:127]
	v_mfma_i32_16x16x64_i8 v[120:123], v[154:157], v[182:185], v[120:123]
	v_mfma_i32_16x16x64_i8 v[108:111], v[146:149], v[190:193], v[108:111]
	v_mfma_i32_16x16x64_i8 v[104:107], v[154:157], v[190:193], v[104:107]
	v_mfma_i32_16x16x64_i8 v[92:95], v[146:149], v[202:205], v[92:95]
	v_mfma_i32_16x16x64_i8 v[88:91], v[154:157], v[202:205], v[88:91]
	v_mfma_i32_16x16x64_i8 v[76:79], v[146:149], v[210:213], v[76:79]
	v_mfma_i32_16x16x64_i8 v[72:75], v[154:157], v[210:213], v[72:75]
	s_setprio 0
	s_setprio 1
	v_mfma_i32_16x16x64_i8 v[116:119], v[162:165], v[178:181], v[116:119]
	v_mfma_i32_16x16x64_i8 v[112:115], v[170:173], v[178:181], v[112:115]
	v_mfma_i32_16x16x64_i8 v[100:103], v[162:165], v[186:189], v[100:103]
	v_mfma_i32_16x16x64_i8 v[96:99], v[170:173], v[186:189], v[96:99]
	v_mfma_i32_16x16x64_i8 v[84:87], v[162:165], v[194:197], v[84:87]
	v_mfma_i32_16x16x64_i8 v[80:83], v[170:173], v[194:197], v[80:83]
	v_mfma_i32_16x16x64_i8 v[68:71], v[162:165], v[206:209], v[68:71]
	v_mfma_i32_16x16x64_i8 v[64:67], v[170:173], v[206:209], v[64:67]
	v_mfma_i32_16x16x64_i8 v[116:119], v[166:169], v[182:185], v[116:119]
	v_mfma_i32_16x16x64_i8 v[112:115], v[174:177], v[182:185], v[112:115]
	v_mfma_i32_16x16x64_i8 v[100:103], v[166:169], v[190:193], v[100:103]
	v_mfma_i32_16x16x64_i8 v[96:99], v[174:177], v[190:193], v[96:99]
	v_mfma_i32_16x16x64_i8 v[84:87], v[166:169], v[202:205], v[84:87]
	v_mfma_i32_16x16x64_i8 v[80:83], v[174:177], v[202:205], v[80:83]
	v_mfma_i32_16x16x64_i8 v[68:71], v[166:169], v[210:213], v[68:71]
	v_mfma_i32_16x16x64_i8 v[64:67], v[174:177], v[210:213], v[64:67]
	s_setprio 0
	s_barrier
	s_add_i32 s52, s66, s31
	v_lshl_add_u64 v[198:199], v[198:199], 0, s[12:13]
	s_mov_b32 m0, s52
	ds_read_b128 v[178:181], v161 offset:49152
	ds_read_b128 v[182:185], v161 offset:50176
	ds_read_b128 v[186:189], v161 offset:51200
	ds_read_b128 v[190:193], v161 offset:52224
	ds_read_b128 v[194:197], v161 offset:53248
	ds_read_b128 v[202:205], v161 offset:54272
	ds_read_b128 v[206:209], v161 offset:55296
	ds_read_b128 v[210:213], v161 offset:56320
	global_load_lds_dwordx4 v[198:199], off
	s_add_i32 m0, s52, 0x2000
	s_add_u32 s50, s50, 0x80080
	v_lshl_add_u64 v[198:199], v[214:215], 0, s[12:13]
	s_addc_u32 s51, s51, 0
	s_add_i32 s52, s67, s31
	global_load_lds_dwordx4 v[198:199], off
	v_lshl_add_u64 v[198:199], s[50:51], 0, v[128:129]
	s_mov_b32 m0, s52
	s_nop 0
	global_load_lds_dwordx4 v[198:199], off
	v_lshl_add_u64 v[198:199], s[50:51], 0, v[130:131]
	s_add_i32 m0, s52, 0x2000
	s_nop 0
	global_load_lds_dwordx4 v[198:199], off
	v_lshl_add_u64 v[198:199], v[216:217], 0, s[12:13]
	s_mov_b32 m0, s55
	s_nop 0
	global_load_lds_dwordx4 v[198:199], off
	v_lshl_add_u64 v[198:199], v[218:219], 0, s[12:13]
	s_mov_b32 m0, s56
	s_nop 0
	global_load_lds_dwordx4 v[198:199], off
	s_waitcnt vmcnt(8)
	s_waitcnt lgkmcnt(0)
	s_barrier
	s_setprio 1
	s_waitcnt lgkmcnt(0)
	v_mfma_i32_16x16x64_i8 v[60:63], v[142:145], v[178:181], v[60:63]
	v_mfma_i32_16x16x64_i8 v[56:59], v[150:153], v[178:181], v[56:59]
	v_mfma_i32_16x16x64_i8 v[44:47], v[142:145], v[186:189], v[44:47]
	v_mfma_i32_16x16x64_i8 v[40:43], v[150:153], v[186:189], v[40:43]
	v_mfma_i32_16x16x64_i8 v[28:31], v[142:145], v[194:197], v[28:31]
	v_mfma_i32_16x16x64_i8 v[24:27], v[150:153], v[194:197], v[24:27]
	v_mfma_i32_16x16x64_i8 v[12:15], v[142:145], v[206:209], v[12:15]
	v_mfma_i32_16x16x64_i8 v[8:11], v[150:153], v[206:209], v[8:11]
	v_mfma_i32_16x16x64_i8 v[60:63], v[146:149], v[182:185], v[60:63]
	v_mfma_i32_16x16x64_i8 v[56:59], v[154:157], v[182:185], v[56:59]
	v_mfma_i32_16x16x64_i8 v[44:47], v[146:149], v[190:193], v[44:47]
	v_mfma_i32_16x16x64_i8 v[40:43], v[154:157], v[190:193], v[40:43]
	v_mfma_i32_16x16x64_i8 v[28:31], v[146:149], v[202:205], v[28:31]
	v_mfma_i32_16x16x64_i8 v[24:27], v[154:157], v[202:205], v[24:27]
	v_mfma_i32_16x16x64_i8 v[12:15], v[146:149], v[210:213], v[12:15]
	v_mfma_i32_16x16x64_i8 v[8:11], v[154:157], v[210:213], v[8:11]
	s_setprio 0
	s_setprio 1
	v_mfma_i32_16x16x64_i8 v[52:55], v[162:165], v[178:181], v[52:55]
	v_mfma_i32_16x16x64_i8 v[48:51], v[170:173], v[178:181], v[48:51]
	v_mfma_i32_16x16x64_i8 v[36:39], v[162:165], v[186:189], v[36:39]
	v_mfma_i32_16x16x64_i8 v[32:35], v[170:173], v[186:189], v[32:35]
	v_mfma_i32_16x16x64_i8 v[20:23], v[162:165], v[194:197], v[20:23]
	v_mfma_i32_16x16x64_i8 v[16:19], v[170:173], v[194:197], v[16:19]
	v_mfma_i32_16x16x64_i8 v[4:7], v[162:165], v[206:209], v[4:7]
	v_mfma_i32_16x16x64_i8 v[0:3], v[170:173], v[206:209], v[0:3]
	v_mfma_i32_16x16x64_i8 v[52:55], v[166:169], v[182:185], v[52:55]
	v_mfma_i32_16x16x64_i8 v[48:51], v[174:177], v[182:185], v[48:51]
	v_mfma_i32_16x16x64_i8 v[36:39], v[166:169], v[190:193], v[36:39]
	v_mfma_i32_16x16x64_i8 v[32:35], v[174:177], v[190:193], v[32:35]
	v_mfma_i32_16x16x64_i8 v[20:23], v[166:169], v[202:205], v[20:23]
	v_mfma_i32_16x16x64_i8 v[16:19], v[174:177], v[202:205], v[16:19]
	v_mfma_i32_16x16x64_i8 v[4:7], v[166:169], v[210:213], v[4:7]
	v_mfma_i32_16x16x64_i8 v[0:3], v[174:177], v[210:213], v[0:3]
	s_setprio 0
	s_add_u32 s48, s48, 0x100
	s_addc_u32 s49, s49, 0
	s_add_u32 s63, s63, 0x100
	s_addc_u32 s64, s64, 0
	s_cmp_ge_i32 s65, s18
	s_mov_b32 s50, s65
	s_barrier
	s_cbranch_scc0 .LBB0_2369
	s_and_b64 vcc, exec, s[16:17]
	s_cbranch_vccz .LBB0_2372

.LBB0_2506:
	v_add_u32_e32 v140, s51, v158
	ds_read_b128 v[128:131], v140
	ds_read_b128 v[132:135], v140 offset:1024
	ds_read_b128 v[150:153], v140 offset:2048
	ds_read_b128 v[162:165], v140 offset:3072
	v_add_u32_e32 v140, s52, v158
	ds_read_b128 v[166:169], v140
	ds_read_b128 v[170:173], v140 offset:1024
	ds_read_b128 v[174:177], v140 offset:2048
	ds_read_b128 v[178:181], v140 offset:3072
	s_add_i32 s57, s10, 2
	s_add_u32 s11, s8, 0xfff80080
	s_addc_u32 s42, s9, -1
	s_cmp_eq_u32 s50, s10
	s_cselect_b32 s10, s54, s55
	s_cselect_b32 s43, s25, s42
	s_cselect_b32 s42, s27, s11
	s_cselect_b32 s11, s53, s56
	v_lshl_add_u64 v[154:155], s[8:9], 0, v[142:143]
	s_add_i32 m0, s33, 0xc000
	ds_read_b128 v[182:185], v160
	ds_read_b128 v[186:189], v160 offset:1024
	ds_read_b128 v[190:193], v160 offset:2048
	ds_read_b128 v[194:197], v160 offset:3072
	ds_read_b128 v[202:205], v160 offset:4096
	ds_read_b128 v[206:209], v160 offset:5120
	ds_read_b128 v[210:213], v160 offset:6144
	ds_read_b128 v[214:217], v160 offset:7168
	global_load_lds_dwordx4 v[154:155], off
	v_lshl_add_u64 v[154:155], s[8:9], 0, v[144:145]
	s_add_i32 m0, s33, 0xe000
	s_nop 0
	global_load_lds_dwordx4 v[154:155], off
	s_waitcnt vmcnt(8)
	s_waitcnt lgkmcnt(0)
	s_barrier
	s_setprio 1
	s_waitcnt lgkmcnt(0)
	v_mfma_i32_16x16x64_i8 v[124:127], v[128:131], v[182:185], v[124:127]
	v_mfma_i32_16x16x64_i8 v[120:123], v[150:153], v[182:185], v[120:123]
	v_mfma_i32_16x16x64_i8 v[108:111], v[128:131], v[190:193], v[108:111]
	v_mfma_i32_16x16x64_i8 v[104:107], v[150:153], v[190:193], v[104:107]
	v_mfma_i32_16x16x64_i8 v[92:95], v[128:131], v[202:205], v[92:95]
	v_mfma_i32_16x16x64_i8 v[88:91], v[150:153], v[202:205], v[88:91]
	v_mfma_i32_16x16x64_i8 v[76:79], v[128:131], v[210:213], v[76:79]
	v_mfma_i32_16x16x64_i8 v[72:75], v[150:153], v[210:213], v[72:75]
	v_mfma_i32_16x16x64_i8 v[124:127], v[132:135], v[186:189], v[124:127]
	v_mfma_i32_16x16x64_i8 v[120:123], v[162:165], v[186:189], v[120:123]
	v_mfma_i32_16x16x64_i8 v[108:111], v[132:135], v[194:197], v[108:111]
	v_mfma_i32_16x16x64_i8 v[104:107], v[162:165], v[194:197], v[104:107]
	v_mfma_i32_16x16x64_i8 v[92:95], v[132:135], v[206:209], v[92:95]
	v_mfma_i32_16x16x64_i8 v[88:91], v[162:165], v[206:209], v[88:91]
	v_mfma_i32_16x16x64_i8 v[76:79], v[132:135], v[214:217], v[76:79]
	v_mfma_i32_16x16x64_i8 v[72:75], v[162:165], v[214:217], v[72:75]
	s_setprio 0
	s_setprio 1
	v_mfma_i32_16x16x64_i8 v[116:119], v[166:169], v[182:185], v[116:119]
	v_mfma_i32_16x16x64_i8 v[112:115], v[174:177], v[182:185], v[112:115]
	v_mfma_i32_16x16x64_i8 v[100:103], v[166:169], v[190:193], v[100:103]
	v_mfma_i32_16x16x64_i8 v[96:99], v[174:177], v[190:193], v[96:99]
	v_mfma_i32_16x16x64_i8 v[84:87], v[166:169], v[202:205], v[84:87]
	v_mfma_i32_16x16x64_i8 v[80:83], v[174:177], v[202:205], v[80:83]
	v_mfma_i32_16x16x64_i8 v[68:71], v[166:169], v[210:213], v[68:71]
	v_mfma_i32_16x16x64_i8 v[64:67], v[174:177], v[210:213], v[64:67]
	v_mfma_i32_16x16x64_i8 v[116:119], v[170:173], v[186:189], v[116:119]
	v_mfma_i32_16x16x64_i8 v[112:115], v[178:181], v[186:189], v[112:115]
	v_mfma_i32_16x16x64_i8 v[100:103], v[170:173], v[194:197], v[100:103]
	v_mfma_i32_16x16x64_i8 v[96:99], v[178:181], v[194:197], v[96:99]
	v_mfma_i32_16x16x64_i8 v[84:87], v[170:173], v[206:209], v[84:87]
	v_mfma_i32_16x16x64_i8 v[80:83], v[178:181], v[206:209], v[80:83]
	v_mfma_i32_16x16x64_i8 v[68:71], v[170:173], v[214:217], v[68:71]
	v_mfma_i32_16x16x64_i8 v[64:67], v[178:181], v[214:217], v[64:67]
	s_setprio 0
	s_barrier
	s_add_i32 s58, s51, s31
	v_lshl_add_u64 v[154:155], s[10:11], 0, v[136:137]
	s_mov_b32 m0, s58
	ds_read_b128 v[182:185], v160 offset:16384
	ds_read_b128 v[186:189], v160 offset:17408
	ds_read_b128 v[190:193], v160 offset:18432
	ds_read_b128 v[194:197], v160 offset:19456
	ds_read_b128 v[202:205], v160 offset:20480
	ds_read_b128 v[206:209], v160 offset:21504
	ds_read_b128 v[210:213], v160 offset:22528
	ds_read_b128 v[214:217], v160 offset:23552
	global_load_lds_dwordx4 v[154:155], off
	s_add_i32 m0, s58, 0x2000
	s_add_u32 s58, s10, 0x80000
	v_lshl_add_u64 v[198:199], s[10:11], 0, v[138:139]
	s_addc_u32 s59, s11, 0
	s_add_i32 s60, s52, s31
	global_load_lds_dwordx4 v[198:199], off
	v_lshl_add_u64 v[218:219], s[58:59], 0, v[136:137]
	s_mov_b32 m0, s60
	v_lshl_add_u64 v[220:221], s[42:43], 0, v[138:139]
	global_load_lds_dwordx4 v[218:219], off
	v_lshl_add_u64 v[218:219], s[58:59], 0, v[138:139]
	s_add_i32 m0, s60, 0x2000
	s_nop 0
	global_load_lds_dwordx4 v[218:219], off
	v_lshl_add_u64 v[218:219], s[42:43], 0, v[136:137]
	s_mov_b32 m0, s33
	s_nop 0
	global_load_lds_dwordx4 v[218:219], off
	s_mov_b32 m0, s34
	s_nop 0
	global_load_lds_dwordx4 v[220:221], off
	s_waitcnt vmcnt(8)
	s_waitcnt lgkmcnt(0)
	s_barrier
	s_setprio 1
	s_waitcnt lgkmcnt(0)
	v_mfma_i32_16x16x64_i8 v[60:63], v[128:131], v[182:185], v[60:63]
	v_mfma_i32_16x16x64_i8 v[56:59], v[150:153], v[182:185], v[56:59]
	v_mfma_i32_16x16x64_i8 v[44:47], v[128:131], v[190:193], v[44:47]
	v_mfma_i32_16x16x64_i8 v[40:43], v[150:153], v[190:193], v[40:43]
	v_mfma_i32_16x16x64_i8 v[28:31], v[128:131], v[202:205], v[28:31]
	v_mfma_i32_16x16x64_i8 v[24:27], v[150:153], v[202:205], v[24:27]
	v_mfma_i32_16x16x64_i8 v[12:15], v[128:131], v[210:213], v[12:15]
	v_mfma_i32_16x16x64_i8 v[8:11], v[150:153], v[210:213], v[8:11]
	v_mfma_i32_16x16x64_i8 v[60:63], v[132:135], v[186:189], v[60:63]
	v_mfma_i32_16x16x64_i8 v[56:59], v[162:165], v[186:189], v[56:59]
	v_mfma_i32_16x16x64_i8 v[44:47], v[132:135], v[194:197], v[44:47]
	v_mfma_i32_16x16x64_i8 v[40:43], v[162:165], v[194:197], v[40:43]
	v_mfma_i32_16x16x64_i8 v[28:31], v[132:135], v[206:209], v[28:31]
	v_mfma_i32_16x16x64_i8 v[24:27], v[162:165], v[206:209], v[24:27]
	v_mfma_i32_16x16x64_i8 v[12:15], v[132:135], v[214:217], v[12:15]
	v_mfma_i32_16x16x64_i8 v[8:11], v[162:165], v[214:217], v[8:11]
	s_setprio 0
	s_setprio 1
	v_mfma_i32_16x16x64_i8 v[52:55], v[166:169], v[182:185], v[52:55]
	v_mfma_i32_16x16x64_i8 v[48:51], v[174:177], v[182:185], v[48:51]
	v_mfma_i32_16x16x64_i8 v[36:39], v[166:169], v[190:193], v[36:39]
	v_mfma_i32_16x16x64_i8 v[32:35], v[174:177], v[190:193], v[32:35]
	v_mfma_i32_16x16x64_i8 v[20:23], v[166:169], v[202:205], v[20:23]
	v_mfma_i32_16x16x64_i8 v[16:19], v[174:177], v[202:205], v[16:19]
	v_mfma_i32_16x16x64_i8 v[4:7], v[166:169], v[210:213], v[4:7]
	v_mfma_i32_16x16x64_i8 v[0:3], v[174:177], v[210:213], v[0:3]
	v_mfma_i32_16x16x64_i8 v[52:55], v[170:173], v[186:189], v[52:55]
	v_mfma_i32_16x16x64_i8 v[48:51], v[178:181], v[186:189], v[48:51]
	v_mfma_i32_16x16x64_i8 v[36:39], v[170:173], v[194:197], v[36:39]
	v_mfma_i32_16x16x64_i8 v[32:35], v[178:181], v[194:197], v[32:35]
	v_mfma_i32_16x16x64_i8 v[20:23], v[170:173], v[206:209], v[20:23]
	v_mfma_i32_16x16x64_i8 v[16:19], v[178:181], v[206:209], v[16:19]
	v_mfma_i32_16x16x64_i8 v[4:7], v[170:173], v[214:217], v[4:7]
	v_mfma_i32_16x16x64_i8 v[0:3], v[178:181], v[214:217], v[0:3]
	s_setprio 0
	s_barrier
	s_add_i32 s58, 0, 0x18000
	v_add_u32_e32 v140, s58, v158
	s_add_i32 s59, 0, 0x1c000
	ds_read_b128 v[128:131], v140
	ds_read_b128 v[132:135], v140 offset:1024
	ds_read_b128 v[150:153], v140 offset:2048
	ds_read_b128 v[162:165], v140 offset:3072
	v_add_u32_e32 v140, s59, v158
	ds_read_b128 v[166:169], v140
	ds_read_b128 v[170:173], v140 offset:1024
	ds_read_b128 v[174:177], v140 offset:2048
	ds_read_b128 v[178:181], v140 offset:3072
	s_add_u32 s42, s42, 0x80000
	s_addc_u32 s43, s43, 0
	s_mov_b32 m0, s35
	v_lshl_add_u64 v[222:223], s[42:43], 0, v[136:137]
	ds_read_b128 v[182:185], v160 offset:32768
	ds_read_b128 v[186:189], v160 offset:33792
	ds_read_b128 v[190:193], v160 offset:34816
	ds_read_b128 v[194:197], v160 offset:35840
	ds_read_b128 v[202:205], v160 offset:36864
	ds_read_b128 v[206:209], v160 offset:37888
	ds_read_b128 v[210:213], v160 offset:38912
	ds_read_b128 v[214:217], v160 offset:39936
	global_load_lds_dwordx4 v[222:223], off
	v_lshl_add_u64 v[222:223], s[42:43], 0, v[138:139]
	s_mov_b32 m0, s44
	s_nop 0
	global_load_lds_dwordx4 v[222:223], off
	s_waitcnt vmcnt(8)
	s_waitcnt lgkmcnt(0)
	s_barrier
	s_setprio 1
	s_waitcnt lgkmcnt(0)
	v_mfma_i32_16x16x64_i8 v[124:127], v[128:131], v[182:185], v[124:127]
	v_mfma_i32_16x16x64_i8 v[120:123], v[150:153], v[182:185], v[120:123]
	v_mfma_i32_16x16x64_i8 v[108:111], v[128:131], v[190:193], v[108:111]
	v_mfma_i32_16x16x64_i8 v[104:107], v[150:153], v[190:193], v[104:107]
	v_mfma_i32_16x16x64_i8 v[92:95], v[128:131], v[202:205], v[92:95]
	v_mfma_i32_16x16x64_i8 v[88:91], v[150:153], v[202:205], v[88:91]
	v_mfma_i32_16x16x64_i8 v[76:79], v[128:131], v[210:213], v[76:79]
	v_mfma_i32_16x16x64_i8 v[72:75], v[150:153], v[210:213], v[72:75]
	v_mfma_i32_16x16x64_i8 v[124:127], v[132:135], v[186:189], v[124:127]
	v_mfma_i32_16x16x64_i8 v[120:123], v[162:165], v[186:189], v[120:123]
	v_mfma_i32_16x16x64_i8 v[108:111], v[132:135], v[194:197], v[108:111]
	v_mfma_i32_16x16x64_i8 v[104:107], v[162:165], v[194:197], v[104:107]
	v_mfma_i32_16x16x64_i8 v[92:95], v[132:135], v[206:209], v[92:95]
	v_mfma_i32_16x16x64_i8 v[88:91], v[162:165], v[206:209], v[88:91]
	v_mfma_i32_16x16x64_i8 v[76:79], v[132:135], v[214:217], v[76:79]
	v_mfma_i32_16x16x64_i8 v[72:75], v[162:165], v[214:217], v[72:75]
	s_setprio 0
	s_setprio 1
	v_mfma_i32_16x16x64_i8 v[116:119], v[166:169], v[182:185], v[116:119]
	v_mfma_i32_16x16x64_i8 v[112:115], v[174:177], v[182:185], v[112:115]
	v_mfma_i32_16x16x64_i8 v[100:103], v[166:169], v[190:193], v[100:103]
	v_mfma_i32_16x16x64_i8 v[96:99], v[174:177], v[190:193], v[96:99]
	v_mfma_i32_16x16x64_i8 v[84:87], v[166:169], v[202:205], v[84:87]
	v_mfma_i32_16x16x64_i8 v[80:83], v[174:177], v[202:205], v[80:83]
	v_mfma_i32_16x16x64_i8 v[68:71], v[166:169], v[210:213], v[68:71]
	v_mfma_i32_16x16x64_i8 v[64:67], v[174:177], v[210:213], v[64:67]
	v_mfma_i32_16x16x64_i8 v[116:119], v[170:173], v[186:189], v[116:119]
	v_mfma_i32_16x16x64_i8 v[112:115], v[178:181], v[186:189], v[112:115]
	v_mfma_i32_16x16x64_i8 v[100:103], v[170:173], v[194:197], v[100:103]
	v_mfma_i32_16x16x64_i8 v[96:99], v[178:181], v[194:197], v[96:99]
	v_mfma_i32_16x16x64_i8 v[84:87], v[170:173], v[206:209], v[84:87]
	v_mfma_i32_16x16x64_i8 v[80:83], v[178:181], v[206:209], v[80:83]
	v_mfma_i32_16x16x64_i8 v[68:71], v[170:173], v[214:217], v[68:71]
	v_mfma_i32_16x16x64_i8 v[64:67], v[178:181], v[214:217], v[64:67]
	s_setprio 0
	s_barrier
	s_add_i32 s42, s58, s31
	v_lshl_add_u64 v[154:155], v[154:155], 0, s[16:17]
	s_mov_b32 m0, s42
	ds_read_b128 v[182:185], v160 offset:49152
	ds_read_b128 v[186:189], v160 offset:50176
	ds_read_b128 v[190:193], v160 offset:51200
	ds_read_b128 v[194:197], v160 offset:52224
	ds_read_b128 v[202:205], v160 offset:53248
	ds_read_b128 v[206:209], v160 offset:54272
	ds_read_b128 v[210:213], v160 offset:55296
	ds_read_b128 v[214:217], v160 offset:56320
	global_load_lds_dwordx4 v[154:155], off
	s_add_i32 m0, s42, 0x2000
	s_add_u32 s10, s10, 0x80080
	v_lshl_add_u64 v[154:155], v[198:199], 0, s[16:17]
	s_addc_u32 s11, s11, 0
	s_add_i32 s42, s59, s31
	global_load_lds_dwordx4 v[154:155], off
	v_lshl_add_u64 v[154:155], s[10:11], 0, v[136:137]
	s_mov_b32 m0, s42
	s_nop 0
	global_load_lds_dwordx4 v[154:155], off
	v_lshl_add_u64 v[154:155], s[10:11], 0, v[138:139]
	s_add_i32 m0, s42, 0x2000
	s_nop 0
	global_load_lds_dwordx4 v[154:155], off
	v_lshl_add_u64 v[154:155], v[218:219], 0, s[16:17]
	s_mov_b32 m0, s48
	s_nop 0
	global_load_lds_dwordx4 v[154:155], off
	v_lshl_add_u64 v[154:155], v[220:221], 0, s[16:17]
	s_mov_b32 m0, s49
	s_nop 0
	global_load_lds_dwordx4 v[154:155], off
	s_waitcnt vmcnt(8)
	s_waitcnt lgkmcnt(0)
	s_barrier
	s_setprio 1
	s_waitcnt lgkmcnt(0)
	v_mfma_i32_16x16x64_i8 v[60:63], v[128:131], v[182:185], v[60:63]
	v_mfma_i32_16x16x64_i8 v[56:59], v[150:153], v[182:185], v[56:59]
	v_mfma_i32_16x16x64_i8 v[44:47], v[128:131], v[190:193], v[44:47]
	v_mfma_i32_16x16x64_i8 v[40:43], v[150:153], v[190:193], v[40:43]
	v_mfma_i32_16x16x64_i8 v[28:31], v[128:131], v[202:205], v[28:31]
	v_mfma_i32_16x16x64_i8 v[24:27], v[150:153], v[202:205], v[24:27]
	v_mfma_i32_16x16x64_i8 v[12:15], v[128:131], v[210:213], v[12:15]
	v_mfma_i32_16x16x64_i8 v[8:11], v[150:153], v[210:213], v[8:11]
	v_mfma_i32_16x16x64_i8 v[60:63], v[132:135], v[186:189], v[60:63]
	v_mfma_i32_16x16x64_i8 v[56:59], v[162:165], v[186:189], v[56:59]
	v_mfma_i32_16x16x64_i8 v[44:47], v[132:135], v[194:197], v[44:47]
	v_mfma_i32_16x16x64_i8 v[40:43], v[162:165], v[194:197], v[40:43]
	v_mfma_i32_16x16x64_i8 v[28:31], v[132:135], v[206:209], v[28:31]
	v_mfma_i32_16x16x64_i8 v[24:27], v[162:165], v[206:209], v[24:27]
	v_mfma_i32_16x16x64_i8 v[12:15], v[132:135], v[214:217], v[12:15]
	v_mfma_i32_16x16x64_i8 v[8:11], v[162:165], v[214:217], v[8:11]
	s_setprio 0
	s_setprio 1
	v_mfma_i32_16x16x64_i8 v[52:55], v[166:169], v[182:185], v[52:55]
	v_mfma_i32_16x16x64_i8 v[48:51], v[174:177], v[182:185], v[48:51]
	v_mfma_i32_16x16x64_i8 v[36:39], v[166:169], v[190:193], v[36:39]
	v_mfma_i32_16x16x64_i8 v[32:35], v[174:177], v[190:193], v[32:35]
	v_mfma_i32_16x16x64_i8 v[20:23], v[166:169], v[202:205], v[20:23]
	v_mfma_i32_16x16x64_i8 v[16:19], v[174:177], v[202:205], v[16:19]
	v_mfma_i32_16x16x64_i8 v[4:7], v[166:169], v[210:213], v[4:7]
	v_mfma_i32_16x16x64_i8 v[0:3], v[174:177], v[210:213], v[0:3]
	v_mfma_i32_16x16x64_i8 v[52:55], v[170:173], v[186:189], v[52:55]
	v_mfma_i32_16x16x64_i8 v[48:51], v[178:181], v[186:189], v[48:51]
	v_mfma_i32_16x16x64_i8 v[36:39], v[170:173], v[194:197], v[36:39]
	v_mfma_i32_16x16x64_i8 v[32:35], v[178:181], v[194:197], v[32:35]
	v_mfma_i32_16x16x64_i8 v[20:23], v[170:173], v[206:209], v[20:23]
	v_mfma_i32_16x16x64_i8 v[16:19], v[178:181], v[206:209], v[16:19]
	v_mfma_i32_16x16x64_i8 v[4:7], v[170:173], v[214:217], v[4:7]
	v_mfma_i32_16x16x64_i8 v[0:3], v[178:181], v[214:217], v[0:3]
	s_setprio 0
	s_add_u32 s8, s8, 0x100
	s_addc_u32 s9, s9, 0
	s_add_u32 s55, s55, 0x100
	s_addc_u32 s56, s56, 0
	s_cmp_ge_i32 s57, s18
	s_mov_b32 s10, s57
	s_barrier
	s_cbranch_scc0 .LBB0_2506
	s_and_b64 vcc, exec, s[20:21]
	s_cbranch_vccz .LBB0_2509
